# attn g1 remapped to workgroup-local dependency on g0; grid barrier between attn0 and attn1 removed
# baseline (speedup 1.0000x reference)
.LBB0_789:
	v_mov_b32_e32 v0, v170
	v_readlane_b32 s6, v253, 57
	v_readfirstlane_b32 s0, v0
	v_and_b32_e32 v4, 63, v0
	s_ashr_i32 s0, s0, 6
	v_mov_b32_e32 v5, v4
	s_lshl_b32 s1, s0, 3
	v_ashrrev_i32_e32 v6, 3, v5
	v_add_u32_e32 v0, s1, v6
	v_lshrrev_b32_e32 v1, 1, v0
	v_xor_b32_e32 v2, v1, v5
	v_ashrrev_i32_e32 v1, 31, v0
	v_lshlrev_b64 v[0:1], 7, v[0:1]
	v_readlane_b32 s7, v253, 58
	v_lshlrev_b32_e32 v2, 4, v2
	v_and_b32_e32 v2, 0x70, v2
	v_lshl_add_u64 v[0:1], s[6:7], 0, v[0:1]
	s_lshl_b32 s2, s0, 10
	s_add_i32 s82, 0, 0x18000
	s_add_i32 s3, s0, 8
	v_lshl_add_u64 v[0:1], v[0:1], 0, v[2:3]
	s_add_i32 m0, s82, s2
	s_lshl_b32 s4, s3, 3
	global_load_lds_dwordx4 v[0:1], off
	v_add_u32_e32 v0, s4, v6
	v_lshrrev_b32_e32 v1, 1, v0
	v_xor_b32_e32 v2, v1, v5
	v_ashrrev_i32_e32 v1, 31, v0
	v_lshlrev_b64 v[0:1], 7, v[0:1]
	v_lshlrev_b32_e32 v2, 4, v2
	v_lshl_add_u64 v[0:1], s[6:7], 0, v[0:1]
	v_and_b32_e32 v2, 0x70, v2
	s_lshl_b32 s5, s3, 10
	v_lshl_add_u64 v[0:1], v[0:1], 0, v[2:3]
	s_add_i32 m0, s82, s5
	v_ashrrev_i32_e32 v6, 4, v5
	s_lshl_b32 s0, s0, 2
	global_load_lds_dwordx4 v[0:1], off
	v_add_u32_e32 v0, s0, v6
	v_xor_b32_e32 v2, v0, v5
	v_ashrrev_i32_e32 v1, 31, v0
	v_readlane_b32 s8, v253, 59
	v_lshlrev_b64 v[0:1], 15, v[0:1]
	v_readlane_b32 s9, v253, 60
	v_lshlrev_b32_e32 v2, 4, v2
	v_and_b32_e32 v2, 0xf0, v2
	v_lshl_add_u64 v[0:1], s[8:9], 0, v[0:1]
	s_add_i32 s62, 0, 0x1c000
	v_lshl_add_u64 v[0:1], v[0:1], 0, v[2:3]
	s_add_i32 m0, s62, s2
	s_lshl_b32 s3, s3, 2
	global_load_lds_dwordx4 v[0:1], off
	v_add_u32_e32 v0, s3, v6
	v_xor_b32_e32 v2, v0, v5
	v_ashrrev_i32_e32 v1, 31, v0
	v_lshlrev_b64 v[0:1], 15, v[0:1]
	v_lshlrev_b32_e32 v2, 4, v2
	v_lshl_add_u64 v[0:1], s[8:9], 0, v[0:1]
	v_and_b32_e32 v2, 0xf0, v2
	v_lshl_add_u64 v[0:1], v[0:1], 0, v[2:3]
	s_add_i32 m0, s62, s5
	s_nop 0
	global_load_lds_dwordx4 v[0:1], off
	s_nop 0
	v_ashrrev_i32_e32 v5, 3, v4
	v_add_u32_e32 v0, s1, v5
	v_lshrrev_b32_e32 v1, 1, v0
	v_xor_b32_e32 v2, v1, v4
	v_ashrrev_i32_e32 v1, 31, v0
	v_lshlrev_b64 v[0:1], 7, v[0:1]
	v_lshlrev_b32_e32 v2, 4, v2
	v_lshl_add_u64 v[0:1], s[6:7], 0, v[0:1]
	v_and_b32_e32 v2, 0x70, v2
	s_add_i32 s1, s2, 0
	v_lshl_add_u64 v[0:1], v[0:1], 0, v[2:3]
	s_mov_b32 m0, s1
	s_add_i32 s2, s5, 0
	global_load_lds_dwordx4 v[0:1], off
	v_add_u32_e32 v0, s4, v5
	v_lshrrev_b32_e32 v1, 1, v0
	v_xor_b32_e32 v2, v1, v4
	v_ashrrev_i32_e32 v1, 31, v0
	v_lshlrev_b64 v[0:1], 7, v[0:1]
	v_lshlrev_b32_e32 v2, 4, v2
	v_lshl_add_u64 v[0:1], s[6:7], 0, v[0:1]
	v_and_b32_e32 v2, 0x70, v2
	v_lshl_add_u64 v[0:1], v[0:1], 0, v[2:3]
	s_mov_b32 m0, s2
	v_ashrrev_i32_e32 v5, 4, v4
	global_load_lds_dwordx4 v[0:1], off
	v_add_u32_e32 v0, s0, v5
	v_xor_b32_e32 v2, v0, v4
	v_ashrrev_i32_e32 v1, 31, v0
	v_lshlrev_b64 v[0:1], 15, v[0:1]
	v_lshlrev_b32_e32 v2, 4, v2
	v_lshl_add_u64 v[0:1], s[8:9], 0, v[0:1]
	v_and_b32_e32 v2, 0xf0, v2
	v_lshl_add_u64 v[0:1], v[0:1], 0, v[2:3]
	s_add_i32 m0, s1, 0x4000
	s_nop 0
	global_load_lds_dwordx4 v[0:1], off
	v_add_u32_e32 v0, s3, v5
	v_xor_b32_e32 v2, v0, v4
	v_ashrrev_i32_e32 v1, 31, v0
	v_lshlrev_b64 v[0:1], 15, v[0:1]
	v_lshlrev_b32_e32 v2, 4, v2
	v_lshl_add_u64 v[0:1], s[8:9], 0, v[0:1]
	v_and_b32_e32 v2, 0xf0, v2
	v_lshl_add_u64 v[0:1], v[0:1], 0, v[2:3]
	s_add_i32 m0, s2, 0x4000
	s_nop 0
	global_load_lds_dwordx4 v[0:1], off
	s_waitcnt vmcnt(0)
	s_waitcnt vmcnt(0) lgkmcnt(0)
	s_barrier
	s_mov_b64 s[4:5], exec
	v_readlane_b32 s0, v252, 2
	v_readlane_b32 s1, v252, 3
	s_and_b64 s[0:1], s[4:5], s[0:1]
	s_mov_b64 exec, s[0:1]
	s_cbranch_execz .LBB0_841
	s_branch .LBB0_841
	v_readlane_b32 s1, v254, 46
	s_getreg_b32 s0, hwreg(HW_REG_XCC_ID, 0, 4)
	s_waitcnt vmcnt(0) expcnt(0) lgkmcnt(0)
	v_mov_b32_e32 v0, s1
	ds_read_b32 v2, v0
	v_readlane_b32 s1, v254, 47
	s_and_b32 s0, s0, 15
	s_waitcnt lgkmcnt(0)
	v_cmp_ne_u32_e32 vcc, 0, v2
	v_mov_b32_e32 v0, s1
	ds_read_b32 v0, v0
	s_cbranch_vccnz .LBB0_805
	s_mov_b32 s1, 1
	s_branch .LBB0_793

.LBB0_844:
	s_waitcnt vmcnt(0) lgkmcnt(0)
	s_mov_b32 s79, 0x3e38aa3b
	s_mov_b32 s77, 0xc000
	s_mov_b32 s78, 0xffffc000
	v_readlane_b32 s1, v253, 23
	v_readfirstlane_b32 s0, v170
	s_nop 3
	s_lshr_b32 s0, s0, 6
	s_and_b32 s74, s1, 7
	s_lshl_b32 s74, s74, 5
	s_lshr_b32 s75, s1, 3
	s_add_u32 s74, s74, s75
	s_lshl_b32 s74, s74, 3
	s_and_b32 s4, s74, 31
	s_lshr_b32 s4, s4, 2
	s_mov_b32 s9, s4
	s_mov_b32 s5, 0
	s_lshr_b32 s75, s74, 5
	s_and_b32 s3, s75, 3
	s_lshr_b32 s2, s75, 2
	s_sub_u32 s6, 8, s0
	s_lshl_b32 s70, s0, 10
	s_lshl_b32 s74, s2, 21
	s_lshl_b32 s75, s3, 19
	s_add_u32 s74, s74, s75
	s_add_u32 s34, s40, s74
	s_addc_u32 s35, s41, 0
	s_add_u32 s30, s34, 0x2000000
	s_addc_u32 s31, s35, 0
	s_lshl_b32 s74, s2, 16
	s_lshl_b32 s75, s3, 14
	s_add_u32 s74, s74, s75
	s_add_u32 s74, s74, 0xc000000
	s_add_u32 s58, s42, s74
	s_addc_u32 s59, s43, 0
	s_add_u32 s74, s2, 16
	s_lshl_b32 s74, s74, 2
	s_add_u32 s74, s74, s3
	s_lshl_b32 s74, s74, 19
	s_add_u32 s60, s42, s74
	s_addc_u32 s61, s43, 0
	s_lshl_b32 s74, s2, 6
	s_add_u32 s74, s74, 1024
	s_lshl_b32 s74, s74, 15
	s_lshl_b32 s75, s3, 13
	s_add_u32 s74, s74, s75
	s_add_u32 s74, s74, 0x6000000
	s_add_u32 s64, s42, s74
	s_addc_u32 s65, s43, 0
	v_and_b32_e32 v141, 63, v170
	v_and_b32_e32 v241, 15, v141
	v_lshrrev_b32_e32 v242, 4, v141
	v_mov_b32_e32 v244, 0xf149f2ca
	v_mov_b32_e32 v248, 0
	v_mov_b32_e32 v249, 0
	v_lshrrev_b32_e32 v142, 1, v241
	v_xor_b32_e32 v142, v142, v242
	v_lshlrev_b32_e32 v142, 4, v142
	v_lshl_add_u32 v142, v241, 7, v142
	s_lshl_b32 s74, s0, 11
	v_add_u32_e32 v230, s74, v142
	v_xor_b32_e32 v231, 64, v230
	v_lshrrev_b32_e32 v142, 1, v242
	v_xor_b32_e32 v243, v142, v241
	v_and_b32_e32 v142, 1, v242
	v_lshlrev_b32_e32 v142, 3, v142
	v_lshl_add_u32 v142, v241, 8, v142
	v_add_u32_e32 v142, 0x10000, v142
	s_add_u32 s74, s0, 0
	s_and_b32 s75, s74, 7
	s_lshl_b32 s75, s75, 1
	s_lshr_b32 s74, s74, 3
	s_lshl_b32 s74, s74, 14
	v_xor_b32_e32 v143, s75, v243
	v_lshl_add_u32 v143, v143, 4, v142
	v_add_u32_e32 v221, s74, v143
	s_add_u32 s74, s0, 1
	s_and_b32 s75, s74, 7
	s_lshl_b32 s75, s75, 1
	s_lshr_b32 s74, s74, 3
	s_lshl_b32 s74, s74, 14
	v_xor_b32_e32 v143, s75, v243
	v_lshl_add_u32 v143, v143, 4, v142
	v_add_u32_e32 v222, s74, v143
	s_add_u32 s74, s0, 2
	s_and_b32 s75, s74, 7
	s_lshl_b32 s75, s75, 1
	s_lshr_b32 s74, s74, 3
	s_lshl_b32 s74, s74, 14
	v_xor_b32_e32 v143, s75, v243
	v_lshl_add_u32 v143, v143, 4, v142
	v_add_u32_e32 v223, s74, v143
	s_add_u32 s74, s0, 3
	s_and_b32 s75, s74, 7
	s_lshl_b32 s75, s75, 1
	s_lshr_b32 s74, s74, 3
	s_lshl_b32 s74, s74, 14
	v_xor_b32_e32 v143, s75, v243
	v_lshl_add_u32 v143, v143, 4, v142
	v_add_u32_e32 v224, s74, v143
	s_add_u32 s74, s0, 4
	s_and_b32 s75, s74, 7
	s_lshl_b32 s75, s75, 1
	s_lshr_b32 s74, s74, 3
	s_lshl_b32 s74, s74, 14
	v_xor_b32_e32 v143, s75, v243
	v_lshl_add_u32 v143, v143, 4, v142
	v_add_u32_e32 v225, s74, v143
	s_add_u32 s74, s0, 5
	s_and_b32 s75, s74, 7
	s_lshl_b32 s75, s75, 1
	s_lshr_b32 s74, s74, 3
	s_lshl_b32 s74, s74, 14
	v_xor_b32_e32 v143, s75, v243
	v_lshl_add_u32 v143, v143, 4, v142
	v_add_u32_e32 v226, s74, v143
	s_add_u32 s74, s0, 6
	s_and_b32 s75, s74, 7
	s_lshl_b32 s75, s75, 1
	s_lshr_b32 s74, s74, 3
	s_lshl_b32 s74, s74, 14
	v_xor_b32_e32 v143, s75, v243
	v_lshl_add_u32 v143, v143, 4, v142
	v_add_u32_e32 v227, s74, v143
	s_add_u32 s74, s0, 7
	s_and_b32 s75, s74, 7
	s_lshl_b32 s75, s75, 1
	s_lshr_b32 s74, s74, 3
	s_lshl_b32 s74, s74, 14
	v_xor_b32_e32 v143, s75, v243
	v_lshl_add_u32 v143, v143, 4, v142
	v_add_u32_e32 v228, s74, v143
	s_add_u32 s74, s0, 8
	s_and_b32 s75, s74, 7
	s_lshl_b32 s75, s75, 1
	s_lshr_b32 s74, s74, 3
	s_lshl_b32 s74, s74, 14
	v_xor_b32_e32 v143, s75, v243
	v_lshl_add_u32 v143, v143, 4, v142
	v_add_u32_e32 v229, s74, v143
	s_and_b32 s74, s0, 1
	s_lshl_b32 s74, s74, 2
	v_add_u32_e32 v142, s74, v242
	v_and_b32_e32 v143, 7, v141
	v_xor_b32_e32 v142, v142, v143
	v_lshlrev_b32_e32 v142, 4, v142
	v_lshrrev_b32_e32 v143, 3, v141
	s_lshl_b32 s74, s0, 3
	v_add_u32_e32 v143, s74, v143
	v_lshl_add_u32 v232, v143, 7, v142
	v_add_u32_e32 v233, 0x2000, v232
	s_and_b32 s74, s0, 3
	s_lshl_b32 s74, s74, 2
	v_add_u32_e32 v142, s74, v242
	v_xor_b32_e32 v142, v142, v241
	v_lshlrev_b32_e32 v142, 4, v142
	s_lshl_b32 s74, s0, 2
	v_add_u32_e32 v143, s74, v242
	v_lshl_add_u32 v234, v143, 15, v142
	v_add_u32_e32 v235, 0x100000, v234
	s_lshl_b32 s74, s0, 4
	v_add_u32_e32 v142, s74, v241
	v_lshlrev_b32_e32 v142, 2, v142
	v_lshlrev_b32_e32 v238, 2, v142
	v_lshlrev_b32_e32 v142, 7, v142
	v_lshl_add_u32 v236, v242, 4, v142
	v_lshl_add_u32 v237, v242, 3, v142
	v_xor_b32_e32 v142, 16, v141
	v_lshlrev_b32_e32 v239, 2, v142
	v_xor_b32_e32 v142, 32, v141
	v_lshlrev_b32_e32 v240, 2, v142
	s_add_u32 s74, s2, 17
	v_cvt_f32_u32_e32 v142, s74
	v_mul_f32_e32 v142, 0xc1000000, v142
	v_mul_f32_e32 v142, 0x3caaaaab, v142
	v_exp_f32_e32 v142, v142
	v_lshlrev_b32_e32 v144, 2, v242
	v_sub_u32_e32 v145, v241, v144
	v_mul_f32_e32 v142, 0x40800000, v142
	v_add_u32_e32 v145, 0x80, v145
	v_mul_f32_e32 v142, 0x3fb8aa3b, v142
	v_cvt_f32_i32_e32 v145, v145
	s_nop 0
	v_mul_f32_e64 v143, -v142, v145
	v_fmamk_f32 v185, v142, 0x0, v143
	v_fmamk_f32 v186, v142, 0x3f800000, v143
	v_fmamk_f32 v187, v142, 0x40000000, v143
	v_fmamk_f32 v188, v142, 0x40400000, v143
	v_fmamk_f32 v189, v142, 0x41800000, v143
	v_fmamk_f32 v190, v142, 0x41880000, v143
	v_fmamk_f32 v191, v142, 0x41900000, v143
	v_fmamk_f32 v192, v142, 0x41980000, v143
	v_fmamk_f32 v193, v142, 0x42000000, v143
	v_fmamk_f32 v194, v142, 0x42040000, v143
	v_fmamk_f32 v195, v142, 0x42080000, v143
	v_fmamk_f32 v196, v142, 0x420c0000, v143
	v_fmamk_f32 v197, v142, 0x42400000, v143
	v_fmamk_f32 v198, v142, 0x42440000, v143
	v_fmamk_f32 v199, v142, 0x42480000, v143
	v_fmamk_f32 v200, v142, 0x424c0000, v143
	v_fmamk_f32 v201, v142, 0x42800000, v143
	v_fmamk_f32 v202, v142, 0x42820000, v143
	v_fmamk_f32 v203, v142, 0x42840000, v143
	v_fmamk_f32 v204, v142, 0x42860000, v143
	v_fmamk_f32 v205, v142, 0x42a00000, v143
	v_fmamk_f32 v206, v142, 0x42a20000, v143
	v_fmamk_f32 v207, v142, 0x42a40000, v143
	v_fmamk_f32 v208, v142, 0x42a60000, v143
	v_fmamk_f32 v209, v142, 0x42c00000, v143
	v_fmamk_f32 v210, v142, 0x42c20000, v143
	v_fmamk_f32 v211, v142, 0x42c40000, v143
	v_fmamk_f32 v212, v142, 0x42c60000, v143
	v_fmamk_f32 v213, v142, 0x42e00000, v143
	v_fmamk_f32 v214, v142, 0x42e20000, v143
	v_fmamk_f32 v215, v142, 0x42e40000, v143
	v_fmamk_f32 v216, v142, 0x42e60000, v143
	v_fmamk_f32 v217, v142, 0x43000000, v143
	v_fmamk_f32 v218, v142, 0x43010000, v143
	v_fmamk_f32 v219, v142, 0x43020000, v143
	v_fmamk_f32 v220, v142, 0x43030000, v143
	v_add_u32_e32 v145, 0, v144
	v_cmp_lt_u32_e32 vcc, v145, v241
	s_nop 1
	v_cndmask_b32_e32 v185, v185, v244, vcc
	v_cmp_gt_u32_e32 vcc, v145, v241
	s_nop 1
	v_cndmask_b32_e32 v217, v217, v244, vcc
	v_add_u32_e32 v145, 1, v144
	v_cmp_lt_u32_e32 vcc, v145, v241
	s_nop 1
	v_cndmask_b32_e32 v186, v186, v244, vcc
	v_cmp_gt_u32_e32 vcc, v145, v241
	s_nop 1
	v_cndmask_b32_e32 v218, v218, v244, vcc
	v_add_u32_e32 v145, 2, v144
	v_cmp_lt_u32_e32 vcc, v145, v241
	s_nop 1
	v_cndmask_b32_e32 v187, v187, v244, vcc
	v_cmp_gt_u32_e32 vcc, v145, v241
	s_nop 1
	v_cndmask_b32_e32 v219, v219, v244, vcc
	v_add_u32_e32 v145, 3, v144
	v_cmp_lt_u32_e32 vcc, v145, v241
	s_nop 1
	v_cndmask_b32_e32 v188, v188, v244, vcc
	v_cmp_gt_u32_e32 vcc, v145, v241
	s_nop 1
	v_cndmask_b32_e32 v220, v220, v244, vcc
	s_sub_u32 s76, s4, 1
	s_max_i32 s76, s76, 0
	s_mul_i32 s74, s5, 1024
	s_lshl_b32 s75, s76, 7
	s_add_u32 s74, s74, s75
	s_lshl_b32 s75, s74, 7
	s_add_u32 s16, s60, s75
	s_addc_u32 s17, s61, 0
	s_lshl_b32 s75, s74, 1
	s_add_u32 s24, s64, s75
	s_addc_u32 s25, s65, 0
	s_add_u32 m0, s70, 0x0
	s_nop 0
	global_load_lds_dwordx4 v232, s[16:17]
	s_add_u32 m0, s70, 0x2000
	s_nop 0
	global_load_lds_dwordx4 v233, s[16:17]
	s_add_u32 m0, s70, 0x10000
	s_nop 0
	global_load_lds_dwordx4 v234, s[24:25]
	s_add_u32 m0, s70, 0x12000
	s_nop 0
	global_load_lds_dwordx4 v235, s[24:25]
	s_mul_i32 s74, s5, 1024
	s_lshl_b32 s75, s4, 7
	s_add_u32 s74, s74, s75
	s_lshl_b32 s75, s74, 7
	s_add_u32 s16, s60, s75
	s_addc_u32 s17, s61, 0
	s_lshl_b32 s75, s74, 1
	s_add_u32 s24, s64, s75
	s_addc_u32 s25, s65, 0
	s_add_u32 m0, s70, 0x4000
	s_nop 0
	global_load_lds_dwordx4 v232, s[16:17]
	s_add_u32 m0, s70, 0x6000
	s_nop 0
	global_load_lds_dwordx4 v233, s[16:17]
	s_add_u32 m0, s70, 0x14000
	s_nop 0
	global_load_lds_dwordx4 v234, s[24:25]
	s_add_u32 m0, s70, 0x16000
	s_nop 0
	global_load_lds_dwordx4 v235, s[24:25]
	s_lshl_b32 s74, s4, 9
	s_add_u32 s74, s74, s5
	s_lshl_b32 s75, s74, 7
	s_add_u32 s10, s30, s75
	s_addc_u32 s11, s31, 0
	s_add_u32 s86, s34, s75
	s_addc_u32 s87, s35, 0
	s_lshl_b32 s75, s74, 2
	s_add_u32 s88, s58, s75
	s_addc_u32 s89, s59, 0
	global_load_dwordx4 v[96:99], v236, s[10:11]
	global_load_dwordx4 v[100:103], v236, s[10:11] offset:64
	global_load_dwordx2 v[112:113], v237, s[86:87]
	global_load_dwordx2 v[114:115], v237, s[86:87] offset:32
	global_load_dwordx2 v[116:117], v237, s[86:87] offset:64
	global_load_dwordx2 v[118:119], v237, s[86:87] offset:96
	global_load_dword v120, v238, s[88:89]
	s_waitcnt vmcnt(0)
	s_barrier
	ds_read_b128 v[4:7], v230 offset:0
	ds_read_b128 v[8:11], v231 offset:0
	ds_read_b128 v[12:15], v230 offset:2048
	ds_read_b128 v[16:19], v231 offset:2048
	ds_read_b128 v[20:23], v230 offset:4096
	ds_read_b128 v[24:27], v231 offset:4096
	ds_read_b128 v[28:31], v230 offset:6144
	ds_read_b128 v[32:35], v231 offset:6144
	ds_read_b128 v[36:39], v230 offset:8192
	ds_read_b128 v[40:43], v231 offset:8192
	s_add_u32 s83, s9, 1
	s_mov_b32 s84, 0
	s_mul_i32 s74, s84, 1024
	s_lshl_b32 s75, s83, 7
	s_add_u32 s74, s74, s75
	s_lshl_b32 s75, s74, 7
	s_add_u32 s16, s60, s75
	s_addc_u32 s17, s61, 0
	s_lshl_b32 s75, s74, 1
	s_add_u32 s24, s64, s75
	s_addc_u32 s25, s65, 0
	s_add_u32 m0, s70, 0x8000
	s_nop 0
	global_load_lds_dwordx4 v232, s[16:17]
	s_add_u32 m0, s70, 0xa000
	s_nop 0
	global_load_lds_dwordx4 v233, s[16:17]
	s_add_u32 m0, s70, 0x18000
	s_nop 0
	global_load_lds_dwordx4 v234, s[24:25]
	s_add_u32 m0, s70, 0x1a000
	s_nop 0
	global_load_lds_dwordx4 v235, s[24:25]
	s_lshl_b32 s74, s83, 9
	s_add_u32 s74, s74, s84
	s_lshl_b32 s75, s74, 7
	s_add_u32 s10, s30, s75
	s_addc_u32 s11, s31, 0
	s_add_u32 s12, s34, s75
	s_addc_u32 s13, s35, 0
	s_lshl_b32 s75, s74, 2
	s_add_u32 s14, s58, s75
	s_addc_u32 s15, s59, 0
	global_load_dwordx4 v[104:107], v236, s[10:11]
	global_load_dwordx4 v[108:111], v236, s[10:11] offset:64
	global_load_dwordx2 v[122:123], v237, s[12:13]
	global_load_dwordx2 v[124:125], v237, s[12:13] offset:32
	global_load_dwordx2 v[126:127], v237, s[12:13] offset:64
	global_load_dwordx2 v[128:129], v237, s[12:13] offset:96
	global_load_dword v121, v238, s[14:15]
	s_waitcnt lgkmcnt(0)
	v_mfma_f32_16x16x32_bf16 v[44:47], v[4:7], v[96:99], 0
	v_mfma_f32_16x16x32_bf16 v[48:51], v[12:15], v[96:99], 0
	v_mfma_f32_16x16x32_bf16 v[52:55], v[20:23], v[96:99], 0
	v_mfma_f32_16x16x32_bf16 v[56:59], v[28:31], v[96:99], 0
	v_mfma_f32_16x16x32_bf16 v[60:63], v[36:39], v[96:99], 0
	v_mfma_f32_16x16x32_bf16 v[44:47], v[8:11], v[100:103], v[44:47]
	v_mfma_f32_16x16x32_bf16 v[48:51], v[16:19], v[100:103], v[48:51]
	v_mfma_f32_16x16x32_bf16 v[52:55], v[24:27], v[100:103], v[52:55]
	v_mfma_f32_16x16x32_bf16 v[56:59], v[32:35], v[100:103], v[56:59]
	v_mfma_f32_16x16x32_bf16 v[60:63], v[40:43], v[100:103], v[60:63]
	ds_read_b128 v[4:7], v230 offset:10240
	ds_read_b128 v[8:11], v231 offset:10240
	ds_read_b128 v[12:15], v230 offset:12288
	ds_read_b128 v[16:19], v231 offset:12288
	ds_read_b128 v[20:23], v230 offset:14336
	ds_read_b128 v[24:27], v231 offset:14336
	ds_read_b128 v[28:31], v230 offset:16384
	ds_read_b128 v[32:35], v231 offset:16384
	s_nop 1
	v_fma_f32 v44, v44, s79, v185
	v_fma_f32 v45, v45, s79, v186
	v_fma_f32 v46, v46, s79, v187
	v_fma_f32 v47, v47, s79, v188
	v_fma_f32 v48, v48, s79, v189
	v_fma_f32 v49, v49, s79, v190
	v_fma_f32 v50, v50, s79, v191
	v_fma_f32 v51, v51, s79, v192
	v_fma_f32 v52, v52, s79, v193
	v_fma_f32 v53, v53, s79, v194
	v_fma_f32 v54, v54, s79, v195
	v_fma_f32 v55, v55, s79, v196
	v_fma_f32 v56, v56, s79, v197
	v_fma_f32 v57, v57, s79, v198
	v_fma_f32 v58, v58, s79, v199
	v_fma_f32 v59, v59, s79, v200
	v_fma_f32 v60, v60, s79, v201
	v_fma_f32 v61, v61, s79, v202
	v_fma_f32 v62, v62, s79, v203
	v_fma_f32 v63, v63, s79, v204
	s_waitcnt lgkmcnt(0)
	v_mfma_f32_16x16x32_bf16 v[64:67], v[4:7], v[96:99], 0
	v_mfma_f32_16x16x32_bf16 v[68:71], v[12:15], v[96:99], 0
	v_mfma_f32_16x16x32_bf16 v[72:75], v[20:23], v[96:99], 0
	v_mfma_f32_16x16x32_bf16 v[76:79], v[28:31], v[96:99], 0
	v_mfma_f32_16x16x32_bf16 v[64:67], v[8:11], v[100:103], v[64:67]
	v_mfma_f32_16x16x32_bf16 v[68:71], v[16:19], v[100:103], v[68:71]
	v_mfma_f32_16x16x32_bf16 v[72:75], v[24:27], v[100:103], v[72:75]
	v_mfma_f32_16x16x32_bf16 v[76:79], v[32:35], v[100:103], v[76:79]
	ds_read_b64 v[4:5], v221 offset:0
	ds_read_b64 v[8:9], v221 offset:4096
	ds_read_b64 v[12:13], v221 offset:8192
	ds_read_b64 v[16:17], v221 offset:12288
	ds_read_b64 v[6:7], v222 offset:0
	ds_read_b64 v[10:11], v222 offset:4096
	ds_read_b64 v[14:15], v222 offset:8192
	ds_read_b64 v[18:19], v222 offset:12288
	s_nop 1
	v_fma_f32 v64, v64, s79, v205
	v_fma_f32 v65, v65, s79, v206
	v_fma_f32 v66, v66, s79, v207
	v_fma_f32 v67, v67, s79, v208
	v_fma_f32 v68, v68, s79, v209
	v_fma_f32 v69, v69, s79, v210
	v_fma_f32 v70, v70, s79, v211
	v_fma_f32 v71, v71, s79, v212
	v_fma_f32 v72, v72, s79, v213
	v_fma_f32 v73, v73, s79, v214
	v_fma_f32 v74, v74, s79, v215
	v_fma_f32 v75, v75, s79, v216
	v_fma_f32 v76, v76, s79, v217
	v_fma_f32 v77, v77, s79, v218
	v_fma_f32 v78, v78, s79, v219
	v_fma_f32 v79, v79, s79, v220
	ds_read_b64 v[20:21], v223 offset:0
	ds_read_b64 v[24:25], v223 offset:4096
	ds_read_b64 v[28:29], v223 offset:8192
	ds_read_b64 v[32:33], v223 offset:12288
	ds_read_b64 v[22:23], v224 offset:0
	ds_read_b64 v[26:27], v224 offset:4096
	ds_read_b64 v[30:31], v224 offset:8192
	ds_read_b64 v[34:35], v224 offset:12288
	s_cmp_lg_u32 s4, 0
	s_cbranch_scc1 .Lat844_i0_nomask
	s_cmp_le_u32 s6, 0
	s_cbranch_scc1 .Lat844_i0_nomask
	v_mov_b32_e32 v44, v244
	v_mov_b32_e32 v45, v244
	v_mov_b32_e32 v46, v244
	v_mov_b32_e32 v47, v244
	s_cmp_le_u32 s6, 1
	s_cbranch_scc1 .Lat844_i0_nomask
	v_mov_b32_e32 v48, v244
	v_mov_b32_e32 v49, v244
	v_mov_b32_e32 v50, v244
	v_mov_b32_e32 v51, v244
	s_cmp_le_u32 s6, 2
	s_cbranch_scc1 .Lat844_i0_nomask
	v_mov_b32_e32 v52, v244
	v_mov_b32_e32 v53, v244
	v_mov_b32_e32 v54, v244
	v_mov_b32_e32 v55, v244
	s_cmp_le_u32 s6, 3
	s_cbranch_scc1 .Lat844_i0_nomask
	v_mov_b32_e32 v56, v244
	v_mov_b32_e32 v57, v244
	v_mov_b32_e32 v58, v244
	v_mov_b32_e32 v59, v244
	s_cmp_le_u32 s6, 4
	s_cbranch_scc1 .Lat844_i0_nomask
	v_mov_b32_e32 v60, v244
	v_mov_b32_e32 v61, v244
	v_mov_b32_e32 v62, v244
	v_mov_b32_e32 v63, v244
	s_cmp_le_u32 s6, 5
	s_cbranch_scc1 .Lat844_i0_nomask
	v_mov_b32_e32 v64, v244
	v_mov_b32_e32 v65, v244
	v_mov_b32_e32 v66, v244
	v_mov_b32_e32 v67, v244
	s_cmp_le_u32 s6, 6
	s_cbranch_scc1 .Lat844_i0_nomask
	v_mov_b32_e32 v68, v244
	v_mov_b32_e32 v69, v244
	v_mov_b32_e32 v70, v244
	v_mov_b32_e32 v71, v244
	s_cmp_le_u32 s6, 7
	s_cbranch_scc1 .Lat844_i0_nomask
	v_mov_b32_e32 v72, v244
	v_mov_b32_e32 v73, v244
	v_mov_b32_e32 v74, v244
	v_mov_b32_e32 v75, v244
.Lat844_i0_nomask:
	v_max3_f32 v245, v44, v45, v46
	v_max3_f32 v245, v245, v47, v48
	v_max3_f32 v245, v245, v49, v50
	v_max3_f32 v245, v245, v51, v52
	v_max3_f32 v245, v245, v53, v54
	v_max3_f32 v245, v245, v55, v56
	v_max3_f32 v245, v245, v57, v58
	v_max3_f32 v245, v245, v59, v60
	v_max3_f32 v245, v245, v61, v62
	v_max3_f32 v245, v245, v63, v64
	v_max3_f32 v245, v245, v65, v66
	v_max3_f32 v245, v245, v67, v68
	v_max3_f32 v245, v245, v69, v70
	v_max3_f32 v245, v245, v71, v72
	v_max3_f32 v245, v245, v73, v74
	v_max3_f32 v245, v245, v75, v76
	v_max3_f32 v245, v245, v77, v78
	v_max_f32_e32 v245, v245, v79
	ds_bpermute_b32 v148, v239, v245
	s_waitcnt lgkmcnt(0)
	v_max_f32_e32 v245, v245, v148
	ds_bpermute_b32 v148, v240, v245
	s_waitcnt lgkmcnt(0)
	v_max_f32_e32 v245, v245, v148
	v_sub_f32_e32 v44, v44, v245
	v_sub_f32_e32 v45, v45, v245
	v_sub_f32_e32 v46, v46, v245
	v_sub_f32_e32 v47, v47, v245
	v_exp_f32_e32 v44, v44
	v_exp_f32_e32 v45, v45
	v_exp_f32_e32 v46, v46
	v_exp_f32_e32 v47, v47
	v_sub_f32_e32 v48, v48, v245
	v_sub_f32_e32 v49, v49, v245
	v_sub_f32_e32 v50, v50, v245
	v_sub_f32_e32 v51, v51, v245
	v_exp_f32_e32 v48, v48
	v_exp_f32_e32 v49, v49
	v_exp_f32_e32 v50, v50
	v_exp_f32_e32 v51, v51
	v_mov_b32_e32 v149, v44
	v_mov_b32_e32 v150, v45
	v_mov_b32_e32 v151, v46
	v_mov_b32_e32 v152, v47
	v_cvt_pk_bf16_f32 v44, v44, v45
	v_cvt_pk_bf16_f32 v45, v46, v47
	v_sub_f32_e32 v52, v52, v245
	v_sub_f32_e32 v53, v53, v245
	v_sub_f32_e32 v54, v54, v245
	v_sub_f32_e32 v55, v55, v245
	v_exp_f32_e32 v52, v52
	v_exp_f32_e32 v53, v53
	v_exp_f32_e32 v54, v54
	v_exp_f32_e32 v55, v55
	v_add_f32_e32 v149, v149, v48
	v_add_f32_e32 v150, v150, v49
	v_add_f32_e32 v151, v151, v50
	v_add_f32_e32 v152, v152, v51
	v_cvt_pk_bf16_f32 v46, v48, v49
	v_cvt_pk_bf16_f32 v47, v50, v51
	v_sub_f32_e32 v56, v56, v245
	v_sub_f32_e32 v57, v57, v245
	v_sub_f32_e32 v58, v58, v245
	v_sub_f32_e32 v59, v59, v245
	v_exp_f32_e32 v56, v56
	v_exp_f32_e32 v57, v57
	v_exp_f32_e32 v58, v58
	v_exp_f32_e32 v59, v59
	v_add_f32_e32 v149, v149, v52
	v_add_f32_e32 v150, v150, v53
	v_add_f32_e32 v151, v151, v54
	v_add_f32_e32 v152, v152, v55
	v_cvt_pk_bf16_f32 v52, v52, v53
	v_cvt_pk_bf16_f32 v53, v54, v55
	v_sub_f32_e32 v60, v60, v245
	v_sub_f32_e32 v61, v61, v245
	v_sub_f32_e32 v62, v62, v245
	v_sub_f32_e32 v63, v63, v245
	v_exp_f32_e32 v60, v60
	v_exp_f32_e32 v61, v61
	v_exp_f32_e32 v62, v62
	v_exp_f32_e32 v63, v63
	v_add_f32_e32 v149, v149, v56
	v_add_f32_e32 v150, v150, v57
	v_add_f32_e32 v151, v151, v58
	v_add_f32_e32 v152, v152, v59
	v_cvt_pk_bf16_f32 v54, v56, v57
	v_cvt_pk_bf16_f32 v55, v58, v59
	v_sub_f32_e32 v64, v64, v245
	v_sub_f32_e32 v65, v65, v245
	v_sub_f32_e32 v66, v66, v245
	v_sub_f32_e32 v67, v67, v245
	v_exp_f32_e32 v64, v64
	v_exp_f32_e32 v65, v65
	v_exp_f32_e32 v66, v66
	v_exp_f32_e32 v67, v67
	v_add_f32_e32 v149, v149, v60
	v_add_f32_e32 v150, v150, v61
	v_add_f32_e32 v151, v151, v62
	v_add_f32_e32 v152, v152, v63
	v_cvt_pk_bf16_f32 v60, v60, v61
	v_cvt_pk_bf16_f32 v61, v62, v63
	v_sub_f32_e32 v68, v68, v245
	v_sub_f32_e32 v69, v69, v245
	v_sub_f32_e32 v70, v70, v245
	v_sub_f32_e32 v71, v71, v245
	v_exp_f32_e32 v68, v68
	v_exp_f32_e32 v69, v69
	v_exp_f32_e32 v70, v70
	v_exp_f32_e32 v71, v71
	v_add_f32_e32 v149, v149, v64
	v_add_f32_e32 v150, v150, v65
	v_add_f32_e32 v151, v151, v66
	v_add_f32_e32 v152, v152, v67
	v_cvt_pk_bf16_f32 v62, v64, v65
	v_cvt_pk_bf16_f32 v63, v66, v67
	v_sub_f32_e32 v72, v72, v245
	v_sub_f32_e32 v73, v73, v245
	v_sub_f32_e32 v74, v74, v245
	v_sub_f32_e32 v75, v75, v245
	v_exp_f32_e32 v72, v72
	v_exp_f32_e32 v73, v73
	v_exp_f32_e32 v74, v74
	v_exp_f32_e32 v75, v75
	v_add_f32_e32 v149, v149, v68
	v_add_f32_e32 v150, v150, v69
	v_add_f32_e32 v151, v151, v70
	v_add_f32_e32 v152, v152, v71
	v_cvt_pk_bf16_f32 v68, v68, v69
	v_cvt_pk_bf16_f32 v69, v70, v71
	v_sub_f32_e32 v76, v76, v245
	v_sub_f32_e32 v77, v77, v245
	v_sub_f32_e32 v78, v78, v245
	v_sub_f32_e32 v79, v79, v245
	v_exp_f32_e32 v76, v76
	v_exp_f32_e32 v77, v77
	v_exp_f32_e32 v78, v78
	v_exp_f32_e32 v79, v79
	v_add_f32_e32 v149, v149, v72
	v_add_f32_e32 v150, v150, v73
	v_add_f32_e32 v151, v151, v74
	v_add_f32_e32 v152, v152, v75
	v_cvt_pk_bf16_f32 v70, v72, v73
	v_cvt_pk_bf16_f32 v71, v74, v75
	s_nop 0
	v_add_f32_e32 v149, v149, v76
	v_add_f32_e32 v150, v150, v77
	v_add_f32_e32 v151, v151, v78
	v_add_f32_e32 v152, v152, v79
	v_cvt_pk_bf16_f32 v76, v76, v77
	v_cvt_pk_bf16_f32 v77, v78, v79
	v_mov_b32_e32 v78, 0
	v_mov_b32_e32 v79, 0
	v_add_f32_e32 v149, v149, v150
	v_add_f32_e32 v151, v151, v152
	v_add_f32_e32 v246, v149, v151
	s_waitcnt lgkmcnt(0)
	v_mfma_f32_16x16x32_bf16 v[80:83], v[4:7], v[44:47], 0
	v_mfma_f32_16x16x32_bf16 v[84:87], v[8:11], v[44:47], 0
	v_mfma_f32_16x16x32_bf16 v[88:91], v[12:15], v[44:47], 0
	v_mfma_f32_16x16x32_bf16 v[92:95], v[16:19], v[44:47], 0
	ds_read_b64 v[4:5], v225 offset:0
	ds_read_b64 v[8:9], v225 offset:4096
	ds_read_b64 v[12:13], v225 offset:8192
	ds_read_b64 v[16:17], v225 offset:12288
	ds_read_b64 v[6:7], v226 offset:0
	ds_read_b64 v[10:11], v226 offset:4096
	ds_read_b64 v[14:15], v226 offset:8192
	ds_read_b64 v[18:19], v226 offset:12288
	v_mfma_f32_16x16x32_bf16 v[80:83], v[20:23], v[52:55], v[80:83]
	v_mfma_f32_16x16x32_bf16 v[84:87], v[24:27], v[52:55], v[84:87]
	v_mfma_f32_16x16x32_bf16 v[88:91], v[28:31], v[52:55], v[88:91]
	v_mfma_f32_16x16x32_bf16 v[92:95], v[32:35], v[52:55], v[92:95]
	ds_read_b64 v[20:21], v227 offset:0
	ds_read_b64 v[24:25], v227 offset:4096
	ds_read_b64 v[28:29], v227 offset:8192
	ds_read_b64 v[32:33], v227 offset:12288
	ds_read_b64 v[22:23], v228 offset:0
	ds_read_b64 v[26:27], v228 offset:4096
	ds_read_b64 v[30:31], v228 offset:8192
	ds_read_b64 v[34:35], v228 offset:12288
	ds_bpermute_b32 v148, v239, v246
	s_waitcnt lgkmcnt(9)
	v_mfma_f32_16x16x32_bf16 v[80:83], v[4:7], v[60:63], v[80:83]
	v_mfma_f32_16x16x32_bf16 v[84:87], v[8:11], v[60:63], v[84:87]
	v_mfma_f32_16x16x32_bf16 v[88:91], v[12:15], v[60:63], v[88:91]
	v_mfma_f32_16x16x32_bf16 v[92:95], v[16:19], v[60:63], v[92:95]
	ds_read_b64 v[4:5], v229 offset:0
	ds_read_b64 v[8:9], v229 offset:4096
	ds_read_b64 v[12:13], v229 offset:8192
	ds_read_b64 v[16:17], v229 offset:12288
	v_mov_b32_e32 v6, 0
	v_mov_b32_e32 v7, 0
	v_mov_b32_e32 v10, 0
	v_mov_b32_e32 v11, 0
	v_mov_b32_e32 v14, 0
	v_mov_b32_e32 v15, 0
	v_mov_b32_e32 v18, 0
	v_mov_b32_e32 v19, 0
	s_waitcnt lgkmcnt(5)
	v_mfma_f32_16x16x32_bf16 v[80:83], v[20:23], v[68:71], v[80:83]
	v_mfma_f32_16x16x32_bf16 v[84:87], v[24:27], v[68:71], v[84:87]
	v_mfma_f32_16x16x32_bf16 v[88:91], v[28:31], v[68:71], v[88:91]
	v_mfma_f32_16x16x32_bf16 v[92:95], v[32:35], v[68:71], v[92:95]
	s_waitcnt lgkmcnt(0)
	v_add_f32_e32 v246, v246, v148
	s_nop 0
	v_mfma_f32_16x16x32_bf16 v[80:83], v[4:7], v[76:79], v[80:83]
	v_mfma_f32_16x16x32_bf16 v[84:87], v[8:11], v[76:79], v[84:87]
	v_mfma_f32_16x16x32_bf16 v[88:91], v[12:15], v[76:79], v[88:91]
	v_mfma_f32_16x16x32_bf16 v[92:95], v[16:19], v[76:79], v[92:95]
	ds_bpermute_b32 v148, v240, v246
	s_waitcnt lgkmcnt(0)
	v_add_f32_e32 v246, v246, v148
	v_rcp_f32_e32 v149, v246
	v_log_f32_e32 v150, v246
	s_nop 0
	v_add_f32_e32 v151, v245, v150
	v_mul_f32_e32 v151, 0x3f317218, v151
	v_max_f32_e32 v152, v120, v151
	v_sub_f32_e32 v153, v120, v152
	v_sub_f32_e32 v154, v151, v152
	v_mul_f32_e32 v153, 0x3fb8aa3b, v153
	v_mul_f32_e32 v154, 0x3fb8aa3b, v154
	v_exp_f32_e32 v153, v153
	v_exp_f32_e32 v154, v154
	s_nop 0
	v_add_f32_e32 v155, v153, v154
	v_rcp_f32_e32 v146, v155
	v_log_f32_e32 v150, v155
	s_nop 0
	v_mul_f32_e32 v154, v154, v146
	v_mul_f32_e32 v146, v153, v146
	v_mul_f32_e32 v147, v149, v154
	v_mul_f32_e32 v150, 0x3f317218, v150
	v_add_f32_e32 v140, v152, v150
	v_mul_f32_e32 v80, v80, v147
	v_mul_f32_e32 v81, v81, v147
	v_mul_f32_e32 v82, v82, v147
	v_mul_f32_e32 v83, v83, v147
	v_mul_f32_e32 v84, v84, v147
	v_mul_f32_e32 v85, v85, v147
	v_mul_f32_e32 v86, v86, v147
	v_mul_f32_e32 v87, v87, v147
	v_mul_f32_e32 v88, v88, v147
	v_mul_f32_e32 v89, v89, v147
	v_mul_f32_e32 v90, v90, v147
	v_mul_f32_e32 v91, v91, v147
	v_mul_f32_e32 v92, v92, v147
	v_mul_f32_e32 v93, v93, v147
	v_mul_f32_e32 v94, v94, v147
	v_mul_f32_e32 v95, v95, v147
	v_lshlrev_b32_e32 v141, 16, v112
	v_and_b32_e32 v142, 0xffff0000, v112
	v_lshlrev_b32_e32 v143, 16, v113
	v_and_b32_e32 v144, 0xffff0000, v113
	v_fmac_f32_e32 v80, v146, v141
	v_fmac_f32_e32 v81, v146, v142
	v_fmac_f32_e32 v82, v146, v143
	v_fmac_f32_e32 v83, v146, v144
	v_cvt_pk_bf16_f32 v132, v80, v81
	v_cvt_pk_bf16_f32 v133, v82, v83
	v_lshlrev_b32_e32 v141, 16, v114
	v_and_b32_e32 v142, 0xffff0000, v114
	v_lshlrev_b32_e32 v143, 16, v115
	v_and_b32_e32 v144, 0xffff0000, v115
	v_fmac_f32_e32 v84, v146, v141
	v_fmac_f32_e32 v85, v146, v142
	v_fmac_f32_e32 v86, v146, v143
	v_fmac_f32_e32 v87, v146, v144
	v_cvt_pk_bf16_f32 v134, v84, v85
	v_cvt_pk_bf16_f32 v135, v86, v87
	v_lshlrev_b32_e32 v141, 16, v116
	v_and_b32_e32 v142, 0xffff0000, v116
	v_lshlrev_b32_e32 v143, 16, v117
	v_and_b32_e32 v144, 0xffff0000, v117
	v_fmac_f32_e32 v88, v146, v141
	v_fmac_f32_e32 v89, v146, v142
	v_fmac_f32_e32 v90, v146, v143
	v_fmac_f32_e32 v91, v146, v144
	v_cvt_pk_bf16_f32 v136, v88, v89
	v_cvt_pk_bf16_f32 v137, v90, v91
	v_lshlrev_b32_e32 v141, 16, v118
	v_and_b32_e32 v142, 0xffff0000, v118
	v_lshlrev_b32_e32 v143, 16, v119
	v_and_b32_e32 v144, 0xffff0000, v119
	v_fmac_f32_e32 v92, v146, v141
	v_fmac_f32_e32 v93, v146, v142
	v_fmac_f32_e32 v94, v146, v143
	v_fmac_f32_e32 v95, v146, v144
	v_cvt_pk_bf16_f32 v138, v92, v93
	v_cvt_pk_bf16_f32 v139, v94, v95
	s_mov_b64 s[26:27], s[86:87]
	s_mov_b64 s[28:29], s[88:89]
	s_mov_b64 s[86:87], s[12:13]
	s_mov_b64 s[88:89], s[14:15]
	s_mov_b32 s4, s83
	s_mov_b32 s5, s84
	s_waitcnt vmcnt(0)
	s_barrier
	ds_read_b128 v[4:7], v230 offset:16384
	ds_read_b128 v[8:11], v231 offset:16384
	ds_read_b128 v[12:15], v230 offset:18432
	ds_read_b128 v[16:19], v231 offset:18432
	ds_read_b128 v[20:23], v230 offset:20480
	ds_read_b128 v[24:27], v231 offset:20480
	ds_read_b128 v[28:31], v230 offset:22528
	ds_read_b128 v[32:35], v231 offset:22528
	ds_read_b128 v[36:39], v230 offset:24576
	ds_read_b128 v[40:43], v231 offset:24576
	global_store_dwordx2 v237, v[132:133], s[26:27]
	global_store_dwordx2 v237, v[134:135], s[26:27] offset:32
	global_store_dwordx2 v237, v[136:137], s[26:27] offset:64
	global_store_dwordx2 v237, v[138:139], s[26:27] offset:96
	s_mov_b64 s[90:91], exec
	s_mov_b64 exec, 0xffff
	global_store_dword v238, v140, s[28:29]
	s_mov_b64 exec, s[90:91]
	s_add_u32 s83, s9, 0
	s_mov_b32 s84, 1
	s_sub_u32 s76, s83, 1
	s_max_i32 s76, s76, 0
	s_mul_i32 s74, s84, 1024
	s_lshl_b32 s75, s76, 7
	s_add_u32 s74, s74, s75
	s_lshl_b32 s75, s74, 7
	s_add_u32 s16, s60, s75
	s_addc_u32 s17, s61, 0
	s_lshl_b32 s75, s74, 1
	s_add_u32 s24, s64, s75
	s_addc_u32 s25, s65, 0
	s_add_u32 m0, s70, 0xc000
	s_nop 0
	global_load_lds_dwordx4 v232, s[16:17]
	s_add_u32 m0, s70, 0xe000
	s_nop 0
	global_load_lds_dwordx4 v233, s[16:17]
	s_add_u32 m0, s70, 0x1c000
	s_nop 0
	global_load_lds_dwordx4 v234, s[24:25]
	s_add_u32 m0, s70, 0x1e000
	s_nop 0
	global_load_lds_dwordx4 v235, s[24:25]
	s_mul_i32 s74, s84, 1024
	s_lshl_b32 s75, s83, 7
	s_add_u32 s74, s74, s75
	s_lshl_b32 s75, s74, 7
	s_add_u32 s16, s60, s75
	s_addc_u32 s17, s61, 0
	s_lshl_b32 s75, s74, 1
	s_add_u32 s24, s64, s75
	s_addc_u32 s25, s65, 0
	s_add_u32 m0, s70, 0x0
	s_nop 0
	global_load_lds_dwordx4 v232, s[16:17]
	s_add_u32 m0, s70, 0x2000
	s_nop 0
	global_load_lds_dwordx4 v233, s[16:17]
	s_add_u32 m0, s70, 0x10000
	s_nop 0
	global_load_lds_dwordx4 v234, s[24:25]
	s_add_u32 m0, s70, 0x12000
	s_nop 0
	global_load_lds_dwordx4 v235, s[24:25]
	s_lshl_b32 s74, s83, 9
	s_add_u32 s74, s74, s84
	s_lshl_b32 s75, s74, 7
	s_add_u32 s10, s30, s75
	s_addc_u32 s11, s31, 0
	s_add_u32 s12, s34, s75
	s_addc_u32 s13, s35, 0
	s_lshl_b32 s75, s74, 2
	s_add_u32 s14, s58, s75
	s_addc_u32 s15, s59, 0
	global_load_dwordx4 v[96:99], v236, s[10:11]
	global_load_dwordx4 v[100:103], v236, s[10:11] offset:64
	global_load_dwordx2 v[112:113], v237, s[12:13]
	global_load_dwordx2 v[114:115], v237, s[12:13] offset:32
	global_load_dwordx2 v[116:117], v237, s[12:13] offset:64
	global_load_dwordx2 v[118:119], v237, s[12:13] offset:96
	global_load_dword v120, v238, s[14:15]
	s_waitcnt lgkmcnt(0)
	v_mfma_f32_16x16x32_bf16 v[44:47], v[4:7], v[104:107], 0
	v_mfma_f32_16x16x32_bf16 v[48:51], v[12:15], v[104:107], 0
	v_mfma_f32_16x16x32_bf16 v[52:55], v[20:23], v[104:107], 0
	v_mfma_f32_16x16x32_bf16 v[56:59], v[28:31], v[104:107], 0
	v_mfma_f32_16x16x32_bf16 v[60:63], v[36:39], v[104:107], 0
	v_mfma_f32_16x16x32_bf16 v[44:47], v[8:11], v[108:111], v[44:47]
	v_mfma_f32_16x16x32_bf16 v[48:51], v[16:19], v[108:111], v[48:51]
	v_mfma_f32_16x16x32_bf16 v[52:55], v[24:27], v[108:111], v[52:55]
	v_mfma_f32_16x16x32_bf16 v[56:59], v[32:35], v[108:111], v[56:59]
	v_mfma_f32_16x16x32_bf16 v[60:63], v[40:43], v[108:111], v[60:63]
	ds_read_b128 v[4:7], v230 offset:26624
	ds_read_b128 v[8:11], v231 offset:26624
	ds_read_b128 v[12:15], v230 offset:28672
	ds_read_b128 v[16:19], v231 offset:28672
	ds_read_b128 v[20:23], v230 offset:30720
	ds_read_b128 v[24:27], v231 offset:30720
	ds_read_b128 v[28:31], v230 offset:32768
	ds_read_b128 v[32:35], v231 offset:32768
	s_nop 1
	v_fma_f32 v44, v44, s79, v185
	v_fma_f32 v45, v45, s79, v186
	v_fma_f32 v46, v46, s79, v187
	v_fma_f32 v47, v47, s79, v188
	v_fma_f32 v48, v48, s79, v189
	v_fma_f32 v49, v49, s79, v190
	v_fma_f32 v50, v50, s79, v191
	v_fma_f32 v51, v51, s79, v192
	v_fma_f32 v52, v52, s79, v193
	v_fma_f32 v53, v53, s79, v194
	v_fma_f32 v54, v54, s79, v195
	v_fma_f32 v55, v55, s79, v196
	v_fma_f32 v56, v56, s79, v197
	v_fma_f32 v57, v57, s79, v198
	v_fma_f32 v58, v58, s79, v199
	v_fma_f32 v59, v59, s79, v200
	v_fma_f32 v60, v60, s79, v201
	v_fma_f32 v61, v61, s79, v202
	v_fma_f32 v62, v62, s79, v203
	v_fma_f32 v63, v63, s79, v204
	s_waitcnt lgkmcnt(0)
	v_mfma_f32_16x16x32_bf16 v[64:67], v[4:7], v[104:107], 0
	v_mfma_f32_16x16x32_bf16 v[68:71], v[12:15], v[104:107], 0
	v_mfma_f32_16x16x32_bf16 v[72:75], v[20:23], v[104:107], 0
	v_mfma_f32_16x16x32_bf16 v[76:79], v[28:31], v[104:107], 0
	v_mfma_f32_16x16x32_bf16 v[64:67], v[8:11], v[108:111], v[64:67]
	v_mfma_f32_16x16x32_bf16 v[68:71], v[16:19], v[108:111], v[68:71]
	v_mfma_f32_16x16x32_bf16 v[72:75], v[24:27], v[108:111], v[72:75]
	v_mfma_f32_16x16x32_bf16 v[76:79], v[32:35], v[108:111], v[76:79]
	ds_read_b64 v[4:5], v221 offset:16384
	ds_read_b64 v[8:9], v221 offset:20480
	ds_read_b64 v[12:13], v221 offset:24576
	ds_read_b64 v[16:17], v221 offset:28672
	ds_read_b64 v[6:7], v222 offset:16384
	ds_read_b64 v[10:11], v222 offset:20480
	ds_read_b64 v[14:15], v222 offset:24576
	ds_read_b64 v[18:19], v222 offset:28672
	s_nop 1
	v_fma_f32 v64, v64, s79, v205
	v_fma_f32 v65, v65, s79, v206
	v_fma_f32 v66, v66, s79, v207
	v_fma_f32 v67, v67, s79, v208
	v_fma_f32 v68, v68, s79, v209
	v_fma_f32 v69, v69, s79, v210
	v_fma_f32 v70, v70, s79, v211
	v_fma_f32 v71, v71, s79, v212
	v_fma_f32 v72, v72, s79, v213
	v_fma_f32 v73, v73, s79, v214
	v_fma_f32 v74, v74, s79, v215
	v_fma_f32 v75, v75, s79, v216
	v_fma_f32 v76, v76, s79, v217
	v_fma_f32 v77, v77, s79, v218
	v_fma_f32 v78, v78, s79, v219
	v_fma_f32 v79, v79, s79, v220
	ds_read_b64 v[20:21], v223 offset:16384
	ds_read_b64 v[24:25], v223 offset:20480
	ds_read_b64 v[28:29], v223 offset:24576
	ds_read_b64 v[32:33], v223 offset:28672
	ds_read_b64 v[22:23], v224 offset:16384
	ds_read_b64 v[26:27], v224 offset:20480
	ds_read_b64 v[30:31], v224 offset:24576
	ds_read_b64 v[34:35], v224 offset:28672
	s_cmp_lg_u32 s4, 0
	s_cbranch_scc1 .Lat844_i1_nomask
	s_cmp_le_u32 s6, 0
	s_cbranch_scc1 .Lat844_i1_nomask
	v_mov_b32_e32 v44, v244
	v_mov_b32_e32 v45, v244
	v_mov_b32_e32 v46, v244
	v_mov_b32_e32 v47, v244
	s_cmp_le_u32 s6, 1
	s_cbranch_scc1 .Lat844_i1_nomask
	v_mov_b32_e32 v48, v244
	v_mov_b32_e32 v49, v244
	v_mov_b32_e32 v50, v244
	v_mov_b32_e32 v51, v244
	s_cmp_le_u32 s6, 2
	s_cbranch_scc1 .Lat844_i1_nomask
	v_mov_b32_e32 v52, v244
	v_mov_b32_e32 v53, v244
	v_mov_b32_e32 v54, v244
	v_mov_b32_e32 v55, v244
	s_cmp_le_u32 s6, 3
	s_cbranch_scc1 .Lat844_i1_nomask
	v_mov_b32_e32 v56, v244
	v_mov_b32_e32 v57, v244
	v_mov_b32_e32 v58, v244
	v_mov_b32_e32 v59, v244
	s_cmp_le_u32 s6, 4
	s_cbranch_scc1 .Lat844_i1_nomask
	v_mov_b32_e32 v60, v244
	v_mov_b32_e32 v61, v244
	v_mov_b32_e32 v62, v244
	v_mov_b32_e32 v63, v244
	s_cmp_le_u32 s6, 5
	s_cbranch_scc1 .Lat844_i1_nomask
	v_mov_b32_e32 v64, v244
	v_mov_b32_e32 v65, v244
	v_mov_b32_e32 v66, v244
	v_mov_b32_e32 v67, v244
	s_cmp_le_u32 s6, 6
	s_cbranch_scc1 .Lat844_i1_nomask
	v_mov_b32_e32 v68, v244
	v_mov_b32_e32 v69, v244
	v_mov_b32_e32 v70, v244
	v_mov_b32_e32 v71, v244
	s_cmp_le_u32 s6, 7
	s_cbranch_scc1 .Lat844_i1_nomask
	v_mov_b32_e32 v72, v244
	v_mov_b32_e32 v73, v244
	v_mov_b32_e32 v74, v244
	v_mov_b32_e32 v75, v244
.Lat844_i1_nomask:
	v_max3_f32 v245, v44, v45, v46
	v_max3_f32 v245, v245, v47, v48
	v_max3_f32 v245, v245, v49, v50
	v_max3_f32 v245, v245, v51, v52
	v_max3_f32 v245, v245, v53, v54
	v_max3_f32 v245, v245, v55, v56
	v_max3_f32 v245, v245, v57, v58
	v_max3_f32 v245, v245, v59, v60
	v_max3_f32 v245, v245, v61, v62
	v_max3_f32 v245, v245, v63, v64
	v_max3_f32 v245, v245, v65, v66
	v_max3_f32 v245, v245, v67, v68
	v_max3_f32 v245, v245, v69, v70
	v_max3_f32 v245, v245, v71, v72
	v_max3_f32 v245, v245, v73, v74
	v_max3_f32 v245, v245, v75, v76
	v_max3_f32 v245, v245, v77, v78
	v_max_f32_e32 v245, v245, v79
	ds_bpermute_b32 v148, v239, v245
	s_waitcnt lgkmcnt(0)
	v_max_f32_e32 v245, v245, v148
	ds_bpermute_b32 v148, v240, v245
	s_waitcnt lgkmcnt(0)
	v_max_f32_e32 v245, v245, v148
	v_sub_f32_e32 v44, v44, v245
	v_sub_f32_e32 v45, v45, v245
	v_sub_f32_e32 v46, v46, v245
	v_sub_f32_e32 v47, v47, v245
	v_exp_f32_e32 v44, v44
	v_exp_f32_e32 v45, v45
	v_exp_f32_e32 v46, v46
	v_exp_f32_e32 v47, v47
	v_sub_f32_e32 v48, v48, v245
	v_sub_f32_e32 v49, v49, v245
	v_sub_f32_e32 v50, v50, v245
	v_sub_f32_e32 v51, v51, v245
	v_exp_f32_e32 v48, v48
	v_exp_f32_e32 v49, v49
	v_exp_f32_e32 v50, v50
	v_exp_f32_e32 v51, v51
	v_mov_b32_e32 v149, v44
	v_mov_b32_e32 v150, v45
	v_mov_b32_e32 v151, v46
	v_mov_b32_e32 v152, v47
	v_cvt_pk_bf16_f32 v44, v44, v45
	v_cvt_pk_bf16_f32 v45, v46, v47
	v_sub_f32_e32 v52, v52, v245
	v_sub_f32_e32 v53, v53, v245
	v_sub_f32_e32 v54, v54, v245
	v_sub_f32_e32 v55, v55, v245
	v_exp_f32_e32 v52, v52
	v_exp_f32_e32 v53, v53
	v_exp_f32_e32 v54, v54
	v_exp_f32_e32 v55, v55
	v_add_f32_e32 v149, v149, v48
	v_add_f32_e32 v150, v150, v49
	v_add_f32_e32 v151, v151, v50
	v_add_f32_e32 v152, v152, v51
	v_cvt_pk_bf16_f32 v46, v48, v49
	v_cvt_pk_bf16_f32 v47, v50, v51
	v_sub_f32_e32 v56, v56, v245
	v_sub_f32_e32 v57, v57, v245
	v_sub_f32_e32 v58, v58, v245
	v_sub_f32_e32 v59, v59, v245
	v_exp_f32_e32 v56, v56
	v_exp_f32_e32 v57, v57
	v_exp_f32_e32 v58, v58
	v_exp_f32_e32 v59, v59
	v_add_f32_e32 v149, v149, v52
	v_add_f32_e32 v150, v150, v53
	v_add_f32_e32 v151, v151, v54
	v_add_f32_e32 v152, v152, v55
	v_cvt_pk_bf16_f32 v52, v52, v53
	v_cvt_pk_bf16_f32 v53, v54, v55
	v_sub_f32_e32 v60, v60, v245
	v_sub_f32_e32 v61, v61, v245
	v_sub_f32_e32 v62, v62, v245
	v_sub_f32_e32 v63, v63, v245
	v_exp_f32_e32 v60, v60
	v_exp_f32_e32 v61, v61
	v_exp_f32_e32 v62, v62
	v_exp_f32_e32 v63, v63
	v_add_f32_e32 v149, v149, v56
	v_add_f32_e32 v150, v150, v57
	v_add_f32_e32 v151, v151, v58
	v_add_f32_e32 v152, v152, v59
	v_cvt_pk_bf16_f32 v54, v56, v57
	v_cvt_pk_bf16_f32 v55, v58, v59
	v_sub_f32_e32 v64, v64, v245
	v_sub_f32_e32 v65, v65, v245
	v_sub_f32_e32 v66, v66, v245
	v_sub_f32_e32 v67, v67, v245
	v_exp_f32_e32 v64, v64
	v_exp_f32_e32 v65, v65
	v_exp_f32_e32 v66, v66
	v_exp_f32_e32 v67, v67
	v_add_f32_e32 v149, v149, v60
	v_add_f32_e32 v150, v150, v61
	v_add_f32_e32 v151, v151, v62
	v_add_f32_e32 v152, v152, v63
	v_cvt_pk_bf16_f32 v60, v60, v61
	v_cvt_pk_bf16_f32 v61, v62, v63
	v_sub_f32_e32 v68, v68, v245
	v_sub_f32_e32 v69, v69, v245
	v_sub_f32_e32 v70, v70, v245
	v_sub_f32_e32 v71, v71, v245
	v_exp_f32_e32 v68, v68
	v_exp_f32_e32 v69, v69
	v_exp_f32_e32 v70, v70
	v_exp_f32_e32 v71, v71
	v_add_f32_e32 v149, v149, v64
	v_add_f32_e32 v150, v150, v65
	v_add_f32_e32 v151, v151, v66
	v_add_f32_e32 v152, v152, v67
	v_cvt_pk_bf16_f32 v62, v64, v65
	v_cvt_pk_bf16_f32 v63, v66, v67
	v_sub_f32_e32 v72, v72, v245
	v_sub_f32_e32 v73, v73, v245
	v_sub_f32_e32 v74, v74, v245
	v_sub_f32_e32 v75, v75, v245
	v_exp_f32_e32 v72, v72
	v_exp_f32_e32 v73, v73
	v_exp_f32_e32 v74, v74
	v_exp_f32_e32 v75, v75
	v_add_f32_e32 v149, v149, v68
	v_add_f32_e32 v150, v150, v69
	v_add_f32_e32 v151, v151, v70
	v_add_f32_e32 v152, v152, v71
	v_cvt_pk_bf16_f32 v68, v68, v69
	v_cvt_pk_bf16_f32 v69, v70, v71
	v_sub_f32_e32 v76, v76, v245
	v_sub_f32_e32 v77, v77, v245
	v_sub_f32_e32 v78, v78, v245
	v_sub_f32_e32 v79, v79, v245
	v_exp_f32_e32 v76, v76
	v_exp_f32_e32 v77, v77
	v_exp_f32_e32 v78, v78
	v_exp_f32_e32 v79, v79
	v_add_f32_e32 v149, v149, v72
	v_add_f32_e32 v150, v150, v73
	v_add_f32_e32 v151, v151, v74
	v_add_f32_e32 v152, v152, v75
	v_cvt_pk_bf16_f32 v70, v72, v73
	v_cvt_pk_bf16_f32 v71, v74, v75
	s_nop 0
	v_add_f32_e32 v149, v149, v76
	v_add_f32_e32 v150, v150, v77
	v_add_f32_e32 v151, v151, v78
	v_add_f32_e32 v152, v152, v79
	v_cvt_pk_bf16_f32 v76, v76, v77
	v_cvt_pk_bf16_f32 v77, v78, v79
	v_mov_b32_e32 v78, 0
	v_mov_b32_e32 v79, 0
	v_add_f32_e32 v149, v149, v150
	v_add_f32_e32 v151, v151, v152
	v_add_f32_e32 v246, v149, v151
	s_waitcnt lgkmcnt(0)
	v_mfma_f32_16x16x32_bf16 v[80:83], v[4:7], v[44:47], 0
	v_mfma_f32_16x16x32_bf16 v[84:87], v[8:11], v[44:47], 0
	v_mfma_f32_16x16x32_bf16 v[88:91], v[12:15], v[44:47], 0
	v_mfma_f32_16x16x32_bf16 v[92:95], v[16:19], v[44:47], 0
	ds_read_b64 v[4:5], v225 offset:16384
	ds_read_b64 v[8:9], v225 offset:20480
	ds_read_b64 v[12:13], v225 offset:24576
	ds_read_b64 v[16:17], v225 offset:28672
	ds_read_b64 v[6:7], v226 offset:16384
	ds_read_b64 v[10:11], v226 offset:20480
	ds_read_b64 v[14:15], v226 offset:24576
	ds_read_b64 v[18:19], v226 offset:28672
	v_mfma_f32_16x16x32_bf16 v[80:83], v[20:23], v[52:55], v[80:83]
	v_mfma_f32_16x16x32_bf16 v[84:87], v[24:27], v[52:55], v[84:87]
	v_mfma_f32_16x16x32_bf16 v[88:91], v[28:31], v[52:55], v[88:91]
	v_mfma_f32_16x16x32_bf16 v[92:95], v[32:35], v[52:55], v[92:95]
	ds_read_b64 v[20:21], v227 offset:16384
	ds_read_b64 v[24:25], v227 offset:20480
	ds_read_b64 v[28:29], v227 offset:24576
	ds_read_b64 v[32:33], v227 offset:28672
	ds_read_b64 v[22:23], v228 offset:16384
	ds_read_b64 v[26:27], v228 offset:20480
	ds_read_b64 v[30:31], v228 offset:24576
	ds_read_b64 v[34:35], v228 offset:28672
	ds_bpermute_b32 v148, v239, v246
	s_waitcnt lgkmcnt(9)
	v_mfma_f32_16x16x32_bf16 v[80:83], v[4:7], v[60:63], v[80:83]
	v_mfma_f32_16x16x32_bf16 v[84:87], v[8:11], v[60:63], v[84:87]
	v_mfma_f32_16x16x32_bf16 v[88:91], v[12:15], v[60:63], v[88:91]
	v_mfma_f32_16x16x32_bf16 v[92:95], v[16:19], v[60:63], v[92:95]
	ds_read_b64 v[4:5], v229 offset:16384
	ds_read_b64 v[8:9], v229 offset:20480
	ds_read_b64 v[12:13], v229 offset:24576
	ds_read_b64 v[16:17], v229 offset:28672
	v_mov_b32_e32 v6, 0
	v_mov_b32_e32 v7, 0
	v_mov_b32_e32 v10, 0
	v_mov_b32_e32 v11, 0
	v_mov_b32_e32 v14, 0
	v_mov_b32_e32 v15, 0
	v_mov_b32_e32 v18, 0
	v_mov_b32_e32 v19, 0
	s_waitcnt lgkmcnt(5)
	v_mfma_f32_16x16x32_bf16 v[80:83], v[20:23], v[68:71], v[80:83]
	v_mfma_f32_16x16x32_bf16 v[84:87], v[24:27], v[68:71], v[84:87]
	v_mfma_f32_16x16x32_bf16 v[88:91], v[28:31], v[68:71], v[88:91]
	v_mfma_f32_16x16x32_bf16 v[92:95], v[32:35], v[68:71], v[92:95]
	s_waitcnt lgkmcnt(0)
	v_add_f32_e32 v246, v246, v148
	s_nop 0
	v_mfma_f32_16x16x32_bf16 v[80:83], v[4:7], v[76:79], v[80:83]
	v_mfma_f32_16x16x32_bf16 v[84:87], v[8:11], v[76:79], v[84:87]
	v_mfma_f32_16x16x32_bf16 v[88:91], v[12:15], v[76:79], v[88:91]
	v_mfma_f32_16x16x32_bf16 v[92:95], v[16:19], v[76:79], v[92:95]
	ds_bpermute_b32 v148, v240, v246
	s_waitcnt lgkmcnt(0)
	v_add_f32_e32 v246, v246, v148
	v_rcp_f32_e32 v149, v246
	v_log_f32_e32 v150, v246
	s_nop 0
	v_add_f32_e32 v151, v245, v150
	v_mul_f32_e32 v151, 0x3f317218, v151
	v_max_f32_e32 v152, v121, v151
	v_sub_f32_e32 v153, v121, v152
	v_sub_f32_e32 v154, v151, v152
	v_mul_f32_e32 v153, 0x3fb8aa3b, v153
	v_mul_f32_e32 v154, 0x3fb8aa3b, v154
	v_exp_f32_e32 v153, v153
	v_exp_f32_e32 v154, v154
	s_nop 0
	v_add_f32_e32 v155, v153, v154
	v_rcp_f32_e32 v146, v155
	v_log_f32_e32 v150, v155
	s_nop 0
	v_mul_f32_e32 v154, v154, v146
	v_mul_f32_e32 v146, v153, v146
	v_mul_f32_e32 v147, v149, v154
	v_mul_f32_e32 v150, 0x3f317218, v150
	v_add_f32_e32 v140, v152, v150
	v_mul_f32_e32 v80, v80, v147
	v_mul_f32_e32 v81, v81, v147
	v_mul_f32_e32 v82, v82, v147
	v_mul_f32_e32 v83, v83, v147
	v_mul_f32_e32 v84, v84, v147
	v_mul_f32_e32 v85, v85, v147
	v_mul_f32_e32 v86, v86, v147
	v_mul_f32_e32 v87, v87, v147
	v_mul_f32_e32 v88, v88, v147
	v_mul_f32_e32 v89, v89, v147
	v_mul_f32_e32 v90, v90, v147
	v_mul_f32_e32 v91, v91, v147
	v_mul_f32_e32 v92, v92, v147
	v_mul_f32_e32 v93, v93, v147
	v_mul_f32_e32 v94, v94, v147
	v_mul_f32_e32 v95, v95, v147
	v_lshlrev_b32_e32 v141, 16, v122
	v_and_b32_e32 v142, 0xffff0000, v122
	v_lshlrev_b32_e32 v143, 16, v123
	v_and_b32_e32 v144, 0xffff0000, v123
	v_fmac_f32_e32 v80, v146, v141
	v_fmac_f32_e32 v81, v146, v142
	v_fmac_f32_e32 v82, v146, v143
	v_fmac_f32_e32 v83, v146, v144
	v_cvt_pk_bf16_f32 v132, v80, v81
	v_cvt_pk_bf16_f32 v133, v82, v83
	v_lshlrev_b32_e32 v141, 16, v124
	v_and_b32_e32 v142, 0xffff0000, v124
	v_lshlrev_b32_e32 v143, 16, v125
	v_and_b32_e32 v144, 0xffff0000, v125
	v_fmac_f32_e32 v84, v146, v141
	v_fmac_f32_e32 v85, v146, v142
	v_fmac_f32_e32 v86, v146, v143
	v_fmac_f32_e32 v87, v146, v144
	v_cvt_pk_bf16_f32 v134, v84, v85
	v_cvt_pk_bf16_f32 v135, v86, v87
	v_lshlrev_b32_e32 v141, 16, v126
	v_and_b32_e32 v142, 0xffff0000, v126
	v_lshlrev_b32_e32 v143, 16, v127
	v_and_b32_e32 v144, 0xffff0000, v127
	v_fmac_f32_e32 v88, v146, v141
	v_fmac_f32_e32 v89, v146, v142
	v_fmac_f32_e32 v90, v146, v143
	v_fmac_f32_e32 v91, v146, v144
	v_cvt_pk_bf16_f32 v136, v88, v89
	v_cvt_pk_bf16_f32 v137, v90, v91
	v_lshlrev_b32_e32 v141, 16, v128
	v_and_b32_e32 v142, 0xffff0000, v128
	v_lshlrev_b32_e32 v143, 16, v129
	v_and_b32_e32 v144, 0xffff0000, v129
	v_fmac_f32_e32 v92, v146, v141
	v_fmac_f32_e32 v93, v146, v142
	v_fmac_f32_e32 v94, v146, v143
	v_fmac_f32_e32 v95, v146, v144
	v_cvt_pk_bf16_f32 v138, v92, v93
	v_cvt_pk_bf16_f32 v139, v94, v95
	s_mov_b64 s[26:27], s[86:87]
	s_mov_b64 s[28:29], s[88:89]
	s_mov_b64 s[86:87], s[12:13]
	s_mov_b64 s[88:89], s[14:15]
	s_mov_b32 s4, s83
	s_mov_b32 s5, s84
	s_waitcnt vmcnt(0)
	s_barrier
	s_cmp_gt_u32 s6, 0
	s_cselect_b32 s74, s77, s78
	v_add_u32_e32 v146, s74, v230
	v_xor_b32_e32 v147, 64, v146
	ds_read_b128 v[4:7], v146 offset:0
	ds_read_b128 v[8:11], v147 offset:0
	s_cmp_gt_u32 s6, 1
	s_cselect_b32 s74, s77, s78
	v_add_u32_e32 v146, s74, v230
	v_xor_b32_e32 v147, 64, v146
	ds_read_b128 v[12:15], v146 offset:2048
	ds_read_b128 v[16:19], v147 offset:2048
	s_cmp_gt_u32 s6, 2
	s_cselect_b32 s74, s77, s78
	v_add_u32_e32 v146, s74, v230
	v_xor_b32_e32 v147, 64, v146
	ds_read_b128 v[20:23], v146 offset:4096
	ds_read_b128 v[24:27], v147 offset:4096
	s_cmp_gt_u32 s6, 3
	s_cselect_b32 s74, s77, s78
	v_add_u32_e32 v146, s74, v230
	v_xor_b32_e32 v147, 64, v146
	ds_read_b128 v[28:31], v146 offset:6144
	ds_read_b128 v[32:35], v147 offset:6144
	s_cmp_gt_u32 s6, 4
	s_cselect_b32 s74, s77, s78
	v_add_u32_e32 v146, s74, v230
	v_xor_b32_e32 v147, 64, v146
	ds_read_b128 v[36:39], v146 offset:8192
	ds_read_b128 v[40:43], v147 offset:8192
	global_store_dwordx2 v237, v[132:133], s[26:27]
	global_store_dwordx2 v237, v[134:135], s[26:27] offset:32
	global_store_dwordx2 v237, v[136:137], s[26:27] offset:64
	global_store_dwordx2 v237, v[138:139], s[26:27] offset:96
	s_mov_b64 s[90:91], exec
	s_mov_b64 exec, 0xffff
	global_store_dword v238, v140, s[28:29]
	s_mov_b64 exec, s[90:91]
	s_add_u32 s83, s9, 1
	s_mov_b32 s84, 1
	s_mul_i32 s74, s84, 1024
	s_lshl_b32 s75, s83, 7
	s_add_u32 s74, s74, s75
	s_lshl_b32 s75, s74, 7
	s_add_u32 s16, s60, s75
	s_addc_u32 s17, s61, 0
	s_lshl_b32 s75, s74, 1
	s_add_u32 s24, s64, s75
	s_addc_u32 s25, s65, 0
	s_add_u32 m0, s70, 0x4000
	s_nop 0
	global_load_lds_dwordx4 v232, s[16:17]
	s_add_u32 m0, s70, 0x6000
	s_nop 0
	global_load_lds_dwordx4 v233, s[16:17]
	s_add_u32 m0, s70, 0x14000
	s_nop 0
	global_load_lds_dwordx4 v234, s[24:25]
	s_add_u32 m0, s70, 0x16000
	s_nop 0
	global_load_lds_dwordx4 v235, s[24:25]
	s_lshl_b32 s74, s83, 9
	s_add_u32 s74, s74, s84
	s_lshl_b32 s75, s74, 7
	s_add_u32 s10, s30, s75
	s_addc_u32 s11, s31, 0
	s_add_u32 s12, s34, s75
	s_addc_u32 s13, s35, 0
	s_lshl_b32 s75, s74, 2
	s_add_u32 s14, s58, s75
	s_addc_u32 s15, s59, 0
	global_load_dwordx4 v[104:107], v236, s[10:11]
	global_load_dwordx4 v[108:111], v236, s[10:11] offset:64
	global_load_dwordx2 v[122:123], v237, s[12:13]
	global_load_dwordx2 v[124:125], v237, s[12:13] offset:32
	global_load_dwordx2 v[126:127], v237, s[12:13] offset:64
	global_load_dwordx2 v[128:129], v237, s[12:13] offset:96
	global_load_dword v121, v238, s[14:15]
	s_waitcnt lgkmcnt(0)
	v_mfma_f32_16x16x32_bf16 v[44:47], v[4:7], v[96:99], 0
	v_mfma_f32_16x16x32_bf16 v[48:51], v[12:15], v[96:99], 0
	v_mfma_f32_16x16x32_bf16 v[52:55], v[20:23], v[96:99], 0
	v_mfma_f32_16x16x32_bf16 v[56:59], v[28:31], v[96:99], 0
	v_mfma_f32_16x16x32_bf16 v[60:63], v[36:39], v[96:99], 0
	v_mfma_f32_16x16x32_bf16 v[44:47], v[8:11], v[100:103], v[44:47]
	v_mfma_f32_16x16x32_bf16 v[48:51], v[16:19], v[100:103], v[48:51]
	v_mfma_f32_16x16x32_bf16 v[52:55], v[24:27], v[100:103], v[52:55]
	v_mfma_f32_16x16x32_bf16 v[56:59], v[32:35], v[100:103], v[56:59]
	v_mfma_f32_16x16x32_bf16 v[60:63], v[40:43], v[100:103], v[60:63]
	s_cmp_gt_u32 s6, 5
	s_cselect_b32 s74, s77, s78
	v_add_u32_e32 v146, s74, v230
	v_xor_b32_e32 v147, 64, v146
	ds_read_b128 v[4:7], v146 offset:10240
	ds_read_b128 v[8:11], v147 offset:10240
	s_cmp_gt_u32 s6, 6
	s_cselect_b32 s74, s77, s78
	v_add_u32_e32 v146, s74, v230
	v_xor_b32_e32 v147, 64, v146
	ds_read_b128 v[12:15], v146 offset:12288
	ds_read_b128 v[16:19], v147 offset:12288
	s_cmp_gt_u32 s6, 7
	s_cselect_b32 s74, s77, s78
	v_add_u32_e32 v146, s74, v230
	v_xor_b32_e32 v147, 64, v146
	ds_read_b128 v[20:23], v146 offset:14336
	ds_read_b128 v[24:27], v147 offset:14336
	s_cmp_gt_u32 s6, 8
	s_cselect_b32 s74, s77, s78
	v_add_u32_e32 v146, s74, v230
	v_xor_b32_e32 v147, 64, v146
	ds_read_b128 v[28:31], v146 offset:16384
	ds_read_b128 v[32:35], v147 offset:16384
	s_nop 1
	v_fma_f32 v44, v44, s79, v185
	v_fma_f32 v45, v45, s79, v186
	v_fma_f32 v46, v46, s79, v187
	v_fma_f32 v47, v47, s79, v188
	v_fma_f32 v48, v48, s79, v189
	v_fma_f32 v49, v49, s79, v190
	v_fma_f32 v50, v50, s79, v191
	v_fma_f32 v51, v51, s79, v192
	v_fma_f32 v52, v52, s79, v193
	v_fma_f32 v53, v53, s79, v194
	v_fma_f32 v54, v54, s79, v195
	v_fma_f32 v55, v55, s79, v196
	v_fma_f32 v56, v56, s79, v197
	v_fma_f32 v57, v57, s79, v198
	v_fma_f32 v58, v58, s79, v199
	v_fma_f32 v59, v59, s79, v200
	v_fma_f32 v60, v60, s79, v201
	v_fma_f32 v61, v61, s79, v202
	v_fma_f32 v62, v62, s79, v203
	v_fma_f32 v63, v63, s79, v204
	s_waitcnt lgkmcnt(0)
	v_mfma_f32_16x16x32_bf16 v[64:67], v[4:7], v[96:99], 0
	v_mfma_f32_16x16x32_bf16 v[68:71], v[12:15], v[96:99], 0
	v_mfma_f32_16x16x32_bf16 v[72:75], v[20:23], v[96:99], 0
	v_mfma_f32_16x16x32_bf16 v[76:79], v[28:31], v[96:99], 0
	v_mfma_f32_16x16x32_bf16 v[64:67], v[8:11], v[100:103], v[64:67]
	v_mfma_f32_16x16x32_bf16 v[68:71], v[16:19], v[100:103], v[68:71]
	v_mfma_f32_16x16x32_bf16 v[72:75], v[24:27], v[100:103], v[72:75]
	v_mfma_f32_16x16x32_bf16 v[76:79], v[32:35], v[100:103], v[76:79]
	s_cmp_gt_u32 s6, 0
	s_cselect_b32 s74, 0, 0xffff0000
	v_add_u32_e32 v146, s74, v221
	ds_read_b64 v[4:5], v146 offset:49152
	ds_read_b64 v[8:9], v146 offset:53248
	ds_read_b64 v[12:13], v146 offset:57344
	ds_read_b64 v[16:17], v146 offset:61440
	s_cmp_gt_u32 s6, 1
	s_cselect_b32 s74, 0, 0xffff0000
	v_add_u32_e32 v146, s74, v222
	ds_read_b64 v[6:7], v146 offset:49152
	ds_read_b64 v[10:11], v146 offset:53248
	ds_read_b64 v[14:15], v146 offset:57344
	ds_read_b64 v[18:19], v146 offset:61440
	s_nop 1
	v_fma_f32 v64, v64, s79, v205
	v_fma_f32 v65, v65, s79, v206
	v_fma_f32 v66, v66, s79, v207
	v_fma_f32 v67, v67, s79, v208
	v_fma_f32 v68, v68, s79, v209
	v_fma_f32 v69, v69, s79, v210
	v_fma_f32 v70, v70, s79, v211
	v_fma_f32 v71, v71, s79, v212
	v_fma_f32 v72, v72, s79, v213
	v_fma_f32 v73, v73, s79, v214
	v_fma_f32 v74, v74, s79, v215
	v_fma_f32 v75, v75, s79, v216
	v_fma_f32 v76, v76, s79, v217
	v_fma_f32 v77, v77, s79, v218
	v_fma_f32 v78, v78, s79, v219
	v_fma_f32 v79, v79, s79, v220
	s_cmp_gt_u32 s6, 2
	s_cselect_b32 s74, 0, 0xffff0000
	v_add_u32_e32 v146, s74, v223
	ds_read_b64 v[20:21], v146 offset:49152
	ds_read_b64 v[24:25], v146 offset:53248
	ds_read_b64 v[28:29], v146 offset:57344
	ds_read_b64 v[32:33], v146 offset:61440
	s_cmp_gt_u32 s6, 3
	s_cselect_b32 s74, 0, 0xffff0000
	v_add_u32_e32 v146, s74, v224
	ds_read_b64 v[22:23], v146 offset:49152
	ds_read_b64 v[26:27], v146 offset:53248
	ds_read_b64 v[30:31], v146 offset:57344
	ds_read_b64 v[34:35], v146 offset:61440
	s_cmp_lg_u32 s4, 0
	s_cbranch_scc1 .Lat844_i2_nomask
	s_cmp_le_u32 s6, 0
	s_cbranch_scc1 .Lat844_i2_nomask
	v_mov_b32_e32 v44, v244
	v_mov_b32_e32 v45, v244
	v_mov_b32_e32 v46, v244
	v_mov_b32_e32 v47, v244
	s_cmp_le_u32 s6, 1
	s_cbranch_scc1 .Lat844_i2_nomask
	v_mov_b32_e32 v48, v244
	v_mov_b32_e32 v49, v244
	v_mov_b32_e32 v50, v244
	v_mov_b32_e32 v51, v244
	s_cmp_le_u32 s6, 2
	s_cbranch_scc1 .Lat844_i2_nomask
	v_mov_b32_e32 v52, v244
	v_mov_b32_e32 v53, v244
	v_mov_b32_e32 v54, v244
	v_mov_b32_e32 v55, v244
	s_cmp_le_u32 s6, 3
	s_cbranch_scc1 .Lat844_i2_nomask
	v_mov_b32_e32 v56, v244
	v_mov_b32_e32 v57, v244
	v_mov_b32_e32 v58, v244
	v_mov_b32_e32 v59, v244
	s_cmp_le_u32 s6, 4
	s_cbranch_scc1 .Lat844_i2_nomask
	v_mov_b32_e32 v60, v244
	v_mov_b32_e32 v61, v244
	v_mov_b32_e32 v62, v244
	v_mov_b32_e32 v63, v244
	s_cmp_le_u32 s6, 5
	s_cbranch_scc1 .Lat844_i2_nomask
	v_mov_b32_e32 v64, v244
	v_mov_b32_e32 v65, v244
	v_mov_b32_e32 v66, v244
	v_mov_b32_e32 v67, v244
	s_cmp_le_u32 s6, 6
	s_cbranch_scc1 .Lat844_i2_nomask
	v_mov_b32_e32 v68, v244
	v_mov_b32_e32 v69, v244
	v_mov_b32_e32 v70, v244
	v_mov_b32_e32 v71, v244
	s_cmp_le_u32 s6, 7
	s_cbranch_scc1 .Lat844_i2_nomask
	v_mov_b32_e32 v72, v244
	v_mov_b32_e32 v73, v244
	v_mov_b32_e32 v74, v244
	v_mov_b32_e32 v75, v244
.Lat844_i2_nomask:
	v_max3_f32 v245, v44, v45, v46
	v_max3_f32 v245, v245, v47, v48
	v_max3_f32 v245, v245, v49, v50
	v_max3_f32 v245, v245, v51, v52
	v_max3_f32 v245, v245, v53, v54
	v_max3_f32 v245, v245, v55, v56
	v_max3_f32 v245, v245, v57, v58
	v_max3_f32 v245, v245, v59, v60
	v_max3_f32 v245, v245, v61, v62
	v_max3_f32 v245, v245, v63, v64
	v_max3_f32 v245, v245, v65, v66
	v_max3_f32 v245, v245, v67, v68
	v_max3_f32 v245, v245, v69, v70
	v_max3_f32 v245, v245, v71, v72
	v_max3_f32 v245, v245, v73, v74
	v_max3_f32 v245, v245, v75, v76
	v_max3_f32 v245, v245, v77, v78
	v_max_f32_e32 v245, v245, v79
	ds_bpermute_b32 v148, v239, v245
	s_waitcnt lgkmcnt(0)
	v_max_f32_e32 v245, v245, v148
	ds_bpermute_b32 v148, v240, v245
	s_waitcnt lgkmcnt(0)
	v_max_f32_e32 v245, v245, v148
	v_sub_f32_e32 v44, v44, v245
	v_sub_f32_e32 v45, v45, v245
	v_sub_f32_e32 v46, v46, v245
	v_sub_f32_e32 v47, v47, v245
	v_exp_f32_e32 v44, v44
	v_exp_f32_e32 v45, v45
	v_exp_f32_e32 v46, v46
	v_exp_f32_e32 v47, v47
	v_sub_f32_e32 v48, v48, v245
	v_sub_f32_e32 v49, v49, v245
	v_sub_f32_e32 v50, v50, v245
	v_sub_f32_e32 v51, v51, v245
	v_exp_f32_e32 v48, v48
	v_exp_f32_e32 v49, v49
	v_exp_f32_e32 v50, v50
	v_exp_f32_e32 v51, v51
	v_mov_b32_e32 v149, v44
	v_mov_b32_e32 v150, v45
	v_mov_b32_e32 v151, v46
	v_mov_b32_e32 v152, v47
	v_cvt_pk_bf16_f32 v44, v44, v45
	v_cvt_pk_bf16_f32 v45, v46, v47
	v_sub_f32_e32 v52, v52, v245
	v_sub_f32_e32 v53, v53, v245
	v_sub_f32_e32 v54, v54, v245
	v_sub_f32_e32 v55, v55, v245
	v_exp_f32_e32 v52, v52
	v_exp_f32_e32 v53, v53
	v_exp_f32_e32 v54, v54
	v_exp_f32_e32 v55, v55
	v_add_f32_e32 v149, v149, v48
	v_add_f32_e32 v150, v150, v49
	v_add_f32_e32 v151, v151, v50
	v_add_f32_e32 v152, v152, v51
	v_cvt_pk_bf16_f32 v46, v48, v49
	v_cvt_pk_bf16_f32 v47, v50, v51
	v_sub_f32_e32 v56, v56, v245
	v_sub_f32_e32 v57, v57, v245
	v_sub_f32_e32 v58, v58, v245
	v_sub_f32_e32 v59, v59, v245
	v_exp_f32_e32 v56, v56
	v_exp_f32_e32 v57, v57
	v_exp_f32_e32 v58, v58
	v_exp_f32_e32 v59, v59
	v_add_f32_e32 v149, v149, v52
	v_add_f32_e32 v150, v150, v53
	v_add_f32_e32 v151, v151, v54
	v_add_f32_e32 v152, v152, v55
	v_cvt_pk_bf16_f32 v52, v52, v53
	v_cvt_pk_bf16_f32 v53, v54, v55
	v_sub_f32_e32 v60, v60, v245
	v_sub_f32_e32 v61, v61, v245
	v_sub_f32_e32 v62, v62, v245
	v_sub_f32_e32 v63, v63, v245
	v_exp_f32_e32 v60, v60
	v_exp_f32_e32 v61, v61
	v_exp_f32_e32 v62, v62
	v_exp_f32_e32 v63, v63
	v_add_f32_e32 v149, v149, v56
	v_add_f32_e32 v150, v150, v57
	v_add_f32_e32 v151, v151, v58
	v_add_f32_e32 v152, v152, v59
	v_cvt_pk_bf16_f32 v54, v56, v57
	v_cvt_pk_bf16_f32 v55, v58, v59
	v_sub_f32_e32 v64, v64, v245
	v_sub_f32_e32 v65, v65, v245
	v_sub_f32_e32 v66, v66, v245
	v_sub_f32_e32 v67, v67, v245
	v_exp_f32_e32 v64, v64
	v_exp_f32_e32 v65, v65
	v_exp_f32_e32 v66, v66
	v_exp_f32_e32 v67, v67
	v_add_f32_e32 v149, v149, v60
	v_add_f32_e32 v150, v150, v61
	v_add_f32_e32 v151, v151, v62
	v_add_f32_e32 v152, v152, v63
	v_cvt_pk_bf16_f32 v60, v60, v61
	v_cvt_pk_bf16_f32 v61, v62, v63
	v_sub_f32_e32 v68, v68, v245
	v_sub_f32_e32 v69, v69, v245
	v_sub_f32_e32 v70, v70, v245
	v_sub_f32_e32 v71, v71, v245
	v_exp_f32_e32 v68, v68
	v_exp_f32_e32 v69, v69
	v_exp_f32_e32 v70, v70
	v_exp_f32_e32 v71, v71
	v_add_f32_e32 v149, v149, v64
	v_add_f32_e32 v150, v150, v65
	v_add_f32_e32 v151, v151, v66
	v_add_f32_e32 v152, v152, v67
	v_cvt_pk_bf16_f32 v62, v64, v65
	v_cvt_pk_bf16_f32 v63, v66, v67
	v_sub_f32_e32 v72, v72, v245
	v_sub_f32_e32 v73, v73, v245
	v_sub_f32_e32 v74, v74, v245
	v_sub_f32_e32 v75, v75, v245
	v_exp_f32_e32 v72, v72
	v_exp_f32_e32 v73, v73
	v_exp_f32_e32 v74, v74
	v_exp_f32_e32 v75, v75
	v_add_f32_e32 v149, v149, v68
	v_add_f32_e32 v150, v150, v69
	v_add_f32_e32 v151, v151, v70
	v_add_f32_e32 v152, v152, v71
	v_cvt_pk_bf16_f32 v68, v68, v69
	v_cvt_pk_bf16_f32 v69, v70, v71
	v_sub_f32_e32 v76, v76, v245
	v_sub_f32_e32 v77, v77, v245
	v_sub_f32_e32 v78, v78, v245
	v_sub_f32_e32 v79, v79, v245
	v_exp_f32_e32 v76, v76
	v_exp_f32_e32 v77, v77
	v_exp_f32_e32 v78, v78
	v_exp_f32_e32 v79, v79
	v_add_f32_e32 v149, v149, v72
	v_add_f32_e32 v150, v150, v73
	v_add_f32_e32 v151, v151, v74
	v_add_f32_e32 v152, v152, v75
	v_cvt_pk_bf16_f32 v70, v72, v73
	v_cvt_pk_bf16_f32 v71, v74, v75
	s_nop 0
	v_add_f32_e32 v149, v149, v76
	v_add_f32_e32 v150, v150, v77
	v_add_f32_e32 v151, v151, v78
	v_add_f32_e32 v152, v152, v79
	v_cvt_pk_bf16_f32 v76, v76, v77
	v_cvt_pk_bf16_f32 v77, v78, v79
	v_mov_b32_e32 v78, 0
	v_mov_b32_e32 v79, 0
	v_add_f32_e32 v149, v149, v150
	v_add_f32_e32 v151, v151, v152
	v_add_f32_e32 v246, v149, v151
	s_waitcnt lgkmcnt(0)
	v_mfma_f32_16x16x32_bf16 v[80:83], v[4:7], v[44:47], 0
	v_mfma_f32_16x16x32_bf16 v[84:87], v[8:11], v[44:47], 0
	v_mfma_f32_16x16x32_bf16 v[88:91], v[12:15], v[44:47], 0
	v_mfma_f32_16x16x32_bf16 v[92:95], v[16:19], v[44:47], 0
	s_cmp_gt_u32 s6, 4
	s_cselect_b32 s74, 0, 0xffff0000
	v_add_u32_e32 v146, s74, v225
	ds_read_b64 v[4:5], v146 offset:49152
	ds_read_b64 v[8:9], v146 offset:53248
	ds_read_b64 v[12:13], v146 offset:57344
	ds_read_b64 v[16:17], v146 offset:61440
	s_cmp_gt_u32 s6, 5
	s_cselect_b32 s74, 0, 0xffff0000
	v_add_u32_e32 v146, s74, v226
	ds_read_b64 v[6:7], v146 offset:49152
	ds_read_b64 v[10:11], v146 offset:53248
	ds_read_b64 v[14:15], v146 offset:57344
	ds_read_b64 v[18:19], v146 offset:61440
	v_mfma_f32_16x16x32_bf16 v[80:83], v[20:23], v[52:55], v[80:83]
	v_mfma_f32_16x16x32_bf16 v[84:87], v[24:27], v[52:55], v[84:87]
	v_mfma_f32_16x16x32_bf16 v[88:91], v[28:31], v[52:55], v[88:91]
	v_mfma_f32_16x16x32_bf16 v[92:95], v[32:35], v[52:55], v[92:95]
	s_cmp_gt_u32 s6, 6
	s_cselect_b32 s74, 0, 0xffff0000
	v_add_u32_e32 v146, s74, v227
	ds_read_b64 v[20:21], v146 offset:49152
	ds_read_b64 v[24:25], v146 offset:53248
	ds_read_b64 v[28:29], v146 offset:57344
	ds_read_b64 v[32:33], v146 offset:61440
	s_cmp_gt_u32 s6, 7
	s_cselect_b32 s74, 0, 0xffff0000
	v_add_u32_e32 v146, s74, v228
	ds_read_b64 v[22:23], v146 offset:49152
	ds_read_b64 v[26:27], v146 offset:53248
	ds_read_b64 v[30:31], v146 offset:57344
	ds_read_b64 v[34:35], v146 offset:61440
	ds_bpermute_b32 v148, v239, v246
	s_waitcnt lgkmcnt(9)
	v_mfma_f32_16x16x32_bf16 v[80:83], v[4:7], v[60:63], v[80:83]
	v_mfma_f32_16x16x32_bf16 v[84:87], v[8:11], v[60:63], v[84:87]
	v_mfma_f32_16x16x32_bf16 v[88:91], v[12:15], v[60:63], v[88:91]
	v_mfma_f32_16x16x32_bf16 v[92:95], v[16:19], v[60:63], v[92:95]
	s_cmp_gt_u32 s6, 8
	s_cselect_b32 s74, 0, 0xffff0000
	v_add_u32_e32 v146, s74, v229
	ds_read_b64 v[4:5], v146 offset:49152
	ds_read_b64 v[8:9], v146 offset:53248
	ds_read_b64 v[12:13], v146 offset:57344
	ds_read_b64 v[16:17], v146 offset:61440
	v_mov_b32_e32 v6, 0
	v_mov_b32_e32 v7, 0
	v_mov_b32_e32 v10, 0
	v_mov_b32_e32 v11, 0
	v_mov_b32_e32 v14, 0
	v_mov_b32_e32 v15, 0
	v_mov_b32_e32 v18, 0
	v_mov_b32_e32 v19, 0
	s_waitcnt lgkmcnt(5)
	v_mfma_f32_16x16x32_bf16 v[80:83], v[20:23], v[68:71], v[80:83]
	v_mfma_f32_16x16x32_bf16 v[84:87], v[24:27], v[68:71], v[84:87]
	v_mfma_f32_16x16x32_bf16 v[88:91], v[28:31], v[68:71], v[88:91]
	v_mfma_f32_16x16x32_bf16 v[92:95], v[32:35], v[68:71], v[92:95]
	s_waitcnt lgkmcnt(0)
	v_add_f32_e32 v246, v246, v148
	s_nop 0
	v_mfma_f32_16x16x32_bf16 v[80:83], v[4:7], v[76:79], v[80:83]
	v_mfma_f32_16x16x32_bf16 v[84:87], v[8:11], v[76:79], v[84:87]
	v_mfma_f32_16x16x32_bf16 v[88:91], v[12:15], v[76:79], v[88:91]
	v_mfma_f32_16x16x32_bf16 v[92:95], v[16:19], v[76:79], v[92:95]
	ds_bpermute_b32 v148, v240, v246
	s_waitcnt lgkmcnt(0)
	v_add_f32_e32 v246, v246, v148
	v_rcp_f32_e32 v149, v246
	v_log_f32_e32 v150, v246
	s_nop 0
	v_add_f32_e32 v151, v245, v150
	v_mul_f32_e32 v151, 0x3f317218, v151
	v_max_f32_e32 v152, v120, v151
	v_sub_f32_e32 v153, v120, v152
	v_sub_f32_e32 v154, v151, v152
	v_mul_f32_e32 v153, 0x3fb8aa3b, v153
	v_mul_f32_e32 v154, 0x3fb8aa3b, v154
	v_exp_f32_e32 v153, v153
	v_exp_f32_e32 v154, v154
	s_nop 0
	v_add_f32_e32 v155, v153, v154
	v_rcp_f32_e32 v146, v155
	v_log_f32_e32 v150, v155
	s_nop 0
	v_mul_f32_e32 v154, v154, v146
	v_mul_f32_e32 v146, v153, v146
	v_mul_f32_e32 v147, v149, v154
	v_mul_f32_e32 v150, 0x3f317218, v150
	v_add_f32_e32 v140, v152, v150
	v_mul_f32_e32 v80, v80, v147
	v_mul_f32_e32 v81, v81, v147
	v_mul_f32_e32 v82, v82, v147
	v_mul_f32_e32 v83, v83, v147
	v_mul_f32_e32 v84, v84, v147
	v_mul_f32_e32 v85, v85, v147
	v_mul_f32_e32 v86, v86, v147
	v_mul_f32_e32 v87, v87, v147
	v_mul_f32_e32 v88, v88, v147
	v_mul_f32_e32 v89, v89, v147
	v_mul_f32_e32 v90, v90, v147
	v_mul_f32_e32 v91, v91, v147
	v_mul_f32_e32 v92, v92, v147
	v_mul_f32_e32 v93, v93, v147
	v_mul_f32_e32 v94, v94, v147
	v_mul_f32_e32 v95, v95, v147
	v_lshlrev_b32_e32 v141, 16, v112
	v_and_b32_e32 v142, 0xffff0000, v112
	v_lshlrev_b32_e32 v143, 16, v113
	v_and_b32_e32 v144, 0xffff0000, v113
	v_fmac_f32_e32 v80, v146, v141
	v_fmac_f32_e32 v81, v146, v142
	v_fmac_f32_e32 v82, v146, v143
	v_fmac_f32_e32 v83, v146, v144
	v_cvt_pk_bf16_f32 v132, v80, v81
	v_cvt_pk_bf16_f32 v133, v82, v83
	v_lshlrev_b32_e32 v141, 16, v114
	v_and_b32_e32 v142, 0xffff0000, v114
	v_lshlrev_b32_e32 v143, 16, v115
	v_and_b32_e32 v144, 0xffff0000, v115
	v_fmac_f32_e32 v84, v146, v141
	v_fmac_f32_e32 v85, v146, v142
	v_fmac_f32_e32 v86, v146, v143
	v_fmac_f32_e32 v87, v146, v144
	v_cvt_pk_bf16_f32 v134, v84, v85
	v_cvt_pk_bf16_f32 v135, v86, v87
	v_lshlrev_b32_e32 v141, 16, v116
	v_and_b32_e32 v142, 0xffff0000, v116
	v_lshlrev_b32_e32 v143, 16, v117
	v_and_b32_e32 v144, 0xffff0000, v117
	v_fmac_f32_e32 v88, v146, v141
	v_fmac_f32_e32 v89, v146, v142
	v_fmac_f32_e32 v90, v146, v143
	v_fmac_f32_e32 v91, v146, v144
	v_cvt_pk_bf16_f32 v136, v88, v89
	v_cvt_pk_bf16_f32 v137, v90, v91
	v_lshlrev_b32_e32 v141, 16, v118
	v_and_b32_e32 v142, 0xffff0000, v118
	v_lshlrev_b32_e32 v143, 16, v119
	v_and_b32_e32 v144, 0xffff0000, v119
	v_fmac_f32_e32 v92, v146, v141
	v_fmac_f32_e32 v93, v146, v142
	v_fmac_f32_e32 v94, v146, v143
	v_fmac_f32_e32 v95, v146, v144
	v_cvt_pk_bf16_f32 v138, v92, v93
	v_cvt_pk_bf16_f32 v139, v94, v95
	s_mov_b64 s[26:27], s[86:87]
	s_mov_b64 s[28:29], s[88:89]
	s_mov_b64 s[86:87], s[12:13]
	s_mov_b64 s[88:89], s[14:15]
	s_mov_b32 s4, s83
	s_mov_b32 s5, s84
	s_waitcnt vmcnt(0)
	s_barrier
	ds_read_b128 v[4:7], v230 offset:0
	ds_read_b128 v[8:11], v231 offset:0
	ds_read_b128 v[12:15], v230 offset:2048
	ds_read_b128 v[16:19], v231 offset:2048
	ds_read_b128 v[20:23], v230 offset:4096
	ds_read_b128 v[24:27], v231 offset:4096
	ds_read_b128 v[28:31], v230 offset:6144
	ds_read_b128 v[32:35], v231 offset:6144
	ds_read_b128 v[36:39], v230 offset:8192
	ds_read_b128 v[40:43], v231 offset:8192
	global_store_dwordx2 v237, v[132:133], s[26:27]
	global_store_dwordx2 v237, v[134:135], s[26:27] offset:32
	global_store_dwordx2 v237, v[136:137], s[26:27] offset:64
	global_store_dwordx2 v237, v[138:139], s[26:27] offset:96
	s_mov_b64 s[90:91], exec
	s_mov_b64 exec, 0xffff
	global_store_dword v238, v140, s[28:29]
	s_mov_b64 exec, s[90:91]
	s_add_u32 s83, s9, 0
	s_mov_b32 s84, 2
	s_sub_u32 s76, s83, 1
	s_max_i32 s76, s76, 0
	s_mul_i32 s74, s84, 1024
	s_lshl_b32 s75, s76, 7
	s_add_u32 s74, s74, s75
	s_lshl_b32 s75, s74, 7
	s_add_u32 s16, s60, s75
	s_addc_u32 s17, s61, 0
	s_lshl_b32 s75, s74, 1
	s_add_u32 s24, s64, s75
	s_addc_u32 s25, s65, 0
	s_add_u32 m0, s70, 0x8000
	s_nop 0
	global_load_lds_dwordx4 v232, s[16:17]
	s_add_u32 m0, s70, 0xa000
	s_nop 0
	global_load_lds_dwordx4 v233, s[16:17]
	s_add_u32 m0, s70, 0x18000
	s_nop 0
	global_load_lds_dwordx4 v234, s[24:25]
	s_add_u32 m0, s70, 0x1a000
	s_nop 0
	global_load_lds_dwordx4 v235, s[24:25]
	s_mul_i32 s74, s84, 1024
	s_lshl_b32 s75, s83, 7
	s_add_u32 s74, s74, s75
	s_lshl_b32 s75, s74, 7
	s_add_u32 s16, s60, s75
	s_addc_u32 s17, s61, 0
	s_lshl_b32 s75, s74, 1
	s_add_u32 s24, s64, s75
	s_addc_u32 s25, s65, 0
	s_add_u32 m0, s70, 0xc000
	s_nop 0
	global_load_lds_dwordx4 v232, s[16:17]
	s_add_u32 m0, s70, 0xe000
	s_nop 0
	global_load_lds_dwordx4 v233, s[16:17]
	s_add_u32 m0, s70, 0x1c000
	s_nop 0
	global_load_lds_dwordx4 v234, s[24:25]
	s_add_u32 m0, s70, 0x1e000
	s_nop 0
	global_load_lds_dwordx4 v235, s[24:25]
	s_lshl_b32 s74, s83, 9
	s_add_u32 s74, s74, s84
	s_lshl_b32 s75, s74, 7
	s_add_u32 s10, s30, s75
	s_addc_u32 s11, s31, 0
	s_add_u32 s12, s34, s75
	s_addc_u32 s13, s35, 0
	s_lshl_b32 s75, s74, 2
	s_add_u32 s14, s58, s75
	s_addc_u32 s15, s59, 0
	global_load_dwordx4 v[96:99], v236, s[10:11]
	global_load_dwordx4 v[100:103], v236, s[10:11] offset:64
	global_load_dwordx2 v[112:113], v237, s[12:13]
	global_load_dwordx2 v[114:115], v237, s[12:13] offset:32
	global_load_dwordx2 v[116:117], v237, s[12:13] offset:64
	global_load_dwordx2 v[118:119], v237, s[12:13] offset:96
	global_load_dword v120, v238, s[14:15]
	s_waitcnt lgkmcnt(0)
	v_mfma_f32_16x16x32_bf16 v[44:47], v[4:7], v[104:107], 0
	v_mfma_f32_16x16x32_bf16 v[48:51], v[12:15], v[104:107], 0
	v_mfma_f32_16x16x32_bf16 v[52:55], v[20:23], v[104:107], 0
	v_mfma_f32_16x16x32_bf16 v[56:59], v[28:31], v[104:107], 0
	v_mfma_f32_16x16x32_bf16 v[60:63], v[36:39], v[104:107], 0
	v_mfma_f32_16x16x32_bf16 v[44:47], v[8:11], v[108:111], v[44:47]
	v_mfma_f32_16x16x32_bf16 v[48:51], v[16:19], v[108:111], v[48:51]
	v_mfma_f32_16x16x32_bf16 v[52:55], v[24:27], v[108:111], v[52:55]
	v_mfma_f32_16x16x32_bf16 v[56:59], v[32:35], v[108:111], v[56:59]
	v_mfma_f32_16x16x32_bf16 v[60:63], v[40:43], v[108:111], v[60:63]
	ds_read_b128 v[4:7], v230 offset:10240
	ds_read_b128 v[8:11], v231 offset:10240
	ds_read_b128 v[12:15], v230 offset:12288
	ds_read_b128 v[16:19], v231 offset:12288
	ds_read_b128 v[20:23], v230 offset:14336
	ds_read_b128 v[24:27], v231 offset:14336
	ds_read_b128 v[28:31], v230 offset:16384
	ds_read_b128 v[32:35], v231 offset:16384
	s_nop 1
	v_fma_f32 v44, v44, s79, v185
	v_fma_f32 v45, v45, s79, v186
	v_fma_f32 v46, v46, s79, v187
	v_fma_f32 v47, v47, s79, v188
	v_fma_f32 v48, v48, s79, v189
	v_fma_f32 v49, v49, s79, v190
	v_fma_f32 v50, v50, s79, v191
	v_fma_f32 v51, v51, s79, v192
	v_fma_f32 v52, v52, s79, v193
	v_fma_f32 v53, v53, s79, v194
	v_fma_f32 v54, v54, s79, v195
	v_fma_f32 v55, v55, s79, v196
	v_fma_f32 v56, v56, s79, v197
	v_fma_f32 v57, v57, s79, v198
	v_fma_f32 v58, v58, s79, v199
	v_fma_f32 v59, v59, s79, v200
	v_fma_f32 v60, v60, s79, v201
	v_fma_f32 v61, v61, s79, v202
	v_fma_f32 v62, v62, s79, v203
	v_fma_f32 v63, v63, s79, v204
	s_waitcnt lgkmcnt(0)
	v_mfma_f32_16x16x32_bf16 v[64:67], v[4:7], v[104:107], 0
	v_mfma_f32_16x16x32_bf16 v[68:71], v[12:15], v[104:107], 0
	v_mfma_f32_16x16x32_bf16 v[72:75], v[20:23], v[104:107], 0
	v_mfma_f32_16x16x32_bf16 v[76:79], v[28:31], v[104:107], 0
	v_mfma_f32_16x16x32_bf16 v[64:67], v[8:11], v[108:111], v[64:67]
	v_mfma_f32_16x16x32_bf16 v[68:71], v[16:19], v[108:111], v[68:71]
	v_mfma_f32_16x16x32_bf16 v[72:75], v[24:27], v[108:111], v[72:75]
	v_mfma_f32_16x16x32_bf16 v[76:79], v[32:35], v[108:111], v[76:79]
	ds_read_b64 v[4:5], v221 offset:0
	ds_read_b64 v[8:9], v221 offset:4096
	ds_read_b64 v[12:13], v221 offset:8192
	ds_read_b64 v[16:17], v221 offset:12288
	ds_read_b64 v[6:7], v222 offset:0
	ds_read_b64 v[10:11], v222 offset:4096
	ds_read_b64 v[14:15], v222 offset:8192
	ds_read_b64 v[18:19], v222 offset:12288
	s_nop 1
	v_fma_f32 v64, v64, s79, v205
	v_fma_f32 v65, v65, s79, v206
	v_fma_f32 v66, v66, s79, v207
	v_fma_f32 v67, v67, s79, v208
	v_fma_f32 v68, v68, s79, v209
	v_fma_f32 v69, v69, s79, v210
	v_fma_f32 v70, v70, s79, v211
	v_fma_f32 v71, v71, s79, v212
	v_fma_f32 v72, v72, s79, v213
	v_fma_f32 v73, v73, s79, v214
	v_fma_f32 v74, v74, s79, v215
	v_fma_f32 v75, v75, s79, v216
	v_fma_f32 v76, v76, s79, v217
	v_fma_f32 v77, v77, s79, v218
	v_fma_f32 v78, v78, s79, v219
	v_fma_f32 v79, v79, s79, v220
	ds_read_b64 v[20:21], v223 offset:0
	ds_read_b64 v[24:25], v223 offset:4096
	ds_read_b64 v[28:29], v223 offset:8192
	ds_read_b64 v[32:33], v223 offset:12288
	ds_read_b64 v[22:23], v224 offset:0
	ds_read_b64 v[26:27], v224 offset:4096
	ds_read_b64 v[30:31], v224 offset:8192
	ds_read_b64 v[34:35], v224 offset:12288
	s_cmp_lg_u32 s4, 0
	s_cbranch_scc1 .Lat844_i3_nomask
	s_cmp_le_u32 s6, 0
	s_cbranch_scc1 .Lat844_i3_nomask
	v_mov_b32_e32 v44, v244
	v_mov_b32_e32 v45, v244
	v_mov_b32_e32 v46, v244
	v_mov_b32_e32 v47, v244
	s_cmp_le_u32 s6, 1
	s_cbranch_scc1 .Lat844_i3_nomask
	v_mov_b32_e32 v48, v244
	v_mov_b32_e32 v49, v244
	v_mov_b32_e32 v50, v244
	v_mov_b32_e32 v51, v244
	s_cmp_le_u32 s6, 2
	s_cbranch_scc1 .Lat844_i3_nomask
	v_mov_b32_e32 v52, v244
	v_mov_b32_e32 v53, v244
	v_mov_b32_e32 v54, v244
	v_mov_b32_e32 v55, v244
	s_cmp_le_u32 s6, 3
	s_cbranch_scc1 .Lat844_i3_nomask
	v_mov_b32_e32 v56, v244
	v_mov_b32_e32 v57, v244
	v_mov_b32_e32 v58, v244
	v_mov_b32_e32 v59, v244
	s_cmp_le_u32 s6, 4
	s_cbranch_scc1 .Lat844_i3_nomask
	v_mov_b32_e32 v60, v244
	v_mov_b32_e32 v61, v244
	v_mov_b32_e32 v62, v244
	v_mov_b32_e32 v63, v244
	s_cmp_le_u32 s6, 5
	s_cbranch_scc1 .Lat844_i3_nomask
	v_mov_b32_e32 v64, v244
	v_mov_b32_e32 v65, v244
	v_mov_b32_e32 v66, v244
	v_mov_b32_e32 v67, v244
	s_cmp_le_u32 s6, 6
	s_cbranch_scc1 .Lat844_i3_nomask
	v_mov_b32_e32 v68, v244
	v_mov_b32_e32 v69, v244
	v_mov_b32_e32 v70, v244
	v_mov_b32_e32 v71, v244
	s_cmp_le_u32 s6, 7
	s_cbranch_scc1 .Lat844_i3_nomask
	v_mov_b32_e32 v72, v244
	v_mov_b32_e32 v73, v244
	v_mov_b32_e32 v74, v244
	v_mov_b32_e32 v75, v244
.Lat844_i3_nomask:
	v_max3_f32 v245, v44, v45, v46
	v_max3_f32 v245, v245, v47, v48
	v_max3_f32 v245, v245, v49, v50
	v_max3_f32 v245, v245, v51, v52
	v_max3_f32 v245, v245, v53, v54
	v_max3_f32 v245, v245, v55, v56
	v_max3_f32 v245, v245, v57, v58
	v_max3_f32 v245, v245, v59, v60
	v_max3_f32 v245, v245, v61, v62
	v_max3_f32 v245, v245, v63, v64
	v_max3_f32 v245, v245, v65, v66
	v_max3_f32 v245, v245, v67, v68
	v_max3_f32 v245, v245, v69, v70
	v_max3_f32 v245, v245, v71, v72
	v_max3_f32 v245, v245, v73, v74
	v_max3_f32 v245, v245, v75, v76
	v_max3_f32 v245, v245, v77, v78
	v_max_f32_e32 v245, v245, v79
	ds_bpermute_b32 v148, v239, v245
	s_waitcnt lgkmcnt(0)
	v_max_f32_e32 v245, v245, v148
	ds_bpermute_b32 v148, v240, v245
	s_waitcnt lgkmcnt(0)
	v_max_f32_e32 v245, v245, v148
	v_sub_f32_e32 v44, v44, v245
	v_sub_f32_e32 v45, v45, v245
	v_sub_f32_e32 v46, v46, v245
	v_sub_f32_e32 v47, v47, v245
	v_exp_f32_e32 v44, v44
	v_exp_f32_e32 v45, v45
	v_exp_f32_e32 v46, v46
	v_exp_f32_e32 v47, v47
	v_sub_f32_e32 v48, v48, v245
	v_sub_f32_e32 v49, v49, v245
	v_sub_f32_e32 v50, v50, v245
	v_sub_f32_e32 v51, v51, v245
	v_exp_f32_e32 v48, v48
	v_exp_f32_e32 v49, v49
	v_exp_f32_e32 v50, v50
	v_exp_f32_e32 v51, v51
	v_mov_b32_e32 v149, v44
	v_mov_b32_e32 v150, v45
	v_mov_b32_e32 v151, v46
	v_mov_b32_e32 v152, v47
	v_cvt_pk_bf16_f32 v44, v44, v45
	v_cvt_pk_bf16_f32 v45, v46, v47
	v_sub_f32_e32 v52, v52, v245
	v_sub_f32_e32 v53, v53, v245
	v_sub_f32_e32 v54, v54, v245
	v_sub_f32_e32 v55, v55, v245
	v_exp_f32_e32 v52, v52
	v_exp_f32_e32 v53, v53
	v_exp_f32_e32 v54, v54
	v_exp_f32_e32 v55, v55
	v_add_f32_e32 v149, v149, v48
	v_add_f32_e32 v150, v150, v49
	v_add_f32_e32 v151, v151, v50
	v_add_f32_e32 v152, v152, v51
	v_cvt_pk_bf16_f32 v46, v48, v49
	v_cvt_pk_bf16_f32 v47, v50, v51
	v_sub_f32_e32 v56, v56, v245
	v_sub_f32_e32 v57, v57, v245
	v_sub_f32_e32 v58, v58, v245
	v_sub_f32_e32 v59, v59, v245
	v_exp_f32_e32 v56, v56
	v_exp_f32_e32 v57, v57
	v_exp_f32_e32 v58, v58
	v_exp_f32_e32 v59, v59
	v_add_f32_e32 v149, v149, v52
	v_add_f32_e32 v150, v150, v53
	v_add_f32_e32 v151, v151, v54
	v_add_f32_e32 v152, v152, v55
	v_cvt_pk_bf16_f32 v52, v52, v53
	v_cvt_pk_bf16_f32 v53, v54, v55
	v_sub_f32_e32 v60, v60, v245
	v_sub_f32_e32 v61, v61, v245
	v_sub_f32_e32 v62, v62, v245
	v_sub_f32_e32 v63, v63, v245
	v_exp_f32_e32 v60, v60
	v_exp_f32_e32 v61, v61
	v_exp_f32_e32 v62, v62
	v_exp_f32_e32 v63, v63
	v_add_f32_e32 v149, v149, v56
	v_add_f32_e32 v150, v150, v57
	v_add_f32_e32 v151, v151, v58
	v_add_f32_e32 v152, v152, v59
	v_cvt_pk_bf16_f32 v54, v56, v57
	v_cvt_pk_bf16_f32 v55, v58, v59
	v_sub_f32_e32 v64, v64, v245
	v_sub_f32_e32 v65, v65, v245
	v_sub_f32_e32 v66, v66, v245
	v_sub_f32_e32 v67, v67, v245
	v_exp_f32_e32 v64, v64
	v_exp_f32_e32 v65, v65
	v_exp_f32_e32 v66, v66
	v_exp_f32_e32 v67, v67
	v_add_f32_e32 v149, v149, v60
	v_add_f32_e32 v150, v150, v61
	v_add_f32_e32 v151, v151, v62
	v_add_f32_e32 v152, v152, v63
	v_cvt_pk_bf16_f32 v60, v60, v61
	v_cvt_pk_bf16_f32 v61, v62, v63
	v_sub_f32_e32 v68, v68, v245
	v_sub_f32_e32 v69, v69, v245
	v_sub_f32_e32 v70, v70, v245
	v_sub_f32_e32 v71, v71, v245
	v_exp_f32_e32 v68, v68
	v_exp_f32_e32 v69, v69
	v_exp_f32_e32 v70, v70
	v_exp_f32_e32 v71, v71
	v_add_f32_e32 v149, v149, v64
	v_add_f32_e32 v150, v150, v65
	v_add_f32_e32 v151, v151, v66
	v_add_f32_e32 v152, v152, v67
	v_cvt_pk_bf16_f32 v62, v64, v65
	v_cvt_pk_bf16_f32 v63, v66, v67
	v_sub_f32_e32 v72, v72, v245
	v_sub_f32_e32 v73, v73, v245
	v_sub_f32_e32 v74, v74, v245
	v_sub_f32_e32 v75, v75, v245
	v_exp_f32_e32 v72, v72
	v_exp_f32_e32 v73, v73
	v_exp_f32_e32 v74, v74
	v_exp_f32_e32 v75, v75
	v_add_f32_e32 v149, v149, v68
	v_add_f32_e32 v150, v150, v69
	v_add_f32_e32 v151, v151, v70
	v_add_f32_e32 v152, v152, v71
	v_cvt_pk_bf16_f32 v68, v68, v69
	v_cvt_pk_bf16_f32 v69, v70, v71
	v_sub_f32_e32 v76, v76, v245
	v_sub_f32_e32 v77, v77, v245
	v_sub_f32_e32 v78, v78, v245
	v_sub_f32_e32 v79, v79, v245
	v_exp_f32_e32 v76, v76
	v_exp_f32_e32 v77, v77
	v_exp_f32_e32 v78, v78
	v_exp_f32_e32 v79, v79
	v_add_f32_e32 v149, v149, v72
	v_add_f32_e32 v150, v150, v73
	v_add_f32_e32 v151, v151, v74
	v_add_f32_e32 v152, v152, v75
	v_cvt_pk_bf16_f32 v70, v72, v73
	v_cvt_pk_bf16_f32 v71, v74, v75
	s_nop 0
	v_add_f32_e32 v149, v149, v76
	v_add_f32_e32 v150, v150, v77
	v_add_f32_e32 v151, v151, v78
	v_add_f32_e32 v152, v152, v79
	v_cvt_pk_bf16_f32 v76, v76, v77
	v_cvt_pk_bf16_f32 v77, v78, v79
	v_mov_b32_e32 v78, 0
	v_mov_b32_e32 v79, 0
	v_add_f32_e32 v149, v149, v150
	v_add_f32_e32 v151, v151, v152
	v_add_f32_e32 v246, v149, v151
	s_waitcnt lgkmcnt(0)
	v_mfma_f32_16x16x32_bf16 v[80:83], v[4:7], v[44:47], 0
	v_mfma_f32_16x16x32_bf16 v[84:87], v[8:11], v[44:47], 0
	v_mfma_f32_16x16x32_bf16 v[88:91], v[12:15], v[44:47], 0
	v_mfma_f32_16x16x32_bf16 v[92:95], v[16:19], v[44:47], 0
	ds_read_b64 v[4:5], v225 offset:0
	ds_read_b64 v[8:9], v225 offset:4096
	ds_read_b64 v[12:13], v225 offset:8192
	ds_read_b64 v[16:17], v225 offset:12288
	ds_read_b64 v[6:7], v226 offset:0
	ds_read_b64 v[10:11], v226 offset:4096
	ds_read_b64 v[14:15], v226 offset:8192
	ds_read_b64 v[18:19], v226 offset:12288
	v_mfma_f32_16x16x32_bf16 v[80:83], v[20:23], v[52:55], v[80:83]
	v_mfma_f32_16x16x32_bf16 v[84:87], v[24:27], v[52:55], v[84:87]
	v_mfma_f32_16x16x32_bf16 v[88:91], v[28:31], v[52:55], v[88:91]
	v_mfma_f32_16x16x32_bf16 v[92:95], v[32:35], v[52:55], v[92:95]
	ds_read_b64 v[20:21], v227 offset:0
	ds_read_b64 v[24:25], v227 offset:4096
	ds_read_b64 v[28:29], v227 offset:8192
	ds_read_b64 v[32:33], v227 offset:12288
	ds_read_b64 v[22:23], v228 offset:0
	ds_read_b64 v[26:27], v228 offset:4096
	ds_read_b64 v[30:31], v228 offset:8192
	ds_read_b64 v[34:35], v228 offset:12288
	ds_bpermute_b32 v148, v239, v246
	s_waitcnt lgkmcnt(9)
	v_mfma_f32_16x16x32_bf16 v[80:83], v[4:7], v[60:63], v[80:83]
	v_mfma_f32_16x16x32_bf16 v[84:87], v[8:11], v[60:63], v[84:87]
	v_mfma_f32_16x16x32_bf16 v[88:91], v[12:15], v[60:63], v[88:91]
	v_mfma_f32_16x16x32_bf16 v[92:95], v[16:19], v[60:63], v[92:95]
	ds_read_b64 v[4:5], v229 offset:0
	ds_read_b64 v[8:9], v229 offset:4096
	ds_read_b64 v[12:13], v229 offset:8192
	ds_read_b64 v[16:17], v229 offset:12288
	v_mov_b32_e32 v6, 0
	v_mov_b32_e32 v7, 0
	v_mov_b32_e32 v10, 0
	v_mov_b32_e32 v11, 0
	v_mov_b32_e32 v14, 0
	v_mov_b32_e32 v15, 0
	v_mov_b32_e32 v18, 0
	v_mov_b32_e32 v19, 0
	s_waitcnt lgkmcnt(5)
	v_mfma_f32_16x16x32_bf16 v[80:83], v[20:23], v[68:71], v[80:83]
	v_mfma_f32_16x16x32_bf16 v[84:87], v[24:27], v[68:71], v[84:87]
	v_mfma_f32_16x16x32_bf16 v[88:91], v[28:31], v[68:71], v[88:91]
	v_mfma_f32_16x16x32_bf16 v[92:95], v[32:35], v[68:71], v[92:95]
	s_waitcnt lgkmcnt(0)
	v_add_f32_e32 v246, v246, v148
	s_nop 0
	v_mfma_f32_16x16x32_bf16 v[80:83], v[4:7], v[76:79], v[80:83]
	v_mfma_f32_16x16x32_bf16 v[84:87], v[8:11], v[76:79], v[84:87]
	v_mfma_f32_16x16x32_bf16 v[88:91], v[12:15], v[76:79], v[88:91]
	v_mfma_f32_16x16x32_bf16 v[92:95], v[16:19], v[76:79], v[92:95]
	ds_bpermute_b32 v148, v240, v246
	s_waitcnt lgkmcnt(0)
	v_add_f32_e32 v246, v246, v148
	v_rcp_f32_e32 v149, v246
	v_log_f32_e32 v150, v246
	s_nop 0
	v_add_f32_e32 v151, v245, v150
	v_mul_f32_e32 v151, 0x3f317218, v151
	v_max_f32_e32 v152, v121, v151
	v_sub_f32_e32 v153, v121, v152
	v_sub_f32_e32 v154, v151, v152
	v_mul_f32_e32 v153, 0x3fb8aa3b, v153
	v_mul_f32_e32 v154, 0x3fb8aa3b, v154
	v_exp_f32_e32 v153, v153
	v_exp_f32_e32 v154, v154
	s_nop 0
	v_add_f32_e32 v155, v153, v154
	v_rcp_f32_e32 v146, v155
	v_log_f32_e32 v150, v155
	s_nop 0
	v_mul_f32_e32 v154, v154, v146
	v_mul_f32_e32 v146, v153, v146
	v_mul_f32_e32 v147, v149, v154
	v_mul_f32_e32 v150, 0x3f317218, v150
	v_add_f32_e32 v140, v152, v150
	v_mul_f32_e32 v80, v80, v147
	v_mul_f32_e32 v81, v81, v147
	v_mul_f32_e32 v82, v82, v147
	v_mul_f32_e32 v83, v83, v147
	v_mul_f32_e32 v84, v84, v147
	v_mul_f32_e32 v85, v85, v147
	v_mul_f32_e32 v86, v86, v147
	v_mul_f32_e32 v87, v87, v147
	v_mul_f32_e32 v88, v88, v147
	v_mul_f32_e32 v89, v89, v147
	v_mul_f32_e32 v90, v90, v147
	v_mul_f32_e32 v91, v91, v147
	v_mul_f32_e32 v92, v92, v147
	v_mul_f32_e32 v93, v93, v147
	v_mul_f32_e32 v94, v94, v147
	v_mul_f32_e32 v95, v95, v147
	v_lshlrev_b32_e32 v141, 16, v122
	v_and_b32_e32 v142, 0xffff0000, v122
	v_lshlrev_b32_e32 v143, 16, v123
	v_and_b32_e32 v144, 0xffff0000, v123
	v_fmac_f32_e32 v80, v146, v141
	v_fmac_f32_e32 v81, v146, v142
	v_fmac_f32_e32 v82, v146, v143
	v_fmac_f32_e32 v83, v146, v144
	v_cvt_pk_bf16_f32 v132, v80, v81
	v_cvt_pk_bf16_f32 v133, v82, v83
	v_lshlrev_b32_e32 v141, 16, v124
	v_and_b32_e32 v142, 0xffff0000, v124
	v_lshlrev_b32_e32 v143, 16, v125
	v_and_b32_e32 v144, 0xffff0000, v125
	v_fmac_f32_e32 v84, v146, v141
	v_fmac_f32_e32 v85, v146, v142
	v_fmac_f32_e32 v86, v146, v143
	v_fmac_f32_e32 v87, v146, v144
	v_cvt_pk_bf16_f32 v134, v84, v85
	v_cvt_pk_bf16_f32 v135, v86, v87
	v_lshlrev_b32_e32 v141, 16, v126
	v_and_b32_e32 v142, 0xffff0000, v126
	v_lshlrev_b32_e32 v143, 16, v127
	v_and_b32_e32 v144, 0xffff0000, v127
	v_fmac_f32_e32 v88, v146, v141
	v_fmac_f32_e32 v89, v146, v142
	v_fmac_f32_e32 v90, v146, v143
	v_fmac_f32_e32 v91, v146, v144
	v_cvt_pk_bf16_f32 v136, v88, v89
	v_cvt_pk_bf16_f32 v137, v90, v91
	v_lshlrev_b32_e32 v141, 16, v128
	v_and_b32_e32 v142, 0xffff0000, v128
	v_lshlrev_b32_e32 v143, 16, v129
	v_and_b32_e32 v144, 0xffff0000, v129
	v_fmac_f32_e32 v92, v146, v141
	v_fmac_f32_e32 v93, v146, v142
	v_fmac_f32_e32 v94, v146, v143
	v_fmac_f32_e32 v95, v146, v144
	v_cvt_pk_bf16_f32 v138, v92, v93
	v_cvt_pk_bf16_f32 v139, v94, v95
	s_mov_b64 s[26:27], s[86:87]
	s_mov_b64 s[28:29], s[88:89]
	s_mov_b64 s[86:87], s[12:13]
	s_mov_b64 s[88:89], s[14:15]
	s_mov_b32 s4, s83
	s_mov_b32 s5, s84
	s_waitcnt vmcnt(0)
	s_barrier
	ds_read_b128 v[4:7], v230 offset:32768
	ds_read_b128 v[8:11], v231 offset:32768
	ds_read_b128 v[12:15], v230 offset:34816
	ds_read_b128 v[16:19], v231 offset:34816
	ds_read_b128 v[20:23], v230 offset:36864
	ds_read_b128 v[24:27], v231 offset:36864
	ds_read_b128 v[28:31], v230 offset:38912
	ds_read_b128 v[32:35], v231 offset:38912
	ds_read_b128 v[36:39], v230 offset:40960
	ds_read_b128 v[40:43], v231 offset:40960
	global_store_dwordx2 v237, v[132:133], s[26:27]
	global_store_dwordx2 v237, v[134:135], s[26:27] offset:32
	global_store_dwordx2 v237, v[136:137], s[26:27] offset:64
	global_store_dwordx2 v237, v[138:139], s[26:27] offset:96
	s_mov_b64 s[90:91], exec
	s_mov_b64 exec, 0xffff
	global_store_dword v238, v140, s[28:29]
	s_mov_b64 exec, s[90:91]
	s_add_u32 s83, s9, 1
	s_mov_b32 s84, 2
	s_mul_i32 s74, s84, 1024
	s_lshl_b32 s75, s83, 7
	s_add_u32 s74, s74, s75
	s_lshl_b32 s75, s74, 7
	s_add_u32 s16, s60, s75
	s_addc_u32 s17, s61, 0
	s_lshl_b32 s75, s74, 1
	s_add_u32 s24, s64, s75
	s_addc_u32 s25, s65, 0
	s_add_u32 m0, s70, 0x0
	s_nop 0
	global_load_lds_dwordx4 v232, s[16:17]
	s_add_u32 m0, s70, 0x2000
	s_nop 0
	global_load_lds_dwordx4 v233, s[16:17]
	s_add_u32 m0, s70, 0x10000
	s_nop 0
	global_load_lds_dwordx4 v234, s[24:25]
	s_add_u32 m0, s70, 0x12000
	s_nop 0
	global_load_lds_dwordx4 v235, s[24:25]
	s_lshl_b32 s74, s83, 9
	s_add_u32 s74, s74, s84
	s_lshl_b32 s75, s74, 7
	s_add_u32 s10, s30, s75
	s_addc_u32 s11, s31, 0
	s_add_u32 s12, s34, s75
	s_addc_u32 s13, s35, 0
	s_lshl_b32 s75, s74, 2
	s_add_u32 s14, s58, s75
	s_addc_u32 s15, s59, 0
	global_load_dwordx4 v[104:107], v236, s[10:11]
	global_load_dwordx4 v[108:111], v236, s[10:11] offset:64
	global_load_dwordx2 v[122:123], v237, s[12:13]
	global_load_dwordx2 v[124:125], v237, s[12:13] offset:32
	global_load_dwordx2 v[126:127], v237, s[12:13] offset:64
	global_load_dwordx2 v[128:129], v237, s[12:13] offset:96
	global_load_dword v121, v238, s[14:15]
	s_waitcnt lgkmcnt(0)
	v_mfma_f32_16x16x32_bf16 v[44:47], v[4:7], v[96:99], 0
	v_mfma_f32_16x16x32_bf16 v[48:51], v[12:15], v[96:99], 0
	v_mfma_f32_16x16x32_bf16 v[52:55], v[20:23], v[96:99], 0
	v_mfma_f32_16x16x32_bf16 v[56:59], v[28:31], v[96:99], 0
	v_mfma_f32_16x16x32_bf16 v[60:63], v[36:39], v[96:99], 0
	v_mfma_f32_16x16x32_bf16 v[44:47], v[8:11], v[100:103], v[44:47]
	v_mfma_f32_16x16x32_bf16 v[48:51], v[16:19], v[100:103], v[48:51]
	v_mfma_f32_16x16x32_bf16 v[52:55], v[24:27], v[100:103], v[52:55]
	v_mfma_f32_16x16x32_bf16 v[56:59], v[32:35], v[100:103], v[56:59]
	v_mfma_f32_16x16x32_bf16 v[60:63], v[40:43], v[100:103], v[60:63]
	ds_read_b128 v[4:7], v230 offset:43008
	ds_read_b128 v[8:11], v231 offset:43008
	ds_read_b128 v[12:15], v230 offset:45056
	ds_read_b128 v[16:19], v231 offset:45056
	ds_read_b128 v[20:23], v230 offset:47104
	ds_read_b128 v[24:27], v231 offset:47104
	ds_read_b128 v[28:31], v230 offset:49152
	ds_read_b128 v[32:35], v231 offset:49152
	s_nop 1
	v_fma_f32 v44, v44, s79, v185
	v_fma_f32 v45, v45, s79, v186
	v_fma_f32 v46, v46, s79, v187
	v_fma_f32 v47, v47, s79, v188
	v_fma_f32 v48, v48, s79, v189
	v_fma_f32 v49, v49, s79, v190
	v_fma_f32 v50, v50, s79, v191
	v_fma_f32 v51, v51, s79, v192
	v_fma_f32 v52, v52, s79, v193
	v_fma_f32 v53, v53, s79, v194
	v_fma_f32 v54, v54, s79, v195
	v_fma_f32 v55, v55, s79, v196
	v_fma_f32 v56, v56, s79, v197
	v_fma_f32 v57, v57, s79, v198
	v_fma_f32 v58, v58, s79, v199
	v_fma_f32 v59, v59, s79, v200
	v_fma_f32 v60, v60, s79, v201
	v_fma_f32 v61, v61, s79, v202
	v_fma_f32 v62, v62, s79, v203
	v_fma_f32 v63, v63, s79, v204
	s_waitcnt lgkmcnt(0)
	v_mfma_f32_16x16x32_bf16 v[64:67], v[4:7], v[96:99], 0
	v_mfma_f32_16x16x32_bf16 v[68:71], v[12:15], v[96:99], 0
	v_mfma_f32_16x16x32_bf16 v[72:75], v[20:23], v[96:99], 0
	v_mfma_f32_16x16x32_bf16 v[76:79], v[28:31], v[96:99], 0
	v_mfma_f32_16x16x32_bf16 v[64:67], v[8:11], v[100:103], v[64:67]
	v_mfma_f32_16x16x32_bf16 v[68:71], v[16:19], v[100:103], v[68:71]
	v_mfma_f32_16x16x32_bf16 v[72:75], v[24:27], v[100:103], v[72:75]
	v_mfma_f32_16x16x32_bf16 v[76:79], v[32:35], v[100:103], v[76:79]
	ds_read_b64 v[4:5], v221 offset:32768
	ds_read_b64 v[8:9], v221 offset:36864
	ds_read_b64 v[12:13], v221 offset:40960
	ds_read_b64 v[16:17], v221 offset:45056
	ds_read_b64 v[6:7], v222 offset:32768
	ds_read_b64 v[10:11], v222 offset:36864
	ds_read_b64 v[14:15], v222 offset:40960
	ds_read_b64 v[18:19], v222 offset:45056
	s_nop 1
	v_fma_f32 v64, v64, s79, v205
	v_fma_f32 v65, v65, s79, v206
	v_fma_f32 v66, v66, s79, v207
	v_fma_f32 v67, v67, s79, v208
	v_fma_f32 v68, v68, s79, v209
	v_fma_f32 v69, v69, s79, v210
	v_fma_f32 v70, v70, s79, v211
	v_fma_f32 v71, v71, s79, v212
	v_fma_f32 v72, v72, s79, v213
	v_fma_f32 v73, v73, s79, v214
	v_fma_f32 v74, v74, s79, v215
	v_fma_f32 v75, v75, s79, v216
	v_fma_f32 v76, v76, s79, v217
	v_fma_f32 v77, v77, s79, v218
	v_fma_f32 v78, v78, s79, v219
	v_fma_f32 v79, v79, s79, v220
	ds_read_b64 v[20:21], v223 offset:32768
	ds_read_b64 v[24:25], v223 offset:36864
	ds_read_b64 v[28:29], v223 offset:40960
	ds_read_b64 v[32:33], v223 offset:45056
	ds_read_b64 v[22:23], v224 offset:32768
	ds_read_b64 v[26:27], v224 offset:36864
	ds_read_b64 v[30:31], v224 offset:40960
	ds_read_b64 v[34:35], v224 offset:45056
	s_cmp_lg_u32 s4, 0
	s_cbranch_scc1 .Lat844_i4_nomask
	s_cmp_le_u32 s6, 0
	s_cbranch_scc1 .Lat844_i4_nomask
	v_mov_b32_e32 v44, v244
	v_mov_b32_e32 v45, v244
	v_mov_b32_e32 v46, v244
	v_mov_b32_e32 v47, v244
	s_cmp_le_u32 s6, 1
	s_cbranch_scc1 .Lat844_i4_nomask
	v_mov_b32_e32 v48, v244
	v_mov_b32_e32 v49, v244
	v_mov_b32_e32 v50, v244
	v_mov_b32_e32 v51, v244
	s_cmp_le_u32 s6, 2
	s_cbranch_scc1 .Lat844_i4_nomask
	v_mov_b32_e32 v52, v244
	v_mov_b32_e32 v53, v244
	v_mov_b32_e32 v54, v244
	v_mov_b32_e32 v55, v244
	s_cmp_le_u32 s6, 3
	s_cbranch_scc1 .Lat844_i4_nomask
	v_mov_b32_e32 v56, v244
	v_mov_b32_e32 v57, v244
	v_mov_b32_e32 v58, v244
	v_mov_b32_e32 v59, v244
	s_cmp_le_u32 s6, 4
	s_cbranch_scc1 .Lat844_i4_nomask
	v_mov_b32_e32 v60, v244
	v_mov_b32_e32 v61, v244
	v_mov_b32_e32 v62, v244
	v_mov_b32_e32 v63, v244
	s_cmp_le_u32 s6, 5
	s_cbranch_scc1 .Lat844_i4_nomask
	v_mov_b32_e32 v64, v244
	v_mov_b32_e32 v65, v244
	v_mov_b32_e32 v66, v244
	v_mov_b32_e32 v67, v244
	s_cmp_le_u32 s6, 6
	s_cbranch_scc1 .Lat844_i4_nomask
	v_mov_b32_e32 v68, v244
	v_mov_b32_e32 v69, v244
	v_mov_b32_e32 v70, v244
	v_mov_b32_e32 v71, v244
	s_cmp_le_u32 s6, 7
	s_cbranch_scc1 .Lat844_i4_nomask
	v_mov_b32_e32 v72, v244
	v_mov_b32_e32 v73, v244
	v_mov_b32_e32 v74, v244
	v_mov_b32_e32 v75, v244
.Lat844_i4_nomask:
	v_max3_f32 v245, v44, v45, v46
	v_max3_f32 v245, v245, v47, v48
	v_max3_f32 v245, v245, v49, v50
	v_max3_f32 v245, v245, v51, v52
	v_max3_f32 v245, v245, v53, v54
	v_max3_f32 v245, v245, v55, v56
	v_max3_f32 v245, v245, v57, v58
	v_max3_f32 v245, v245, v59, v60
	v_max3_f32 v245, v245, v61, v62
	v_max3_f32 v245, v245, v63, v64
	v_max3_f32 v245, v245, v65, v66
	v_max3_f32 v245, v245, v67, v68
	v_max3_f32 v245, v245, v69, v70
	v_max3_f32 v245, v245, v71, v72
	v_max3_f32 v245, v245, v73, v74
	v_max3_f32 v245, v245, v75, v76
	v_max3_f32 v245, v245, v77, v78
	v_max_f32_e32 v245, v245, v79
	ds_bpermute_b32 v148, v239, v245
	s_waitcnt lgkmcnt(0)
	v_max_f32_e32 v245, v245, v148
	ds_bpermute_b32 v148, v240, v245
	s_waitcnt lgkmcnt(0)
	v_max_f32_e32 v245, v245, v148
	v_sub_f32_e32 v44, v44, v245
	v_sub_f32_e32 v45, v45, v245
	v_sub_f32_e32 v46, v46, v245
	v_sub_f32_e32 v47, v47, v245
	v_exp_f32_e32 v44, v44
	v_exp_f32_e32 v45, v45
	v_exp_f32_e32 v46, v46
	v_exp_f32_e32 v47, v47
	v_sub_f32_e32 v48, v48, v245
	v_sub_f32_e32 v49, v49, v245
	v_sub_f32_e32 v50, v50, v245
	v_sub_f32_e32 v51, v51, v245
	v_exp_f32_e32 v48, v48
	v_exp_f32_e32 v49, v49
	v_exp_f32_e32 v50, v50
	v_exp_f32_e32 v51, v51
	v_mov_b32_e32 v149, v44
	v_mov_b32_e32 v150, v45
	v_mov_b32_e32 v151, v46
	v_mov_b32_e32 v152, v47
	v_cvt_pk_bf16_f32 v44, v44, v45
	v_cvt_pk_bf16_f32 v45, v46, v47
	v_sub_f32_e32 v52, v52, v245
	v_sub_f32_e32 v53, v53, v245
	v_sub_f32_e32 v54, v54, v245
	v_sub_f32_e32 v55, v55, v245
	v_exp_f32_e32 v52, v52
	v_exp_f32_e32 v53, v53
	v_exp_f32_e32 v54, v54
	v_exp_f32_e32 v55, v55
	v_add_f32_e32 v149, v149, v48
	v_add_f32_e32 v150, v150, v49
	v_add_f32_e32 v151, v151, v50
	v_add_f32_e32 v152, v152, v51
	v_cvt_pk_bf16_f32 v46, v48, v49
	v_cvt_pk_bf16_f32 v47, v50, v51
	v_sub_f32_e32 v56, v56, v245
	v_sub_f32_e32 v57, v57, v245
	v_sub_f32_e32 v58, v58, v245
	v_sub_f32_e32 v59, v59, v245
	v_exp_f32_e32 v56, v56
	v_exp_f32_e32 v57, v57
	v_exp_f32_e32 v58, v58
	v_exp_f32_e32 v59, v59
	v_add_f32_e32 v149, v149, v52
	v_add_f32_e32 v150, v150, v53
	v_add_f32_e32 v151, v151, v54
	v_add_f32_e32 v152, v152, v55
	v_cvt_pk_bf16_f32 v52, v52, v53
	v_cvt_pk_bf16_f32 v53, v54, v55
	v_sub_f32_e32 v60, v60, v245
	v_sub_f32_e32 v61, v61, v245
	v_sub_f32_e32 v62, v62, v245
	v_sub_f32_e32 v63, v63, v245
	v_exp_f32_e32 v60, v60
	v_exp_f32_e32 v61, v61
	v_exp_f32_e32 v62, v62
	v_exp_f32_e32 v63, v63
	v_add_f32_e32 v149, v149, v56
	v_add_f32_e32 v150, v150, v57
	v_add_f32_e32 v151, v151, v58
	v_add_f32_e32 v152, v152, v59
	v_cvt_pk_bf16_f32 v54, v56, v57
	v_cvt_pk_bf16_f32 v55, v58, v59
	v_sub_f32_e32 v64, v64, v245
	v_sub_f32_e32 v65, v65, v245
	v_sub_f32_e32 v66, v66, v245
	v_sub_f32_e32 v67, v67, v245
	v_exp_f32_e32 v64, v64
	v_exp_f32_e32 v65, v65
	v_exp_f32_e32 v66, v66
	v_exp_f32_e32 v67, v67
	v_add_f32_e32 v149, v149, v60
	v_add_f32_e32 v150, v150, v61
	v_add_f32_e32 v151, v151, v62
	v_add_f32_e32 v152, v152, v63
	v_cvt_pk_bf16_f32 v60, v60, v61
	v_cvt_pk_bf16_f32 v61, v62, v63
	v_sub_f32_e32 v68, v68, v245
	v_sub_f32_e32 v69, v69, v245
	v_sub_f32_e32 v70, v70, v245
	v_sub_f32_e32 v71, v71, v245
	v_exp_f32_e32 v68, v68
	v_exp_f32_e32 v69, v69
	v_exp_f32_e32 v70, v70
	v_exp_f32_e32 v71, v71
	v_add_f32_e32 v149, v149, v64
	v_add_f32_e32 v150, v150, v65
	v_add_f32_e32 v151, v151, v66
	v_add_f32_e32 v152, v152, v67
	v_cvt_pk_bf16_f32 v62, v64, v65
	v_cvt_pk_bf16_f32 v63, v66, v67
	v_sub_f32_e32 v72, v72, v245
	v_sub_f32_e32 v73, v73, v245
	v_sub_f32_e32 v74, v74, v245
	v_sub_f32_e32 v75, v75, v245
	v_exp_f32_e32 v72, v72
	v_exp_f32_e32 v73, v73
	v_exp_f32_e32 v74, v74
	v_exp_f32_e32 v75, v75
	v_add_f32_e32 v149, v149, v68
	v_add_f32_e32 v150, v150, v69
	v_add_f32_e32 v151, v151, v70
	v_add_f32_e32 v152, v152, v71
	v_cvt_pk_bf16_f32 v68, v68, v69
	v_cvt_pk_bf16_f32 v69, v70, v71
	v_sub_f32_e32 v76, v76, v245
	v_sub_f32_e32 v77, v77, v245
	v_sub_f32_e32 v78, v78, v245
	v_sub_f32_e32 v79, v79, v245
	v_exp_f32_e32 v76, v76
	v_exp_f32_e32 v77, v77
	v_exp_f32_e32 v78, v78
	v_exp_f32_e32 v79, v79
	v_add_f32_e32 v149, v149, v72
	v_add_f32_e32 v150, v150, v73
	v_add_f32_e32 v151, v151, v74
	v_add_f32_e32 v152, v152, v75
	v_cvt_pk_bf16_f32 v70, v72, v73
	v_cvt_pk_bf16_f32 v71, v74, v75
	s_nop 0
	v_add_f32_e32 v149, v149, v76
	v_add_f32_e32 v150, v150, v77
	v_add_f32_e32 v151, v151, v78
	v_add_f32_e32 v152, v152, v79
	v_cvt_pk_bf16_f32 v76, v76, v77
	v_cvt_pk_bf16_f32 v77, v78, v79
	v_mov_b32_e32 v78, 0
	v_mov_b32_e32 v79, 0
	v_add_f32_e32 v149, v149, v150
	v_add_f32_e32 v151, v151, v152
	v_add_f32_e32 v246, v149, v151
	s_waitcnt lgkmcnt(0)
	v_mfma_f32_16x16x32_bf16 v[80:83], v[4:7], v[44:47], 0
	v_mfma_f32_16x16x32_bf16 v[84:87], v[8:11], v[44:47], 0
	v_mfma_f32_16x16x32_bf16 v[88:91], v[12:15], v[44:47], 0
	v_mfma_f32_16x16x32_bf16 v[92:95], v[16:19], v[44:47], 0
	ds_read_b64 v[4:5], v225 offset:32768
	ds_read_b64 v[8:9], v225 offset:36864
	ds_read_b64 v[12:13], v225 offset:40960
	ds_read_b64 v[16:17], v225 offset:45056
	ds_read_b64 v[6:7], v226 offset:32768
	ds_read_b64 v[10:11], v226 offset:36864
	ds_read_b64 v[14:15], v226 offset:40960
	ds_read_b64 v[18:19], v226 offset:45056
	v_mfma_f32_16x16x32_bf16 v[80:83], v[20:23], v[52:55], v[80:83]
	v_mfma_f32_16x16x32_bf16 v[84:87], v[24:27], v[52:55], v[84:87]
	v_mfma_f32_16x16x32_bf16 v[88:91], v[28:31], v[52:55], v[88:91]
	v_mfma_f32_16x16x32_bf16 v[92:95], v[32:35], v[52:55], v[92:95]
	ds_read_b64 v[20:21], v227 offset:32768
	ds_read_b64 v[24:25], v227 offset:36864
	ds_read_b64 v[28:29], v227 offset:40960
	ds_read_b64 v[32:33], v227 offset:45056
	ds_read_b64 v[22:23], v228 offset:32768
	ds_read_b64 v[26:27], v228 offset:36864
	ds_read_b64 v[30:31], v228 offset:40960
	ds_read_b64 v[34:35], v228 offset:45056
	ds_bpermute_b32 v148, v239, v246
	s_waitcnt lgkmcnt(9)
	v_mfma_f32_16x16x32_bf16 v[80:83], v[4:7], v[60:63], v[80:83]
	v_mfma_f32_16x16x32_bf16 v[84:87], v[8:11], v[60:63], v[84:87]
	v_mfma_f32_16x16x32_bf16 v[88:91], v[12:15], v[60:63], v[88:91]
	v_mfma_f32_16x16x32_bf16 v[92:95], v[16:19], v[60:63], v[92:95]
	ds_read_b64 v[4:5], v229 offset:32768
	ds_read_b64 v[8:9], v229 offset:36864
	ds_read_b64 v[12:13], v229 offset:40960
	ds_read_b64 v[16:17], v229 offset:45056
	v_mov_b32_e32 v6, 0
	v_mov_b32_e32 v7, 0
	v_mov_b32_e32 v10, 0
	v_mov_b32_e32 v11, 0
	v_mov_b32_e32 v14, 0
	v_mov_b32_e32 v15, 0
	v_mov_b32_e32 v18, 0
	v_mov_b32_e32 v19, 0
	s_waitcnt lgkmcnt(5)
	v_mfma_f32_16x16x32_bf16 v[80:83], v[20:23], v[68:71], v[80:83]
	v_mfma_f32_16x16x32_bf16 v[84:87], v[24:27], v[68:71], v[84:87]
	v_mfma_f32_16x16x32_bf16 v[88:91], v[28:31], v[68:71], v[88:91]
	v_mfma_f32_16x16x32_bf16 v[92:95], v[32:35], v[68:71], v[92:95]
	s_waitcnt lgkmcnt(0)
	v_add_f32_e32 v246, v246, v148
	s_nop 0
	v_mfma_f32_16x16x32_bf16 v[80:83], v[4:7], v[76:79], v[80:83]
	v_mfma_f32_16x16x32_bf16 v[84:87], v[8:11], v[76:79], v[84:87]
	v_mfma_f32_16x16x32_bf16 v[88:91], v[12:15], v[76:79], v[88:91]
	v_mfma_f32_16x16x32_bf16 v[92:95], v[16:19], v[76:79], v[92:95]
	ds_bpermute_b32 v148, v240, v246
	s_waitcnt lgkmcnt(0)
	v_add_f32_e32 v246, v246, v148
	v_rcp_f32_e32 v149, v246
	v_log_f32_e32 v150, v246
	s_nop 0
	v_add_f32_e32 v151, v245, v150
	v_mul_f32_e32 v151, 0x3f317218, v151
	v_max_f32_e32 v152, v120, v151
	v_sub_f32_e32 v153, v120, v152
	v_sub_f32_e32 v154, v151, v152
	v_mul_f32_e32 v153, 0x3fb8aa3b, v153
	v_mul_f32_e32 v154, 0x3fb8aa3b, v154
	v_exp_f32_e32 v153, v153
	v_exp_f32_e32 v154, v154
	s_nop 0
	v_add_f32_e32 v155, v153, v154
	v_rcp_f32_e32 v146, v155
	v_log_f32_e32 v150, v155
	s_nop 0
	v_mul_f32_e32 v154, v154, v146
	v_mul_f32_e32 v146, v153, v146
	v_mul_f32_e32 v147, v149, v154
	v_mul_f32_e32 v150, 0x3f317218, v150
	v_add_f32_e32 v140, v152, v150
	v_mul_f32_e32 v80, v80, v147
	v_mul_f32_e32 v81, v81, v147
	v_mul_f32_e32 v82, v82, v147
	v_mul_f32_e32 v83, v83, v147
	v_mul_f32_e32 v84, v84, v147
	v_mul_f32_e32 v85, v85, v147
	v_mul_f32_e32 v86, v86, v147
	v_mul_f32_e32 v87, v87, v147
	v_mul_f32_e32 v88, v88, v147
	v_mul_f32_e32 v89, v89, v147
	v_mul_f32_e32 v90, v90, v147
	v_mul_f32_e32 v91, v91, v147
	v_mul_f32_e32 v92, v92, v147
	v_mul_f32_e32 v93, v93, v147
	v_mul_f32_e32 v94, v94, v147
	v_mul_f32_e32 v95, v95, v147
	v_lshlrev_b32_e32 v141, 16, v112
	v_and_b32_e32 v142, 0xffff0000, v112
	v_lshlrev_b32_e32 v143, 16, v113
	v_and_b32_e32 v144, 0xffff0000, v113
	v_fmac_f32_e32 v80, v146, v141
	v_fmac_f32_e32 v81, v146, v142
	v_fmac_f32_e32 v82, v146, v143
	v_fmac_f32_e32 v83, v146, v144
	v_cvt_pk_bf16_f32 v132, v80, v81
	v_cvt_pk_bf16_f32 v133, v82, v83
	v_lshlrev_b32_e32 v141, 16, v114
	v_and_b32_e32 v142, 0xffff0000, v114
	v_lshlrev_b32_e32 v143, 16, v115
	v_and_b32_e32 v144, 0xffff0000, v115
	v_fmac_f32_e32 v84, v146, v141
	v_fmac_f32_e32 v85, v146, v142
	v_fmac_f32_e32 v86, v146, v143
	v_fmac_f32_e32 v87, v146, v144
	v_cvt_pk_bf16_f32 v134, v84, v85
	v_cvt_pk_bf16_f32 v135, v86, v87
	v_lshlrev_b32_e32 v141, 16, v116
	v_and_b32_e32 v142, 0xffff0000, v116
	v_lshlrev_b32_e32 v143, 16, v117
	v_and_b32_e32 v144, 0xffff0000, v117
	v_fmac_f32_e32 v88, v146, v141
	v_fmac_f32_e32 v89, v146, v142
	v_fmac_f32_e32 v90, v146, v143
	v_fmac_f32_e32 v91, v146, v144
	v_cvt_pk_bf16_f32 v136, v88, v89
	v_cvt_pk_bf16_f32 v137, v90, v91
	v_lshlrev_b32_e32 v141, 16, v118
	v_and_b32_e32 v142, 0xffff0000, v118
	v_lshlrev_b32_e32 v143, 16, v119
	v_and_b32_e32 v144, 0xffff0000, v119
	v_fmac_f32_e32 v92, v146, v141
	v_fmac_f32_e32 v93, v146, v142
	v_fmac_f32_e32 v94, v146, v143
	v_fmac_f32_e32 v95, v146, v144
	v_cvt_pk_bf16_f32 v138, v92, v93
	v_cvt_pk_bf16_f32 v139, v94, v95
	s_mov_b64 s[26:27], s[86:87]
	s_mov_b64 s[28:29], s[88:89]
	s_mov_b64 s[86:87], s[12:13]
	s_mov_b64 s[88:89], s[14:15]
	s_mov_b32 s4, s83
	s_mov_b32 s5, s84
	s_waitcnt vmcnt(0)
	s_barrier
	s_cmp_gt_u32 s6, 0
	s_cselect_b32 s74, s77, s78
	v_add_u32_e32 v146, s74, v230
	v_xor_b32_e32 v147, 64, v146
	ds_read_b128 v[4:7], v146 offset:0
	ds_read_b128 v[8:11], v147 offset:0
	s_cmp_gt_u32 s6, 1
	s_cselect_b32 s74, s77, s78
	v_add_u32_e32 v146, s74, v230
	v_xor_b32_e32 v147, 64, v146
	ds_read_b128 v[12:15], v146 offset:2048
	ds_read_b128 v[16:19], v147 offset:2048
	s_cmp_gt_u32 s6, 2
	s_cselect_b32 s74, s77, s78
	v_add_u32_e32 v146, s74, v230
	v_xor_b32_e32 v147, 64, v146
	ds_read_b128 v[20:23], v146 offset:4096
	ds_read_b128 v[24:27], v147 offset:4096
	s_cmp_gt_u32 s6, 3
	s_cselect_b32 s74, s77, s78
	v_add_u32_e32 v146, s74, v230
	v_xor_b32_e32 v147, 64, v146
	ds_read_b128 v[28:31], v146 offset:6144
	ds_read_b128 v[32:35], v147 offset:6144
	s_cmp_gt_u32 s6, 4
	s_cselect_b32 s74, s77, s78
	v_add_u32_e32 v146, s74, v230
	v_xor_b32_e32 v147, 64, v146
	ds_read_b128 v[36:39], v146 offset:8192
	ds_read_b128 v[40:43], v147 offset:8192
	global_store_dwordx2 v237, v[132:133], s[26:27]
	global_store_dwordx2 v237, v[134:135], s[26:27] offset:32
	global_store_dwordx2 v237, v[136:137], s[26:27] offset:64
	global_store_dwordx2 v237, v[138:139], s[26:27] offset:96
	s_mov_b64 s[90:91], exec
	s_mov_b64 exec, 0xffff
	global_store_dword v238, v140, s[28:29]
	s_mov_b64 exec, s[90:91]
	s_add_u32 s83, s9, 0
	s_mov_b32 s84, 3
	s_sub_u32 s76, s83, 1
	s_max_i32 s76, s76, 0
	s_mul_i32 s74, s84, 1024
	s_lshl_b32 s75, s76, 7
	s_add_u32 s74, s74, s75
	s_lshl_b32 s75, s74, 7
	s_add_u32 s16, s60, s75
	s_addc_u32 s17, s61, 0
	s_lshl_b32 s75, s74, 1
	s_add_u32 s24, s64, s75
	s_addc_u32 s25, s65, 0
	s_add_u32 m0, s70, 0x4000
	s_nop 0
	global_load_lds_dwordx4 v232, s[16:17]
	s_add_u32 m0, s70, 0x6000
	s_nop 0
	global_load_lds_dwordx4 v233, s[16:17]
	s_add_u32 m0, s70, 0x14000
	s_nop 0
	global_load_lds_dwordx4 v234, s[24:25]
	s_add_u32 m0, s70, 0x16000
	s_nop 0
	global_load_lds_dwordx4 v235, s[24:25]
	s_mul_i32 s74, s84, 1024
	s_lshl_b32 s75, s83, 7
	s_add_u32 s74, s74, s75
	s_lshl_b32 s75, s74, 7
	s_add_u32 s16, s60, s75
	s_addc_u32 s17, s61, 0
	s_lshl_b32 s75, s74, 1
	s_add_u32 s24, s64, s75
	s_addc_u32 s25, s65, 0
	s_add_u32 m0, s70, 0x8000
	s_nop 0
	global_load_lds_dwordx4 v232, s[16:17]
	s_add_u32 m0, s70, 0xa000
	s_nop 0
	global_load_lds_dwordx4 v233, s[16:17]
	s_add_u32 m0, s70, 0x18000
	s_nop 0
	global_load_lds_dwordx4 v234, s[24:25]
	s_add_u32 m0, s70, 0x1a000
	s_nop 0
	global_load_lds_dwordx4 v235, s[24:25]
	s_lshl_b32 s74, s83, 9
	s_add_u32 s74, s74, s84
	s_lshl_b32 s75, s74, 7
	s_add_u32 s10, s30, s75
	s_addc_u32 s11, s31, 0
	s_add_u32 s12, s34, s75
	s_addc_u32 s13, s35, 0
	s_lshl_b32 s75, s74, 2
	s_add_u32 s14, s58, s75
	s_addc_u32 s15, s59, 0
	global_load_dwordx4 v[96:99], v236, s[10:11]
	global_load_dwordx4 v[100:103], v236, s[10:11] offset:64
	global_load_dwordx2 v[112:113], v237, s[12:13]
	global_load_dwordx2 v[114:115], v237, s[12:13] offset:32
	global_load_dwordx2 v[116:117], v237, s[12:13] offset:64
	global_load_dwordx2 v[118:119], v237, s[12:13] offset:96
	global_load_dword v120, v238, s[14:15]
	s_waitcnt lgkmcnt(0)
	v_mfma_f32_16x16x32_bf16 v[44:47], v[4:7], v[104:107], 0
	v_mfma_f32_16x16x32_bf16 v[48:51], v[12:15], v[104:107], 0
	v_mfma_f32_16x16x32_bf16 v[52:55], v[20:23], v[104:107], 0
	v_mfma_f32_16x16x32_bf16 v[56:59], v[28:31], v[104:107], 0
	v_mfma_f32_16x16x32_bf16 v[60:63], v[36:39], v[104:107], 0
	v_mfma_f32_16x16x32_bf16 v[44:47], v[8:11], v[108:111], v[44:47]
	v_mfma_f32_16x16x32_bf16 v[48:51], v[16:19], v[108:111], v[48:51]
	v_mfma_f32_16x16x32_bf16 v[52:55], v[24:27], v[108:111], v[52:55]
	v_mfma_f32_16x16x32_bf16 v[56:59], v[32:35], v[108:111], v[56:59]
	v_mfma_f32_16x16x32_bf16 v[60:63], v[40:43], v[108:111], v[60:63]
	s_cmp_gt_u32 s6, 5
	s_cselect_b32 s74, s77, s78
	v_add_u32_e32 v146, s74, v230
	v_xor_b32_e32 v147, 64, v146
	ds_read_b128 v[4:7], v146 offset:10240
	ds_read_b128 v[8:11], v147 offset:10240
	s_cmp_gt_u32 s6, 6
	s_cselect_b32 s74, s77, s78
	v_add_u32_e32 v146, s74, v230
	v_xor_b32_e32 v147, 64, v146
	ds_read_b128 v[12:15], v146 offset:12288
	ds_read_b128 v[16:19], v147 offset:12288
	s_cmp_gt_u32 s6, 7
	s_cselect_b32 s74, s77, s78
	v_add_u32_e32 v146, s74, v230
	v_xor_b32_e32 v147, 64, v146
	ds_read_b128 v[20:23], v146 offset:14336
	ds_read_b128 v[24:27], v147 offset:14336
	s_cmp_gt_u32 s6, 8
	s_cselect_b32 s74, s77, s78
	v_add_u32_e32 v146, s74, v230
	v_xor_b32_e32 v147, 64, v146
	ds_read_b128 v[28:31], v146 offset:16384
	ds_read_b128 v[32:35], v147 offset:16384
	s_nop 1
	v_fma_f32 v44, v44, s79, v185
	v_fma_f32 v45, v45, s79, v186
	v_fma_f32 v46, v46, s79, v187
	v_fma_f32 v47, v47, s79, v188
	v_fma_f32 v48, v48, s79, v189
	v_fma_f32 v49, v49, s79, v190
	v_fma_f32 v50, v50, s79, v191
	v_fma_f32 v51, v51, s79, v192
	v_fma_f32 v52, v52, s79, v193
	v_fma_f32 v53, v53, s79, v194
	v_fma_f32 v54, v54, s79, v195
	v_fma_f32 v55, v55, s79, v196
	v_fma_f32 v56, v56, s79, v197
	v_fma_f32 v57, v57, s79, v198
	v_fma_f32 v58, v58, s79, v199
	v_fma_f32 v59, v59, s79, v200
	v_fma_f32 v60, v60, s79, v201
	v_fma_f32 v61, v61, s79, v202
	v_fma_f32 v62, v62, s79, v203
	v_fma_f32 v63, v63, s79, v204
	s_waitcnt lgkmcnt(0)
	v_mfma_f32_16x16x32_bf16 v[64:67], v[4:7], v[104:107], 0
	v_mfma_f32_16x16x32_bf16 v[68:71], v[12:15], v[104:107], 0
	v_mfma_f32_16x16x32_bf16 v[72:75], v[20:23], v[104:107], 0
	v_mfma_f32_16x16x32_bf16 v[76:79], v[28:31], v[104:107], 0
	v_mfma_f32_16x16x32_bf16 v[64:67], v[8:11], v[108:111], v[64:67]
	v_mfma_f32_16x16x32_bf16 v[68:71], v[16:19], v[108:111], v[68:71]
	v_mfma_f32_16x16x32_bf16 v[72:75], v[24:27], v[108:111], v[72:75]
	v_mfma_f32_16x16x32_bf16 v[76:79], v[32:35], v[108:111], v[76:79]
	s_cmp_gt_u32 s6, 0
	s_cselect_b32 s74, 0, 0xffff0000
	v_add_u32_e32 v146, s74, v221
	ds_read_b64 v[4:5], v146 offset:49152
	ds_read_b64 v[8:9], v146 offset:53248
	ds_read_b64 v[12:13], v146 offset:57344
	ds_read_b64 v[16:17], v146 offset:61440
	s_cmp_gt_u32 s6, 1
	s_cselect_b32 s74, 0, 0xffff0000
	v_add_u32_e32 v146, s74, v222
	ds_read_b64 v[6:7], v146 offset:49152
	ds_read_b64 v[10:11], v146 offset:53248
	ds_read_b64 v[14:15], v146 offset:57344
	ds_read_b64 v[18:19], v146 offset:61440
	s_nop 1
	v_fma_f32 v64, v64, s79, v205
	v_fma_f32 v65, v65, s79, v206
	v_fma_f32 v66, v66, s79, v207
	v_fma_f32 v67, v67, s79, v208
	v_fma_f32 v68, v68, s79, v209
	v_fma_f32 v69, v69, s79, v210
	v_fma_f32 v70, v70, s79, v211
	v_fma_f32 v71, v71, s79, v212
	v_fma_f32 v72, v72, s79, v213
	v_fma_f32 v73, v73, s79, v214
	v_fma_f32 v74, v74, s79, v215
	v_fma_f32 v75, v75, s79, v216
	v_fma_f32 v76, v76, s79, v217
	v_fma_f32 v77, v77, s79, v218
	v_fma_f32 v78, v78, s79, v219
	v_fma_f32 v79, v79, s79, v220
	s_cmp_gt_u32 s6, 2
	s_cselect_b32 s74, 0, 0xffff0000
	v_add_u32_e32 v146, s74, v223
	ds_read_b64 v[20:21], v146 offset:49152
	ds_read_b64 v[24:25], v146 offset:53248
	ds_read_b64 v[28:29], v146 offset:57344
	ds_read_b64 v[32:33], v146 offset:61440
	s_cmp_gt_u32 s6, 3
	s_cselect_b32 s74, 0, 0xffff0000
	v_add_u32_e32 v146, s74, v224
	ds_read_b64 v[22:23], v146 offset:49152
	ds_read_b64 v[26:27], v146 offset:53248
	ds_read_b64 v[30:31], v146 offset:57344
	ds_read_b64 v[34:35], v146 offset:61440
	s_cmp_lg_u32 s4, 0
	s_cbranch_scc1 .Lat844_i5_nomask
	s_cmp_le_u32 s6, 0
	s_cbranch_scc1 .Lat844_i5_nomask
	v_mov_b32_e32 v44, v244
	v_mov_b32_e32 v45, v244
	v_mov_b32_e32 v46, v244
	v_mov_b32_e32 v47, v244
	s_cmp_le_u32 s6, 1
	s_cbranch_scc1 .Lat844_i5_nomask
	v_mov_b32_e32 v48, v244
	v_mov_b32_e32 v49, v244
	v_mov_b32_e32 v50, v244
	v_mov_b32_e32 v51, v244
	s_cmp_le_u32 s6, 2
	s_cbranch_scc1 .Lat844_i5_nomask
	v_mov_b32_e32 v52, v244
	v_mov_b32_e32 v53, v244
	v_mov_b32_e32 v54, v244
	v_mov_b32_e32 v55, v244
	s_cmp_le_u32 s6, 3
	s_cbranch_scc1 .Lat844_i5_nomask
	v_mov_b32_e32 v56, v244
	v_mov_b32_e32 v57, v244
	v_mov_b32_e32 v58, v244
	v_mov_b32_e32 v59, v244
	s_cmp_le_u32 s6, 4
	s_cbranch_scc1 .Lat844_i5_nomask
	v_mov_b32_e32 v60, v244
	v_mov_b32_e32 v61, v244
	v_mov_b32_e32 v62, v244
	v_mov_b32_e32 v63, v244
	s_cmp_le_u32 s6, 5
	s_cbranch_scc1 .Lat844_i5_nomask
	v_mov_b32_e32 v64, v244
	v_mov_b32_e32 v65, v244
	v_mov_b32_e32 v66, v244
	v_mov_b32_e32 v67, v244
	s_cmp_le_u32 s6, 6
	s_cbranch_scc1 .Lat844_i5_nomask
	v_mov_b32_e32 v68, v244
	v_mov_b32_e32 v69, v244
	v_mov_b32_e32 v70, v244
	v_mov_b32_e32 v71, v244
	s_cmp_le_u32 s6, 7
	s_cbranch_scc1 .Lat844_i5_nomask
	v_mov_b32_e32 v72, v244
	v_mov_b32_e32 v73, v244
	v_mov_b32_e32 v74, v244
	v_mov_b32_e32 v75, v244
.Lat844_i5_nomask:
	v_max3_f32 v245, v44, v45, v46
	v_max3_f32 v245, v245, v47, v48
	v_max3_f32 v245, v245, v49, v50
	v_max3_f32 v245, v245, v51, v52
	v_max3_f32 v245, v245, v53, v54
	v_max3_f32 v245, v245, v55, v56
	v_max3_f32 v245, v245, v57, v58
	v_max3_f32 v245, v245, v59, v60
	v_max3_f32 v245, v245, v61, v62
	v_max3_f32 v245, v245, v63, v64
	v_max3_f32 v245, v245, v65, v66
	v_max3_f32 v245, v245, v67, v68
	v_max3_f32 v245, v245, v69, v70
	v_max3_f32 v245, v245, v71, v72
	v_max3_f32 v245, v245, v73, v74
	v_max3_f32 v245, v245, v75, v76
	v_max3_f32 v245, v245, v77, v78
	v_max_f32_e32 v245, v245, v79
	ds_bpermute_b32 v148, v239, v245
	s_waitcnt lgkmcnt(0)
	v_max_f32_e32 v245, v245, v148
	ds_bpermute_b32 v148, v240, v245
	s_waitcnt lgkmcnt(0)
	v_max_f32_e32 v245, v245, v148
	v_sub_f32_e32 v44, v44, v245
	v_sub_f32_e32 v45, v45, v245
	v_sub_f32_e32 v46, v46, v245
	v_sub_f32_e32 v47, v47, v245
	v_exp_f32_e32 v44, v44
	v_exp_f32_e32 v45, v45
	v_exp_f32_e32 v46, v46
	v_exp_f32_e32 v47, v47
	v_sub_f32_e32 v48, v48, v245
	v_sub_f32_e32 v49, v49, v245
	v_sub_f32_e32 v50, v50, v245
	v_sub_f32_e32 v51, v51, v245
	v_exp_f32_e32 v48, v48
	v_exp_f32_e32 v49, v49
	v_exp_f32_e32 v50, v50
	v_exp_f32_e32 v51, v51
	v_mov_b32_e32 v149, v44
	v_mov_b32_e32 v150, v45
	v_mov_b32_e32 v151, v46
	v_mov_b32_e32 v152, v47
	v_cvt_pk_bf16_f32 v44, v44, v45
	v_cvt_pk_bf16_f32 v45, v46, v47
	v_sub_f32_e32 v52, v52, v245
	v_sub_f32_e32 v53, v53, v245
	v_sub_f32_e32 v54, v54, v245
	v_sub_f32_e32 v55, v55, v245
	v_exp_f32_e32 v52, v52
	v_exp_f32_e32 v53, v53
	v_exp_f32_e32 v54, v54
	v_exp_f32_e32 v55, v55
	v_add_f32_e32 v149, v149, v48
	v_add_f32_e32 v150, v150, v49
	v_add_f32_e32 v151, v151, v50
	v_add_f32_e32 v152, v152, v51
	v_cvt_pk_bf16_f32 v46, v48, v49
	v_cvt_pk_bf16_f32 v47, v50, v51
	v_sub_f32_e32 v56, v56, v245
	v_sub_f32_e32 v57, v57, v245
	v_sub_f32_e32 v58, v58, v245
	v_sub_f32_e32 v59, v59, v245
	v_exp_f32_e32 v56, v56
	v_exp_f32_e32 v57, v57
	v_exp_f32_e32 v58, v58
	v_exp_f32_e32 v59, v59
	v_add_f32_e32 v149, v149, v52
	v_add_f32_e32 v150, v150, v53
	v_add_f32_e32 v151, v151, v54
	v_add_f32_e32 v152, v152, v55
	v_cvt_pk_bf16_f32 v52, v52, v53
	v_cvt_pk_bf16_f32 v53, v54, v55
	v_sub_f32_e32 v60, v60, v245
	v_sub_f32_e32 v61, v61, v245
	v_sub_f32_e32 v62, v62, v245
	v_sub_f32_e32 v63, v63, v245
	v_exp_f32_e32 v60, v60
	v_exp_f32_e32 v61, v61
	v_exp_f32_e32 v62, v62
	v_exp_f32_e32 v63, v63
	v_add_f32_e32 v149, v149, v56
	v_add_f32_e32 v150, v150, v57
	v_add_f32_e32 v151, v151, v58
	v_add_f32_e32 v152, v152, v59
	v_cvt_pk_bf16_f32 v54, v56, v57
	v_cvt_pk_bf16_f32 v55, v58, v59
	v_sub_f32_e32 v64, v64, v245
	v_sub_f32_e32 v65, v65, v245
	v_sub_f32_e32 v66, v66, v245
	v_sub_f32_e32 v67, v67, v245
	v_exp_f32_e32 v64, v64
	v_exp_f32_e32 v65, v65
	v_exp_f32_e32 v66, v66
	v_exp_f32_e32 v67, v67
	v_add_f32_e32 v149, v149, v60
	v_add_f32_e32 v150, v150, v61
	v_add_f32_e32 v151, v151, v62
	v_add_f32_e32 v152, v152, v63
	v_cvt_pk_bf16_f32 v60, v60, v61
	v_cvt_pk_bf16_f32 v61, v62, v63
	v_sub_f32_e32 v68, v68, v245
	v_sub_f32_e32 v69, v69, v245
	v_sub_f32_e32 v70, v70, v245
	v_sub_f32_e32 v71, v71, v245
	v_exp_f32_e32 v68, v68
	v_exp_f32_e32 v69, v69
	v_exp_f32_e32 v70, v70
	v_exp_f32_e32 v71, v71
	v_add_f32_e32 v149, v149, v64
	v_add_f32_e32 v150, v150, v65
	v_add_f32_e32 v151, v151, v66
	v_add_f32_e32 v152, v152, v67
	v_cvt_pk_bf16_f32 v62, v64, v65
	v_cvt_pk_bf16_f32 v63, v66, v67
	v_sub_f32_e32 v72, v72, v245
	v_sub_f32_e32 v73, v73, v245
	v_sub_f32_e32 v74, v74, v245
	v_sub_f32_e32 v75, v75, v245
	v_exp_f32_e32 v72, v72
	v_exp_f32_e32 v73, v73
	v_exp_f32_e32 v74, v74
	v_exp_f32_e32 v75, v75
	v_add_f32_e32 v149, v149, v68
	v_add_f32_e32 v150, v150, v69
	v_add_f32_e32 v151, v151, v70
	v_add_f32_e32 v152, v152, v71
	v_cvt_pk_bf16_f32 v68, v68, v69
	v_cvt_pk_bf16_f32 v69, v70, v71
	v_sub_f32_e32 v76, v76, v245
	v_sub_f32_e32 v77, v77, v245
	v_sub_f32_e32 v78, v78, v245
	v_sub_f32_e32 v79, v79, v245
	v_exp_f32_e32 v76, v76
	v_exp_f32_e32 v77, v77
	v_exp_f32_e32 v78, v78
	v_exp_f32_e32 v79, v79
	v_add_f32_e32 v149, v149, v72
	v_add_f32_e32 v150, v150, v73
	v_add_f32_e32 v151, v151, v74
	v_add_f32_e32 v152, v152, v75
	v_cvt_pk_bf16_f32 v70, v72, v73
	v_cvt_pk_bf16_f32 v71, v74, v75
	s_nop 0
	v_add_f32_e32 v149, v149, v76
	v_add_f32_e32 v150, v150, v77
	v_add_f32_e32 v151, v151, v78
	v_add_f32_e32 v152, v152, v79
	v_cvt_pk_bf16_f32 v76, v76, v77
	v_cvt_pk_bf16_f32 v77, v78, v79
	v_mov_b32_e32 v78, 0
	v_mov_b32_e32 v79, 0
	v_add_f32_e32 v149, v149, v150
	v_add_f32_e32 v151, v151, v152
	v_add_f32_e32 v246, v149, v151
	s_waitcnt lgkmcnt(0)
	v_mfma_f32_16x16x32_bf16 v[80:83], v[4:7], v[44:47], 0
	v_mfma_f32_16x16x32_bf16 v[84:87], v[8:11], v[44:47], 0
	v_mfma_f32_16x16x32_bf16 v[88:91], v[12:15], v[44:47], 0
	v_mfma_f32_16x16x32_bf16 v[92:95], v[16:19], v[44:47], 0
	s_cmp_gt_u32 s6, 4
	s_cselect_b32 s74, 0, 0xffff0000
	v_add_u32_e32 v146, s74, v225
	ds_read_b64 v[4:5], v146 offset:49152
	ds_read_b64 v[8:9], v146 offset:53248
	ds_read_b64 v[12:13], v146 offset:57344
	ds_read_b64 v[16:17], v146 offset:61440
	s_cmp_gt_u32 s6, 5
	s_cselect_b32 s74, 0, 0xffff0000
	v_add_u32_e32 v146, s74, v226
	ds_read_b64 v[6:7], v146 offset:49152
	ds_read_b64 v[10:11], v146 offset:53248
	ds_read_b64 v[14:15], v146 offset:57344
	ds_read_b64 v[18:19], v146 offset:61440
	v_mfma_f32_16x16x32_bf16 v[80:83], v[20:23], v[52:55], v[80:83]
	v_mfma_f32_16x16x32_bf16 v[84:87], v[24:27], v[52:55], v[84:87]
	v_mfma_f32_16x16x32_bf16 v[88:91], v[28:31], v[52:55], v[88:91]
	v_mfma_f32_16x16x32_bf16 v[92:95], v[32:35], v[52:55], v[92:95]
	s_cmp_gt_u32 s6, 6
	s_cselect_b32 s74, 0, 0xffff0000
	v_add_u32_e32 v146, s74, v227
	ds_read_b64 v[20:21], v146 offset:49152
	ds_read_b64 v[24:25], v146 offset:53248
	ds_read_b64 v[28:29], v146 offset:57344
	ds_read_b64 v[32:33], v146 offset:61440
	s_cmp_gt_u32 s6, 7
	s_cselect_b32 s74, 0, 0xffff0000
	v_add_u32_e32 v146, s74, v228
	ds_read_b64 v[22:23], v146 offset:49152
	ds_read_b64 v[26:27], v146 offset:53248
	ds_read_b64 v[30:31], v146 offset:57344
	ds_read_b64 v[34:35], v146 offset:61440
	ds_bpermute_b32 v148, v239, v246
	s_waitcnt lgkmcnt(9)
	v_mfma_f32_16x16x32_bf16 v[80:83], v[4:7], v[60:63], v[80:83]
	v_mfma_f32_16x16x32_bf16 v[84:87], v[8:11], v[60:63], v[84:87]
	v_mfma_f32_16x16x32_bf16 v[88:91], v[12:15], v[60:63], v[88:91]
	v_mfma_f32_16x16x32_bf16 v[92:95], v[16:19], v[60:63], v[92:95]
	s_cmp_gt_u32 s6, 8
	s_cselect_b32 s74, 0, 0xffff0000
	v_add_u32_e32 v146, s74, v229
	ds_read_b64 v[4:5], v146 offset:49152
	ds_read_b64 v[8:9], v146 offset:53248
	ds_read_b64 v[12:13], v146 offset:57344
	ds_read_b64 v[16:17], v146 offset:61440
	v_mov_b32_e32 v6, 0
	v_mov_b32_e32 v7, 0
	v_mov_b32_e32 v10, 0
	v_mov_b32_e32 v11, 0
	v_mov_b32_e32 v14, 0
	v_mov_b32_e32 v15, 0
	v_mov_b32_e32 v18, 0
	v_mov_b32_e32 v19, 0
	s_waitcnt lgkmcnt(5)
	v_mfma_f32_16x16x32_bf16 v[80:83], v[20:23], v[68:71], v[80:83]
	v_mfma_f32_16x16x32_bf16 v[84:87], v[24:27], v[68:71], v[84:87]
	v_mfma_f32_16x16x32_bf16 v[88:91], v[28:31], v[68:71], v[88:91]
	v_mfma_f32_16x16x32_bf16 v[92:95], v[32:35], v[68:71], v[92:95]
	s_waitcnt lgkmcnt(0)
	v_add_f32_e32 v246, v246, v148
	s_nop 0
	v_mfma_f32_16x16x32_bf16 v[80:83], v[4:7], v[76:79], v[80:83]
	v_mfma_f32_16x16x32_bf16 v[84:87], v[8:11], v[76:79], v[84:87]
	v_mfma_f32_16x16x32_bf16 v[88:91], v[12:15], v[76:79], v[88:91]
	v_mfma_f32_16x16x32_bf16 v[92:95], v[16:19], v[76:79], v[92:95]
	ds_bpermute_b32 v148, v240, v246
	s_waitcnt lgkmcnt(0)
	v_add_f32_e32 v246, v246, v148
	v_rcp_f32_e32 v149, v246
	v_log_f32_e32 v150, v246
	s_nop 0
	v_add_f32_e32 v151, v245, v150
	v_mul_f32_e32 v151, 0x3f317218, v151
	v_max_f32_e32 v152, v121, v151
	v_sub_f32_e32 v153, v121, v152
	v_sub_f32_e32 v154, v151, v152
	v_mul_f32_e32 v153, 0x3fb8aa3b, v153
	v_mul_f32_e32 v154, 0x3fb8aa3b, v154
	v_exp_f32_e32 v153, v153
	v_exp_f32_e32 v154, v154
	s_nop 0
	v_add_f32_e32 v155, v153, v154
	v_rcp_f32_e32 v146, v155
	v_log_f32_e32 v150, v155
	s_nop 0
	v_mul_f32_e32 v154, v154, v146
	v_mul_f32_e32 v146, v153, v146
	v_mul_f32_e32 v147, v149, v154
	v_mul_f32_e32 v150, 0x3f317218, v150
	v_add_f32_e32 v140, v152, v150
	v_mul_f32_e32 v80, v80, v147
	v_mul_f32_e32 v81, v81, v147
	v_mul_f32_e32 v82, v82, v147
	v_mul_f32_e32 v83, v83, v147
	v_mul_f32_e32 v84, v84, v147
	v_mul_f32_e32 v85, v85, v147
	v_mul_f32_e32 v86, v86, v147
	v_mul_f32_e32 v87, v87, v147
	v_mul_f32_e32 v88, v88, v147
	v_mul_f32_e32 v89, v89, v147
	v_mul_f32_e32 v90, v90, v147
	v_mul_f32_e32 v91, v91, v147
	v_mul_f32_e32 v92, v92, v147
	v_mul_f32_e32 v93, v93, v147
	v_mul_f32_e32 v94, v94, v147
	v_mul_f32_e32 v95, v95, v147
	v_lshlrev_b32_e32 v141, 16, v122
	v_and_b32_e32 v142, 0xffff0000, v122
	v_lshlrev_b32_e32 v143, 16, v123
	v_and_b32_e32 v144, 0xffff0000, v123
	v_fmac_f32_e32 v80, v146, v141
	v_fmac_f32_e32 v81, v146, v142
	v_fmac_f32_e32 v82, v146, v143
	v_fmac_f32_e32 v83, v146, v144
	v_cvt_pk_bf16_f32 v132, v80, v81
	v_cvt_pk_bf16_f32 v133, v82, v83
	v_lshlrev_b32_e32 v141, 16, v124
	v_and_b32_e32 v142, 0xffff0000, v124
	v_lshlrev_b32_e32 v143, 16, v125
	v_and_b32_e32 v144, 0xffff0000, v125
	v_fmac_f32_e32 v84, v146, v141
	v_fmac_f32_e32 v85, v146, v142
	v_fmac_f32_e32 v86, v146, v143
	v_fmac_f32_e32 v87, v146, v144
	v_cvt_pk_bf16_f32 v134, v84, v85
	v_cvt_pk_bf16_f32 v135, v86, v87
	v_lshlrev_b32_e32 v141, 16, v126
	v_and_b32_e32 v142, 0xffff0000, v126
	v_lshlrev_b32_e32 v143, 16, v127
	v_and_b32_e32 v144, 0xffff0000, v127
	v_fmac_f32_e32 v88, v146, v141
	v_fmac_f32_e32 v89, v146, v142
	v_fmac_f32_e32 v90, v146, v143
	v_fmac_f32_e32 v91, v146, v144
	v_cvt_pk_bf16_f32 v136, v88, v89
	v_cvt_pk_bf16_f32 v137, v90, v91
	v_lshlrev_b32_e32 v141, 16, v128
	v_and_b32_e32 v142, 0xffff0000, v128
	v_lshlrev_b32_e32 v143, 16, v129
	v_and_b32_e32 v144, 0xffff0000, v129
	v_fmac_f32_e32 v92, v146, v141
	v_fmac_f32_e32 v93, v146, v142
	v_fmac_f32_e32 v94, v146, v143
	v_fmac_f32_e32 v95, v146, v144
	v_cvt_pk_bf16_f32 v138, v92, v93
	v_cvt_pk_bf16_f32 v139, v94, v95
	s_mov_b64 s[26:27], s[86:87]
	s_mov_b64 s[28:29], s[88:89]
	s_mov_b64 s[86:87], s[12:13]
	s_mov_b64 s[88:89], s[14:15]
	s_mov_b32 s4, s83
	s_mov_b32 s5, s84
	s_waitcnt vmcnt(0)
	s_barrier
	ds_read_b128 v[4:7], v230 offset:16384
	ds_read_b128 v[8:11], v231 offset:16384
	ds_read_b128 v[12:15], v230 offset:18432
	ds_read_b128 v[16:19], v231 offset:18432
	ds_read_b128 v[20:23], v230 offset:20480
	ds_read_b128 v[24:27], v231 offset:20480
	ds_read_b128 v[28:31], v230 offset:22528
	ds_read_b128 v[32:35], v231 offset:22528
	ds_read_b128 v[36:39], v230 offset:24576
	ds_read_b128 v[40:43], v231 offset:24576
	global_store_dwordx2 v237, v[132:133], s[26:27]
	global_store_dwordx2 v237, v[134:135], s[26:27] offset:32
	global_store_dwordx2 v237, v[136:137], s[26:27] offset:64
	global_store_dwordx2 v237, v[138:139], s[26:27] offset:96
	s_mov_b64 s[90:91], exec
	s_mov_b64 exec, 0xffff
	global_store_dword v238, v140, s[28:29]
	s_mov_b64 exec, s[90:91]
	s_add_u32 s83, s9, 1
	s_mov_b32 s84, 3
	s_mul_i32 s74, s84, 1024
	s_lshl_b32 s75, s83, 7
	s_add_u32 s74, s74, s75
	s_lshl_b32 s75, s74, 7
	s_add_u32 s16, s60, s75
	s_addc_u32 s17, s61, 0
	s_lshl_b32 s75, s74, 1
	s_add_u32 s24, s64, s75
	s_addc_u32 s25, s65, 0
	s_add_u32 m0, s70, 0xc000
	s_nop 0
	global_load_lds_dwordx4 v232, s[16:17]
	s_add_u32 m0, s70, 0xe000
	s_nop 0
	global_load_lds_dwordx4 v233, s[16:17]
	s_add_u32 m0, s70, 0x1c000
	s_nop 0
	global_load_lds_dwordx4 v234, s[24:25]
	s_add_u32 m0, s70, 0x1e000
	s_nop 0
	global_load_lds_dwordx4 v235, s[24:25]
	s_lshl_b32 s74, s83, 9
	s_add_u32 s74, s74, s84
	s_lshl_b32 s75, s74, 7
	s_add_u32 s10, s30, s75
	s_addc_u32 s11, s31, 0
	s_add_u32 s12, s34, s75
	s_addc_u32 s13, s35, 0
	s_lshl_b32 s75, s74, 2
	s_add_u32 s14, s58, s75
	s_addc_u32 s15, s59, 0
	global_load_dwordx4 v[104:107], v236, s[10:11]
	global_load_dwordx4 v[108:111], v236, s[10:11] offset:64
	global_load_dwordx2 v[122:123], v237, s[12:13]
	global_load_dwordx2 v[124:125], v237, s[12:13] offset:32
	global_load_dwordx2 v[126:127], v237, s[12:13] offset:64
	global_load_dwordx2 v[128:129], v237, s[12:13] offset:96
	global_load_dword v121, v238, s[14:15]
	s_waitcnt lgkmcnt(0)
	v_mfma_f32_16x16x32_bf16 v[44:47], v[4:7], v[96:99], 0
	v_mfma_f32_16x16x32_bf16 v[48:51], v[12:15], v[96:99], 0
	v_mfma_f32_16x16x32_bf16 v[52:55], v[20:23], v[96:99], 0
	v_mfma_f32_16x16x32_bf16 v[56:59], v[28:31], v[96:99], 0
	v_mfma_f32_16x16x32_bf16 v[60:63], v[36:39], v[96:99], 0
	v_mfma_f32_16x16x32_bf16 v[44:47], v[8:11], v[100:103], v[44:47]
	v_mfma_f32_16x16x32_bf16 v[48:51], v[16:19], v[100:103], v[48:51]
	v_mfma_f32_16x16x32_bf16 v[52:55], v[24:27], v[100:103], v[52:55]
	v_mfma_f32_16x16x32_bf16 v[56:59], v[32:35], v[100:103], v[56:59]
	v_mfma_f32_16x16x32_bf16 v[60:63], v[40:43], v[100:103], v[60:63]
	ds_read_b128 v[4:7], v230 offset:26624
	ds_read_b128 v[8:11], v231 offset:26624
	ds_read_b128 v[12:15], v230 offset:28672
	ds_read_b128 v[16:19], v231 offset:28672
	ds_read_b128 v[20:23], v230 offset:30720
	ds_read_b128 v[24:27], v231 offset:30720
	ds_read_b128 v[28:31], v230 offset:32768
	ds_read_b128 v[32:35], v231 offset:32768
	s_nop 1
	v_fma_f32 v44, v44, s79, v185
	v_fma_f32 v45, v45, s79, v186
	v_fma_f32 v46, v46, s79, v187
	v_fma_f32 v47, v47, s79, v188
	v_fma_f32 v48, v48, s79, v189
	v_fma_f32 v49, v49, s79, v190
	v_fma_f32 v50, v50, s79, v191
	v_fma_f32 v51, v51, s79, v192
	v_fma_f32 v52, v52, s79, v193
	v_fma_f32 v53, v53, s79, v194
	v_fma_f32 v54, v54, s79, v195
	v_fma_f32 v55, v55, s79, v196
	v_fma_f32 v56, v56, s79, v197
	v_fma_f32 v57, v57, s79, v198
	v_fma_f32 v58, v58, s79, v199
	v_fma_f32 v59, v59, s79, v200
	v_fma_f32 v60, v60, s79, v201
	v_fma_f32 v61, v61, s79, v202
	v_fma_f32 v62, v62, s79, v203
	v_fma_f32 v63, v63, s79, v204
	s_waitcnt lgkmcnt(0)
	v_mfma_f32_16x16x32_bf16 v[64:67], v[4:7], v[96:99], 0
	v_mfma_f32_16x16x32_bf16 v[68:71], v[12:15], v[96:99], 0
	v_mfma_f32_16x16x32_bf16 v[72:75], v[20:23], v[96:99], 0
	v_mfma_f32_16x16x32_bf16 v[76:79], v[28:31], v[96:99], 0
	v_mfma_f32_16x16x32_bf16 v[64:67], v[8:11], v[100:103], v[64:67]
	v_mfma_f32_16x16x32_bf16 v[68:71], v[16:19], v[100:103], v[68:71]
	v_mfma_f32_16x16x32_bf16 v[72:75], v[24:27], v[100:103], v[72:75]
	v_mfma_f32_16x16x32_bf16 v[76:79], v[32:35], v[100:103], v[76:79]
	ds_read_b64 v[4:5], v221 offset:16384
	ds_read_b64 v[8:9], v221 offset:20480
	ds_read_b64 v[12:13], v221 offset:24576
	ds_read_b64 v[16:17], v221 offset:28672
	ds_read_b64 v[6:7], v222 offset:16384
	ds_read_b64 v[10:11], v222 offset:20480
	ds_read_b64 v[14:15], v222 offset:24576
	ds_read_b64 v[18:19], v222 offset:28672
	s_nop 1
	v_fma_f32 v64, v64, s79, v205
	v_fma_f32 v65, v65, s79, v206
	v_fma_f32 v66, v66, s79, v207
	v_fma_f32 v67, v67, s79, v208
	v_fma_f32 v68, v68, s79, v209
	v_fma_f32 v69, v69, s79, v210
	v_fma_f32 v70, v70, s79, v211
	v_fma_f32 v71, v71, s79, v212
	v_fma_f32 v72, v72, s79, v213
	v_fma_f32 v73, v73, s79, v214
	v_fma_f32 v74, v74, s79, v215
	v_fma_f32 v75, v75, s79, v216
	v_fma_f32 v76, v76, s79, v217
	v_fma_f32 v77, v77, s79, v218
	v_fma_f32 v78, v78, s79, v219
	v_fma_f32 v79, v79, s79, v220
	ds_read_b64 v[20:21], v223 offset:16384
	ds_read_b64 v[24:25], v223 offset:20480
	ds_read_b64 v[28:29], v223 offset:24576
	ds_read_b64 v[32:33], v223 offset:28672
	ds_read_b64 v[22:23], v224 offset:16384
	ds_read_b64 v[26:27], v224 offset:20480
	ds_read_b64 v[30:31], v224 offset:24576
	ds_read_b64 v[34:35], v224 offset:28672
	s_cmp_lg_u32 s4, 0
	s_cbranch_scc1 .Lat844_i6_nomask
	s_cmp_le_u32 s6, 0
	s_cbranch_scc1 .Lat844_i6_nomask
	v_mov_b32_e32 v44, v244
	v_mov_b32_e32 v45, v244
	v_mov_b32_e32 v46, v244
	v_mov_b32_e32 v47, v244
	s_cmp_le_u32 s6, 1
	s_cbranch_scc1 .Lat844_i6_nomask
	v_mov_b32_e32 v48, v244
	v_mov_b32_e32 v49, v244
	v_mov_b32_e32 v50, v244
	v_mov_b32_e32 v51, v244
	s_cmp_le_u32 s6, 2
	s_cbranch_scc1 .Lat844_i6_nomask
	v_mov_b32_e32 v52, v244
	v_mov_b32_e32 v53, v244
	v_mov_b32_e32 v54, v244
	v_mov_b32_e32 v55, v244
	s_cmp_le_u32 s6, 3
	s_cbranch_scc1 .Lat844_i6_nomask
	v_mov_b32_e32 v56, v244
	v_mov_b32_e32 v57, v244
	v_mov_b32_e32 v58, v244
	v_mov_b32_e32 v59, v244
	s_cmp_le_u32 s6, 4
	s_cbranch_scc1 .Lat844_i6_nomask
	v_mov_b32_e32 v60, v244
	v_mov_b32_e32 v61, v244
	v_mov_b32_e32 v62, v244
	v_mov_b32_e32 v63, v244
	s_cmp_le_u32 s6, 5
	s_cbranch_scc1 .Lat844_i6_nomask
	v_mov_b32_e32 v64, v244
	v_mov_b32_e32 v65, v244
	v_mov_b32_e32 v66, v244
	v_mov_b32_e32 v67, v244
	s_cmp_le_u32 s6, 6
	s_cbranch_scc1 .Lat844_i6_nomask
	v_mov_b32_e32 v68, v244
	v_mov_b32_e32 v69, v244
	v_mov_b32_e32 v70, v244
	v_mov_b32_e32 v71, v244
	s_cmp_le_u32 s6, 7
	s_cbranch_scc1 .Lat844_i6_nomask
	v_mov_b32_e32 v72, v244
	v_mov_b32_e32 v73, v244
	v_mov_b32_e32 v74, v244
	v_mov_b32_e32 v75, v244
.Lat844_i6_nomask:
	v_max3_f32 v245, v44, v45, v46
	v_max3_f32 v245, v245, v47, v48
	v_max3_f32 v245, v245, v49, v50
	v_max3_f32 v245, v245, v51, v52
	v_max3_f32 v245, v245, v53, v54
	v_max3_f32 v245, v245, v55, v56
	v_max3_f32 v245, v245, v57, v58
	v_max3_f32 v245, v245, v59, v60
	v_max3_f32 v245, v245, v61, v62
	v_max3_f32 v245, v245, v63, v64
	v_max3_f32 v245, v245, v65, v66
	v_max3_f32 v245, v245, v67, v68
	v_max3_f32 v245, v245, v69, v70
	v_max3_f32 v245, v245, v71, v72
	v_max3_f32 v245, v245, v73, v74
	v_max3_f32 v245, v245, v75, v76
	v_max3_f32 v245, v245, v77, v78
	v_max_f32_e32 v245, v245, v79
	ds_bpermute_b32 v148, v239, v245
	s_waitcnt lgkmcnt(0)
	v_max_f32_e32 v245, v245, v148
	ds_bpermute_b32 v148, v240, v245
	s_waitcnt lgkmcnt(0)
	v_max_f32_e32 v245, v245, v148
	v_sub_f32_e32 v44, v44, v245
	v_sub_f32_e32 v45, v45, v245
	v_sub_f32_e32 v46, v46, v245
	v_sub_f32_e32 v47, v47, v245
	v_exp_f32_e32 v44, v44
	v_exp_f32_e32 v45, v45
	v_exp_f32_e32 v46, v46
	v_exp_f32_e32 v47, v47
	v_sub_f32_e32 v48, v48, v245
	v_sub_f32_e32 v49, v49, v245
	v_sub_f32_e32 v50, v50, v245
	v_sub_f32_e32 v51, v51, v245
	v_exp_f32_e32 v48, v48
	v_exp_f32_e32 v49, v49
	v_exp_f32_e32 v50, v50
	v_exp_f32_e32 v51, v51
	v_mov_b32_e32 v149, v44
	v_mov_b32_e32 v150, v45
	v_mov_b32_e32 v151, v46
	v_mov_b32_e32 v152, v47
	v_cvt_pk_bf16_f32 v44, v44, v45
	v_cvt_pk_bf16_f32 v45, v46, v47
	v_sub_f32_e32 v52, v52, v245
	v_sub_f32_e32 v53, v53, v245
	v_sub_f32_e32 v54, v54, v245
	v_sub_f32_e32 v55, v55, v245
	v_exp_f32_e32 v52, v52
	v_exp_f32_e32 v53, v53
	v_exp_f32_e32 v54, v54
	v_exp_f32_e32 v55, v55
	v_add_f32_e32 v149, v149, v48
	v_add_f32_e32 v150, v150, v49
	v_add_f32_e32 v151, v151, v50
	v_add_f32_e32 v152, v152, v51
	v_cvt_pk_bf16_f32 v46, v48, v49
	v_cvt_pk_bf16_f32 v47, v50, v51
	v_sub_f32_e32 v56, v56, v245
	v_sub_f32_e32 v57, v57, v245
	v_sub_f32_e32 v58, v58, v245
	v_sub_f32_e32 v59, v59, v245
	v_exp_f32_e32 v56, v56
	v_exp_f32_e32 v57, v57
	v_exp_f32_e32 v58, v58
	v_exp_f32_e32 v59, v59
	v_add_f32_e32 v149, v149, v52
	v_add_f32_e32 v150, v150, v53
	v_add_f32_e32 v151, v151, v54
	v_add_f32_e32 v152, v152, v55
	v_cvt_pk_bf16_f32 v52, v52, v53
	v_cvt_pk_bf16_f32 v53, v54, v55
	v_sub_f32_e32 v60, v60, v245
	v_sub_f32_e32 v61, v61, v245
	v_sub_f32_e32 v62, v62, v245
	v_sub_f32_e32 v63, v63, v245
	v_exp_f32_e32 v60, v60
	v_exp_f32_e32 v61, v61
	v_exp_f32_e32 v62, v62
	v_exp_f32_e32 v63, v63
	v_add_f32_e32 v149, v149, v56
	v_add_f32_e32 v150, v150, v57
	v_add_f32_e32 v151, v151, v58
	v_add_f32_e32 v152, v152, v59
	v_cvt_pk_bf16_f32 v54, v56, v57
	v_cvt_pk_bf16_f32 v55, v58, v59
	v_sub_f32_e32 v64, v64, v245
	v_sub_f32_e32 v65, v65, v245
	v_sub_f32_e32 v66, v66, v245
	v_sub_f32_e32 v67, v67, v245
	v_exp_f32_e32 v64, v64
	v_exp_f32_e32 v65, v65
	v_exp_f32_e32 v66, v66
	v_exp_f32_e32 v67, v67
	v_add_f32_e32 v149, v149, v60
	v_add_f32_e32 v150, v150, v61
	v_add_f32_e32 v151, v151, v62
	v_add_f32_e32 v152, v152, v63
	v_cvt_pk_bf16_f32 v60, v60, v61
	v_cvt_pk_bf16_f32 v61, v62, v63
	v_sub_f32_e32 v68, v68, v245
	v_sub_f32_e32 v69, v69, v245
	v_sub_f32_e32 v70, v70, v245
	v_sub_f32_e32 v71, v71, v245
	v_exp_f32_e32 v68, v68
	v_exp_f32_e32 v69, v69
	v_exp_f32_e32 v70, v70
	v_exp_f32_e32 v71, v71
	v_add_f32_e32 v149, v149, v64
	v_add_f32_e32 v150, v150, v65
	v_add_f32_e32 v151, v151, v66
	v_add_f32_e32 v152, v152, v67
	v_cvt_pk_bf16_f32 v62, v64, v65
	v_cvt_pk_bf16_f32 v63, v66, v67
	v_sub_f32_e32 v72, v72, v245
	v_sub_f32_e32 v73, v73, v245
	v_sub_f32_e32 v74, v74, v245
	v_sub_f32_e32 v75, v75, v245
	v_exp_f32_e32 v72, v72
	v_exp_f32_e32 v73, v73
	v_exp_f32_e32 v74, v74
	v_exp_f32_e32 v75, v75
	v_add_f32_e32 v149, v149, v68
	v_add_f32_e32 v150, v150, v69
	v_add_f32_e32 v151, v151, v70
	v_add_f32_e32 v152, v152, v71
	v_cvt_pk_bf16_f32 v68, v68, v69
	v_cvt_pk_bf16_f32 v69, v70, v71
	v_sub_f32_e32 v76, v76, v245
	v_sub_f32_e32 v77, v77, v245
	v_sub_f32_e32 v78, v78, v245
	v_sub_f32_e32 v79, v79, v245
	v_exp_f32_e32 v76, v76
	v_exp_f32_e32 v77, v77
	v_exp_f32_e32 v78, v78
	v_exp_f32_e32 v79, v79
	v_add_f32_e32 v149, v149, v72
	v_add_f32_e32 v150, v150, v73
	v_add_f32_e32 v151, v151, v74
	v_add_f32_e32 v152, v152, v75
	v_cvt_pk_bf16_f32 v70, v72, v73
	v_cvt_pk_bf16_f32 v71, v74, v75
	s_nop 0
	v_add_f32_e32 v149, v149, v76
	v_add_f32_e32 v150, v150, v77
	v_add_f32_e32 v151, v151, v78
	v_add_f32_e32 v152, v152, v79
	v_cvt_pk_bf16_f32 v76, v76, v77
	v_cvt_pk_bf16_f32 v77, v78, v79
	v_mov_b32_e32 v78, 0
	v_mov_b32_e32 v79, 0
	v_add_f32_e32 v149, v149, v150
	v_add_f32_e32 v151, v151, v152
	v_add_f32_e32 v246, v149, v151
	s_waitcnt lgkmcnt(0)
	v_mfma_f32_16x16x32_bf16 v[80:83], v[4:7], v[44:47], 0
	v_mfma_f32_16x16x32_bf16 v[84:87], v[8:11], v[44:47], 0
	v_mfma_f32_16x16x32_bf16 v[88:91], v[12:15], v[44:47], 0
	v_mfma_f32_16x16x32_bf16 v[92:95], v[16:19], v[44:47], 0
	ds_read_b64 v[4:5], v225 offset:16384
	ds_read_b64 v[8:9], v225 offset:20480
	ds_read_b64 v[12:13], v225 offset:24576
	ds_read_b64 v[16:17], v225 offset:28672
	ds_read_b64 v[6:7], v226 offset:16384
	ds_read_b64 v[10:11], v226 offset:20480
	ds_read_b64 v[14:15], v226 offset:24576
	ds_read_b64 v[18:19], v226 offset:28672
	v_mfma_f32_16x16x32_bf16 v[80:83], v[20:23], v[52:55], v[80:83]
	v_mfma_f32_16x16x32_bf16 v[84:87], v[24:27], v[52:55], v[84:87]
	v_mfma_f32_16x16x32_bf16 v[88:91], v[28:31], v[52:55], v[88:91]
	v_mfma_f32_16x16x32_bf16 v[92:95], v[32:35], v[52:55], v[92:95]
	ds_read_b64 v[20:21], v227 offset:16384
	ds_read_b64 v[24:25], v227 offset:20480
	ds_read_b64 v[28:29], v227 offset:24576
	ds_read_b64 v[32:33], v227 offset:28672
	ds_read_b64 v[22:23], v228 offset:16384
	ds_read_b64 v[26:27], v228 offset:20480
	ds_read_b64 v[30:31], v228 offset:24576
	ds_read_b64 v[34:35], v228 offset:28672
	ds_bpermute_b32 v148, v239, v246
	s_waitcnt lgkmcnt(9)
	v_mfma_f32_16x16x32_bf16 v[80:83], v[4:7], v[60:63], v[80:83]
	v_mfma_f32_16x16x32_bf16 v[84:87], v[8:11], v[60:63], v[84:87]
	v_mfma_f32_16x16x32_bf16 v[88:91], v[12:15], v[60:63], v[88:91]
	v_mfma_f32_16x16x32_bf16 v[92:95], v[16:19], v[60:63], v[92:95]
	ds_read_b64 v[4:5], v229 offset:16384
	ds_read_b64 v[8:9], v229 offset:20480
	ds_read_b64 v[12:13], v229 offset:24576
	ds_read_b64 v[16:17], v229 offset:28672
	v_mov_b32_e32 v6, 0
	v_mov_b32_e32 v7, 0
	v_mov_b32_e32 v10, 0
	v_mov_b32_e32 v11, 0
	v_mov_b32_e32 v14, 0
	v_mov_b32_e32 v15, 0
	v_mov_b32_e32 v18, 0
	v_mov_b32_e32 v19, 0
	s_waitcnt lgkmcnt(5)
	v_mfma_f32_16x16x32_bf16 v[80:83], v[20:23], v[68:71], v[80:83]
	v_mfma_f32_16x16x32_bf16 v[84:87], v[24:27], v[68:71], v[84:87]
	v_mfma_f32_16x16x32_bf16 v[88:91], v[28:31], v[68:71], v[88:91]
	v_mfma_f32_16x16x32_bf16 v[92:95], v[32:35], v[68:71], v[92:95]
	s_waitcnt lgkmcnt(0)
	v_add_f32_e32 v246, v246, v148
	s_nop 0
	v_mfma_f32_16x16x32_bf16 v[80:83], v[4:7], v[76:79], v[80:83]
	v_mfma_f32_16x16x32_bf16 v[84:87], v[8:11], v[76:79], v[84:87]
	v_mfma_f32_16x16x32_bf16 v[88:91], v[12:15], v[76:79], v[88:91]
	v_mfma_f32_16x16x32_bf16 v[92:95], v[16:19], v[76:79], v[92:95]
	ds_bpermute_b32 v148, v240, v246
	s_waitcnt lgkmcnt(0)
	v_add_f32_e32 v246, v246, v148
	v_rcp_f32_e32 v149, v246
	v_log_f32_e32 v150, v246
	s_nop 0
	v_add_f32_e32 v151, v245, v150
	v_mul_f32_e32 v151, 0x3f317218, v151
	v_max_f32_e32 v152, v120, v151
	v_sub_f32_e32 v153, v120, v152
	v_sub_f32_e32 v154, v151, v152
	v_mul_f32_e32 v153, 0x3fb8aa3b, v153
	v_mul_f32_e32 v154, 0x3fb8aa3b, v154
	v_exp_f32_e32 v153, v153
	v_exp_f32_e32 v154, v154
	s_nop 0
	v_add_f32_e32 v155, v153, v154
	v_rcp_f32_e32 v146, v155
	v_log_f32_e32 v150, v155
	s_nop 0
	v_mul_f32_e32 v154, v154, v146
	v_mul_f32_e32 v146, v153, v146
	v_mul_f32_e32 v147, v149, v154
	v_mul_f32_e32 v150, 0x3f317218, v150
	v_add_f32_e32 v140, v152, v150
	v_mul_f32_e32 v80, v80, v147
	v_mul_f32_e32 v81, v81, v147
	v_mul_f32_e32 v82, v82, v147
	v_mul_f32_e32 v83, v83, v147
	v_mul_f32_e32 v84, v84, v147
	v_mul_f32_e32 v85, v85, v147
	v_mul_f32_e32 v86, v86, v147
	v_mul_f32_e32 v87, v87, v147
	v_mul_f32_e32 v88, v88, v147
	v_mul_f32_e32 v89, v89, v147
	v_mul_f32_e32 v90, v90, v147
	v_mul_f32_e32 v91, v91, v147
	v_mul_f32_e32 v92, v92, v147
	v_mul_f32_e32 v93, v93, v147
	v_mul_f32_e32 v94, v94, v147
	v_mul_f32_e32 v95, v95, v147
	v_lshlrev_b32_e32 v141, 16, v112
	v_and_b32_e32 v142, 0xffff0000, v112
	v_lshlrev_b32_e32 v143, 16, v113
	v_and_b32_e32 v144, 0xffff0000, v113
	v_fmac_f32_e32 v80, v146, v141
	v_fmac_f32_e32 v81, v146, v142
	v_fmac_f32_e32 v82, v146, v143
	v_fmac_f32_e32 v83, v146, v144
	v_cvt_pk_bf16_f32 v132, v80, v81
	v_cvt_pk_bf16_f32 v133, v82, v83
	v_lshlrev_b32_e32 v141, 16, v114
	v_and_b32_e32 v142, 0xffff0000, v114
	v_lshlrev_b32_e32 v143, 16, v115
	v_and_b32_e32 v144, 0xffff0000, v115
	v_fmac_f32_e32 v84, v146, v141
	v_fmac_f32_e32 v85, v146, v142
	v_fmac_f32_e32 v86, v146, v143
	v_fmac_f32_e32 v87, v146, v144
	v_cvt_pk_bf16_f32 v134, v84, v85
	v_cvt_pk_bf16_f32 v135, v86, v87
	v_lshlrev_b32_e32 v141, 16, v116
	v_and_b32_e32 v142, 0xffff0000, v116
	v_lshlrev_b32_e32 v143, 16, v117
	v_and_b32_e32 v144, 0xffff0000, v117
	v_fmac_f32_e32 v88, v146, v141
	v_fmac_f32_e32 v89, v146, v142
	v_fmac_f32_e32 v90, v146, v143
	v_fmac_f32_e32 v91, v146, v144
	v_cvt_pk_bf16_f32 v136, v88, v89
	v_cvt_pk_bf16_f32 v137, v90, v91
	v_lshlrev_b32_e32 v141, 16, v118
	v_and_b32_e32 v142, 0xffff0000, v118
	v_lshlrev_b32_e32 v143, 16, v119
	v_and_b32_e32 v144, 0xffff0000, v119
	v_fmac_f32_e32 v92, v146, v141
	v_fmac_f32_e32 v93, v146, v142
	v_fmac_f32_e32 v94, v146, v143
	v_fmac_f32_e32 v95, v146, v144
	v_cvt_pk_bf16_f32 v138, v92, v93
	v_cvt_pk_bf16_f32 v139, v94, v95
	s_mov_b64 s[26:27], s[86:87]
	s_mov_b64 s[28:29], s[88:89]
	s_mov_b64 s[86:87], s[12:13]
	s_mov_b64 s[88:89], s[14:15]
	s_mov_b32 s4, s83
	s_mov_b32 s5, s84
	s_waitcnt vmcnt(0)
	s_barrier
	ds_read_b128 v[4:7], v230 offset:32768
	ds_read_b128 v[8:11], v231 offset:32768
	ds_read_b128 v[12:15], v230 offset:34816
	ds_read_b128 v[16:19], v231 offset:34816
	ds_read_b128 v[20:23], v230 offset:36864
	ds_read_b128 v[24:27], v231 offset:36864
	ds_read_b128 v[28:31], v230 offset:38912
	ds_read_b128 v[32:35], v231 offset:38912
	ds_read_b128 v[36:39], v230 offset:40960
	ds_read_b128 v[40:43], v231 offset:40960
	global_store_dwordx2 v237, v[132:133], s[26:27]
	global_store_dwordx2 v237, v[134:135], s[26:27] offset:32
	global_store_dwordx2 v237, v[136:137], s[26:27] offset:64
	global_store_dwordx2 v237, v[138:139], s[26:27] offset:96
	s_mov_b64 s[90:91], exec
	s_mov_b64 exec, 0xffff
	global_store_dword v238, v140, s[28:29]
	s_mov_b64 exec, s[90:91]
	s_waitcnt lgkmcnt(0)
	v_mfma_f32_16x16x32_bf16 v[44:47], v[4:7], v[104:107], 0
	v_mfma_f32_16x16x32_bf16 v[48:51], v[12:15], v[104:107], 0
	v_mfma_f32_16x16x32_bf16 v[52:55], v[20:23], v[104:107], 0
	v_mfma_f32_16x16x32_bf16 v[56:59], v[28:31], v[104:107], 0
	v_mfma_f32_16x16x32_bf16 v[60:63], v[36:39], v[104:107], 0
	v_mfma_f32_16x16x32_bf16 v[44:47], v[8:11], v[108:111], v[44:47]
	v_mfma_f32_16x16x32_bf16 v[48:51], v[16:19], v[108:111], v[48:51]
	v_mfma_f32_16x16x32_bf16 v[52:55], v[24:27], v[108:111], v[52:55]
	v_mfma_f32_16x16x32_bf16 v[56:59], v[32:35], v[108:111], v[56:59]
	v_mfma_f32_16x16x32_bf16 v[60:63], v[40:43], v[108:111], v[60:63]
	ds_read_b128 v[4:7], v230 offset:43008
	ds_read_b128 v[8:11], v231 offset:43008
	ds_read_b128 v[12:15], v230 offset:45056
	ds_read_b128 v[16:19], v231 offset:45056
	ds_read_b128 v[20:23], v230 offset:47104
	ds_read_b128 v[24:27], v231 offset:47104
	ds_read_b128 v[28:31], v230 offset:49152
	ds_read_b128 v[32:35], v231 offset:49152
	s_nop 1
	v_fma_f32 v44, v44, s79, v185
	v_fma_f32 v45, v45, s79, v186
	v_fma_f32 v46, v46, s79, v187
	v_fma_f32 v47, v47, s79, v188
	v_fma_f32 v48, v48, s79, v189
	v_fma_f32 v49, v49, s79, v190
	v_fma_f32 v50, v50, s79, v191
	v_fma_f32 v51, v51, s79, v192
	v_fma_f32 v52, v52, s79, v193
	v_fma_f32 v53, v53, s79, v194
	v_fma_f32 v54, v54, s79, v195
	v_fma_f32 v55, v55, s79, v196
	v_fma_f32 v56, v56, s79, v197
	v_fma_f32 v57, v57, s79, v198
	v_fma_f32 v58, v58, s79, v199
	v_fma_f32 v59, v59, s79, v200
	v_fma_f32 v60, v60, s79, v201
	v_fma_f32 v61, v61, s79, v202
	v_fma_f32 v62, v62, s79, v203
	v_fma_f32 v63, v63, s79, v204
	s_waitcnt lgkmcnt(0)
	v_mfma_f32_16x16x32_bf16 v[64:67], v[4:7], v[104:107], 0
	v_mfma_f32_16x16x32_bf16 v[68:71], v[12:15], v[104:107], 0
	v_mfma_f32_16x16x32_bf16 v[72:75], v[20:23], v[104:107], 0
	v_mfma_f32_16x16x32_bf16 v[76:79], v[28:31], v[104:107], 0
	v_mfma_f32_16x16x32_bf16 v[64:67], v[8:11], v[108:111], v[64:67]
	v_mfma_f32_16x16x32_bf16 v[68:71], v[16:19], v[108:111], v[68:71]
	v_mfma_f32_16x16x32_bf16 v[72:75], v[24:27], v[108:111], v[72:75]
	v_mfma_f32_16x16x32_bf16 v[76:79], v[32:35], v[108:111], v[76:79]
	ds_read_b64 v[4:5], v221 offset:32768
	ds_read_b64 v[8:9], v221 offset:36864
	ds_read_b64 v[12:13], v221 offset:40960
	ds_read_b64 v[16:17], v221 offset:45056
	ds_read_b64 v[6:7], v222 offset:32768
	ds_read_b64 v[10:11], v222 offset:36864
	ds_read_b64 v[14:15], v222 offset:40960
	ds_read_b64 v[18:19], v222 offset:45056
	s_nop 1
	v_fma_f32 v64, v64, s79, v205
	v_fma_f32 v65, v65, s79, v206
	v_fma_f32 v66, v66, s79, v207
	v_fma_f32 v67, v67, s79, v208
	v_fma_f32 v68, v68, s79, v209
	v_fma_f32 v69, v69, s79, v210
	v_fma_f32 v70, v70, s79, v211
	v_fma_f32 v71, v71, s79, v212
	v_fma_f32 v72, v72, s79, v213
	v_fma_f32 v73, v73, s79, v214
	v_fma_f32 v74, v74, s79, v215
	v_fma_f32 v75, v75, s79, v216
	v_fma_f32 v76, v76, s79, v217
	v_fma_f32 v77, v77, s79, v218
	v_fma_f32 v78, v78, s79, v219
	v_fma_f32 v79, v79, s79, v220
	ds_read_b64 v[20:21], v223 offset:32768
	ds_read_b64 v[24:25], v223 offset:36864
	ds_read_b64 v[28:29], v223 offset:40960
	ds_read_b64 v[32:33], v223 offset:45056
	ds_read_b64 v[22:23], v224 offset:32768
	ds_read_b64 v[26:27], v224 offset:36864
	ds_read_b64 v[30:31], v224 offset:40960
	ds_read_b64 v[34:35], v224 offset:45056
	s_cmp_lg_u32 s4, 0
	s_cbranch_scc1 .Lat844_i7_nomask
	s_cmp_le_u32 s6, 0
	s_cbranch_scc1 .Lat844_i7_nomask
	v_mov_b32_e32 v44, v244
	v_mov_b32_e32 v45, v244
	v_mov_b32_e32 v46, v244
	v_mov_b32_e32 v47, v244
	s_cmp_le_u32 s6, 1
	s_cbranch_scc1 .Lat844_i7_nomask
	v_mov_b32_e32 v48, v244
	v_mov_b32_e32 v49, v244
	v_mov_b32_e32 v50, v244
	v_mov_b32_e32 v51, v244
	s_cmp_le_u32 s6, 2
	s_cbranch_scc1 .Lat844_i7_nomask
	v_mov_b32_e32 v52, v244
	v_mov_b32_e32 v53, v244
	v_mov_b32_e32 v54, v244
	v_mov_b32_e32 v55, v244
	s_cmp_le_u32 s6, 3
	s_cbranch_scc1 .Lat844_i7_nomask
	v_mov_b32_e32 v56, v244
	v_mov_b32_e32 v57, v244
	v_mov_b32_e32 v58, v244
	v_mov_b32_e32 v59, v244
	s_cmp_le_u32 s6, 4
	s_cbranch_scc1 .Lat844_i7_nomask
	v_mov_b32_e32 v60, v244
	v_mov_b32_e32 v61, v244
	v_mov_b32_e32 v62, v244
	v_mov_b32_e32 v63, v244
	s_cmp_le_u32 s6, 5
	s_cbranch_scc1 .Lat844_i7_nomask
	v_mov_b32_e32 v64, v244
	v_mov_b32_e32 v65, v244
	v_mov_b32_e32 v66, v244
	v_mov_b32_e32 v67, v244
	s_cmp_le_u32 s6, 6
	s_cbranch_scc1 .Lat844_i7_nomask
	v_mov_b32_e32 v68, v244
	v_mov_b32_e32 v69, v244
	v_mov_b32_e32 v70, v244
	v_mov_b32_e32 v71, v244
	s_cmp_le_u32 s6, 7
	s_cbranch_scc1 .Lat844_i7_nomask
	v_mov_b32_e32 v72, v244
	v_mov_b32_e32 v73, v244
	v_mov_b32_e32 v74, v244
	v_mov_b32_e32 v75, v244
.Lat844_i7_nomask:
	v_max3_f32 v245, v44, v45, v46
	v_max3_f32 v245, v245, v47, v48
	v_max3_f32 v245, v245, v49, v50
	v_max3_f32 v245, v245, v51, v52
	v_max3_f32 v245, v245, v53, v54
	v_max3_f32 v245, v245, v55, v56
	v_max3_f32 v245, v245, v57, v58
	v_max3_f32 v245, v245, v59, v60
	v_max3_f32 v245, v245, v61, v62
	v_max3_f32 v245, v245, v63, v64
	v_max3_f32 v245, v245, v65, v66
	v_max3_f32 v245, v245, v67, v68
	v_max3_f32 v245, v245, v69, v70
	v_max3_f32 v245, v245, v71, v72
	v_max3_f32 v245, v245, v73, v74
	v_max3_f32 v245, v245, v75, v76
	v_max3_f32 v245, v245, v77, v78
	v_max_f32_e32 v245, v245, v79
	ds_bpermute_b32 v148, v239, v245
	s_waitcnt lgkmcnt(0)
	v_max_f32_e32 v245, v245, v148
	ds_bpermute_b32 v148, v240, v245
	s_waitcnt lgkmcnt(0)
	v_max_f32_e32 v245, v245, v148
	v_sub_f32_e32 v44, v44, v245
	v_sub_f32_e32 v45, v45, v245
	v_sub_f32_e32 v46, v46, v245
	v_sub_f32_e32 v47, v47, v245
	v_exp_f32_e32 v44, v44
	v_exp_f32_e32 v45, v45
	v_exp_f32_e32 v46, v46
	v_exp_f32_e32 v47, v47
	v_sub_f32_e32 v48, v48, v245
	v_sub_f32_e32 v49, v49, v245
	v_sub_f32_e32 v50, v50, v245
	v_sub_f32_e32 v51, v51, v245
	v_exp_f32_e32 v48, v48
	v_exp_f32_e32 v49, v49
	v_exp_f32_e32 v50, v50
	v_exp_f32_e32 v51, v51
	v_mov_b32_e32 v149, v44
	v_mov_b32_e32 v150, v45
	v_mov_b32_e32 v151, v46
	v_mov_b32_e32 v152, v47
	v_cvt_pk_bf16_f32 v44, v44, v45
	v_cvt_pk_bf16_f32 v45, v46, v47
	v_sub_f32_e32 v52, v52, v245
	v_sub_f32_e32 v53, v53, v245
	v_sub_f32_e32 v54, v54, v245
	v_sub_f32_e32 v55, v55, v245
	v_exp_f32_e32 v52, v52
	v_exp_f32_e32 v53, v53
	v_exp_f32_e32 v54, v54
	v_exp_f32_e32 v55, v55
	v_add_f32_e32 v149, v149, v48
	v_add_f32_e32 v150, v150, v49
	v_add_f32_e32 v151, v151, v50
	v_add_f32_e32 v152, v152, v51
	v_cvt_pk_bf16_f32 v46, v48, v49
	v_cvt_pk_bf16_f32 v47, v50, v51
	v_sub_f32_e32 v56, v56, v245
	v_sub_f32_e32 v57, v57, v245
	v_sub_f32_e32 v58, v58, v245
	v_sub_f32_e32 v59, v59, v245
	v_exp_f32_e32 v56, v56
	v_exp_f32_e32 v57, v57
	v_exp_f32_e32 v58, v58
	v_exp_f32_e32 v59, v59
	v_add_f32_e32 v149, v149, v52
	v_add_f32_e32 v150, v150, v53
	v_add_f32_e32 v151, v151, v54
	v_add_f32_e32 v152, v152, v55
	v_cvt_pk_bf16_f32 v52, v52, v53
	v_cvt_pk_bf16_f32 v53, v54, v55
	v_sub_f32_e32 v60, v60, v245
	v_sub_f32_e32 v61, v61, v245
	v_sub_f32_e32 v62, v62, v245
	v_sub_f32_e32 v63, v63, v245
	v_exp_f32_e32 v60, v60
	v_exp_f32_e32 v61, v61
	v_exp_f32_e32 v62, v62
	v_exp_f32_e32 v63, v63
	v_add_f32_e32 v149, v149, v56
	v_add_f32_e32 v150, v150, v57
	v_add_f32_e32 v151, v151, v58
	v_add_f32_e32 v152, v152, v59
	v_cvt_pk_bf16_f32 v54, v56, v57
	v_cvt_pk_bf16_f32 v55, v58, v59
	v_sub_f32_e32 v64, v64, v245
	v_sub_f32_e32 v65, v65, v245
	v_sub_f32_e32 v66, v66, v245
	v_sub_f32_e32 v67, v67, v245
	v_exp_f32_e32 v64, v64
	v_exp_f32_e32 v65, v65
	v_exp_f32_e32 v66, v66
	v_exp_f32_e32 v67, v67
	v_add_f32_e32 v149, v149, v60
	v_add_f32_e32 v150, v150, v61
	v_add_f32_e32 v151, v151, v62
	v_add_f32_e32 v152, v152, v63
	v_cvt_pk_bf16_f32 v60, v60, v61
	v_cvt_pk_bf16_f32 v61, v62, v63
	v_sub_f32_e32 v68, v68, v245
	v_sub_f32_e32 v69, v69, v245
	v_sub_f32_e32 v70, v70, v245
	v_sub_f32_e32 v71, v71, v245
	v_exp_f32_e32 v68, v68
	v_exp_f32_e32 v69, v69
	v_exp_f32_e32 v70, v70
	v_exp_f32_e32 v71, v71
	v_add_f32_e32 v149, v149, v64
	v_add_f32_e32 v150, v150, v65
	v_add_f32_e32 v151, v151, v66
	v_add_f32_e32 v152, v152, v67
	v_cvt_pk_bf16_f32 v62, v64, v65
	v_cvt_pk_bf16_f32 v63, v66, v67
	v_sub_f32_e32 v72, v72, v245
	v_sub_f32_e32 v73, v73, v245
	v_sub_f32_e32 v74, v74, v245
	v_sub_f32_e32 v75, v75, v245
	v_exp_f32_e32 v72, v72
	v_exp_f32_e32 v73, v73
	v_exp_f32_e32 v74, v74
	v_exp_f32_e32 v75, v75
	v_add_f32_e32 v149, v149, v68
	v_add_f32_e32 v150, v150, v69
	v_add_f32_e32 v151, v151, v70
	v_add_f32_e32 v152, v152, v71
	v_cvt_pk_bf16_f32 v68, v68, v69
	v_cvt_pk_bf16_f32 v69, v70, v71
	v_sub_f32_e32 v76, v76, v245
	v_sub_f32_e32 v77, v77, v245
	v_sub_f32_e32 v78, v78, v245
	v_sub_f32_e32 v79, v79, v245
	v_exp_f32_e32 v76, v76
	v_exp_f32_e32 v77, v77
	v_exp_f32_e32 v78, v78
	v_exp_f32_e32 v79, v79
	v_add_f32_e32 v149, v149, v72
	v_add_f32_e32 v150, v150, v73
	v_add_f32_e32 v151, v151, v74
	v_add_f32_e32 v152, v152, v75
	v_cvt_pk_bf16_f32 v70, v72, v73
	v_cvt_pk_bf16_f32 v71, v74, v75
	s_nop 0
	v_add_f32_e32 v149, v149, v76
	v_add_f32_e32 v150, v150, v77
	v_add_f32_e32 v151, v151, v78
	v_add_f32_e32 v152, v152, v79
	v_cvt_pk_bf16_f32 v76, v76, v77
	v_cvt_pk_bf16_f32 v77, v78, v79
	v_mov_b32_e32 v78, 0
	v_mov_b32_e32 v79, 0
	v_add_f32_e32 v149, v149, v150
	v_add_f32_e32 v151, v151, v152
	v_add_f32_e32 v246, v149, v151
	s_waitcnt lgkmcnt(0)
	v_mfma_f32_16x16x32_bf16 v[80:83], v[4:7], v[44:47], 0
	v_mfma_f32_16x16x32_bf16 v[84:87], v[8:11], v[44:47], 0
	v_mfma_f32_16x16x32_bf16 v[88:91], v[12:15], v[44:47], 0
	v_mfma_f32_16x16x32_bf16 v[92:95], v[16:19], v[44:47], 0
	ds_read_b64 v[4:5], v225 offset:32768
	ds_read_b64 v[8:9], v225 offset:36864
	ds_read_b64 v[12:13], v225 offset:40960
	ds_read_b64 v[16:17], v225 offset:45056
	ds_read_b64 v[6:7], v226 offset:32768
	ds_read_b64 v[10:11], v226 offset:36864
	ds_read_b64 v[14:15], v226 offset:40960
	ds_read_b64 v[18:19], v226 offset:45056
	v_mfma_f32_16x16x32_bf16 v[80:83], v[20:23], v[52:55], v[80:83]
	v_mfma_f32_16x16x32_bf16 v[84:87], v[24:27], v[52:55], v[84:87]
	v_mfma_f32_16x16x32_bf16 v[88:91], v[28:31], v[52:55], v[88:91]
	v_mfma_f32_16x16x32_bf16 v[92:95], v[32:35], v[52:55], v[92:95]
	ds_read_b64 v[20:21], v227 offset:32768
	ds_read_b64 v[24:25], v227 offset:36864
	ds_read_b64 v[28:29], v227 offset:40960
	ds_read_b64 v[32:33], v227 offset:45056
	ds_read_b64 v[22:23], v228 offset:32768
	ds_read_b64 v[26:27], v228 offset:36864
	ds_read_b64 v[30:31], v228 offset:40960
	ds_read_b64 v[34:35], v228 offset:45056
	ds_bpermute_b32 v148, v239, v246
	s_waitcnt lgkmcnt(9)
	v_mfma_f32_16x16x32_bf16 v[80:83], v[4:7], v[60:63], v[80:83]
	v_mfma_f32_16x16x32_bf16 v[84:87], v[8:11], v[60:63], v[84:87]
	v_mfma_f32_16x16x32_bf16 v[88:91], v[12:15], v[60:63], v[88:91]
	v_mfma_f32_16x16x32_bf16 v[92:95], v[16:19], v[60:63], v[92:95]
	ds_read_b64 v[4:5], v229 offset:32768
	ds_read_b64 v[8:9], v229 offset:36864
	ds_read_b64 v[12:13], v229 offset:40960
	ds_read_b64 v[16:17], v229 offset:45056
	v_mov_b32_e32 v6, 0
	v_mov_b32_e32 v7, 0
	v_mov_b32_e32 v10, 0
	v_mov_b32_e32 v11, 0
	v_mov_b32_e32 v14, 0
	v_mov_b32_e32 v15, 0
	v_mov_b32_e32 v18, 0
	v_mov_b32_e32 v19, 0
	s_waitcnt lgkmcnt(5)
	v_mfma_f32_16x16x32_bf16 v[80:83], v[20:23], v[68:71], v[80:83]
	v_mfma_f32_16x16x32_bf16 v[84:87], v[24:27], v[68:71], v[84:87]
	v_mfma_f32_16x16x32_bf16 v[88:91], v[28:31], v[68:71], v[88:91]
	v_mfma_f32_16x16x32_bf16 v[92:95], v[32:35], v[68:71], v[92:95]
	s_waitcnt lgkmcnt(0)
	v_add_f32_e32 v246, v246, v148
	s_nop 0
	v_mfma_f32_16x16x32_bf16 v[80:83], v[4:7], v[76:79], v[80:83]
	v_mfma_f32_16x16x32_bf16 v[84:87], v[8:11], v[76:79], v[84:87]
	v_mfma_f32_16x16x32_bf16 v[88:91], v[12:15], v[76:79], v[88:91]
	v_mfma_f32_16x16x32_bf16 v[92:95], v[16:19], v[76:79], v[92:95]
	ds_bpermute_b32 v148, v240, v246
	s_waitcnt lgkmcnt(0)
	v_add_f32_e32 v246, v246, v148
	v_rcp_f32_e32 v149, v246
	v_log_f32_e32 v150, v246
	s_nop 0
	v_add_f32_e32 v151, v245, v150
	v_mul_f32_e32 v151, 0x3f317218, v151
	v_max_f32_e32 v152, v121, v151
	v_sub_f32_e32 v153, v121, v152
	v_sub_f32_e32 v154, v151, v152
	v_mul_f32_e32 v153, 0x3fb8aa3b, v153
	v_mul_f32_e32 v154, 0x3fb8aa3b, v154
	v_exp_f32_e32 v153, v153
	v_exp_f32_e32 v154, v154
	s_nop 0
	v_add_f32_e32 v155, v153, v154
	v_rcp_f32_e32 v146, v155
	v_log_f32_e32 v150, v155
	s_nop 0
	v_mul_f32_e32 v154, v154, v146
	v_mul_f32_e32 v146, v153, v146
	v_mul_f32_e32 v147, v149, v154
	v_mul_f32_e32 v150, 0x3f317218, v150
	v_add_f32_e32 v140, v152, v150
	v_mul_f32_e32 v80, v80, v147
	v_mul_f32_e32 v81, v81, v147
	v_mul_f32_e32 v82, v82, v147
	v_mul_f32_e32 v83, v83, v147
	v_mul_f32_e32 v84, v84, v147
	v_mul_f32_e32 v85, v85, v147
	v_mul_f32_e32 v86, v86, v147
	v_mul_f32_e32 v87, v87, v147
	v_mul_f32_e32 v88, v88, v147
	v_mul_f32_e32 v89, v89, v147
	v_mul_f32_e32 v90, v90, v147
	v_mul_f32_e32 v91, v91, v147
	v_mul_f32_e32 v92, v92, v147
	v_mul_f32_e32 v93, v93, v147
	v_mul_f32_e32 v94, v94, v147
	v_mul_f32_e32 v95, v95, v147
	v_lshlrev_b32_e32 v141, 16, v122
	v_and_b32_e32 v142, 0xffff0000, v122
	v_lshlrev_b32_e32 v143, 16, v123
	v_and_b32_e32 v144, 0xffff0000, v123
	v_fmac_f32_e32 v80, v146, v141
	v_fmac_f32_e32 v81, v146, v142
	v_fmac_f32_e32 v82, v146, v143
	v_fmac_f32_e32 v83, v146, v144
	v_cvt_pk_bf16_f32 v132, v80, v81
	v_cvt_pk_bf16_f32 v133, v82, v83
	v_lshlrev_b32_e32 v141, 16, v124
	v_and_b32_e32 v142, 0xffff0000, v124
	v_lshlrev_b32_e32 v143, 16, v125
	v_and_b32_e32 v144, 0xffff0000, v125
	v_fmac_f32_e32 v84, v146, v141
	v_fmac_f32_e32 v85, v146, v142
	v_fmac_f32_e32 v86, v146, v143
	v_fmac_f32_e32 v87, v146, v144
	v_cvt_pk_bf16_f32 v134, v84, v85
	v_cvt_pk_bf16_f32 v135, v86, v87
	v_lshlrev_b32_e32 v141, 16, v126
	v_and_b32_e32 v142, 0xffff0000, v126
	v_lshlrev_b32_e32 v143, 16, v127
	v_and_b32_e32 v144, 0xffff0000, v127
	v_fmac_f32_e32 v88, v146, v141
	v_fmac_f32_e32 v89, v146, v142
	v_fmac_f32_e32 v90, v146, v143
	v_fmac_f32_e32 v91, v146, v144
	v_cvt_pk_bf16_f32 v136, v88, v89
	v_cvt_pk_bf16_f32 v137, v90, v91
	v_lshlrev_b32_e32 v141, 16, v128
	v_and_b32_e32 v142, 0xffff0000, v128
	v_lshlrev_b32_e32 v143, 16, v129
	v_and_b32_e32 v144, 0xffff0000, v129
	v_fmac_f32_e32 v92, v146, v141
	v_fmac_f32_e32 v93, v146, v142
	v_fmac_f32_e32 v94, v146, v143
	v_fmac_f32_e32 v95, v146, v144
	v_cvt_pk_bf16_f32 v138, v92, v93
	v_cvt_pk_bf16_f32 v139, v94, v95
	s_mov_b64 s[26:27], s[86:87]
	s_mov_b64 s[28:29], s[88:89]
	s_mov_b64 s[86:87], s[12:13]
	s_mov_b64 s[88:89], s[14:15]
	s_mov_b32 s4, s83
	s_mov_b32 s5, s84
	s_setprio 0
	global_store_dwordx2 v237, v[132:133], s[26:27]
	global_store_dwordx2 v237, v[134:135], s[26:27] offset:32
	global_store_dwordx2 v237, v[136:137], s[26:27] offset:64
	global_store_dwordx2 v237, v[138:139], s[26:27] offset:96
	s_mov_b64 s[90:91], exec
	s_mov_b64 exec, 0xffff
	global_store_dword v238, v140, s[28:29]
	s_mov_b64 exec, s[90:91]
	s_mov_b32 s67, 0x10000
	s_mov_b32 s68, 0x14000
	v_mov_b32_e32 v183, v239
	v_mov_b32_e32 v184, v240
	s_waitcnt vmcnt(0)
	s_barrier
	s_waitcnt vmcnt(0)
	s_barrier
	s_mov_b64 s[4:5], exec
	v_readlane_b32 s0, v252, 2
	v_readlane_b32 s30, v253, 24
	v_readlane_b32 s1, v252, 3
	v_readlane_b32 s31, v253, 25
	v_readlane_b32 s34, v253, 15
	v_readlane_b32 s36, v252, 27
	v_readlane_b32 s8, v253, 19
	v_readlane_b32 s10, v253, 21
	v_readlane_b32 s38, v252, 29
	v_readlane_b32 s60, v252, 31
	v_readlane_b32 s64, v252, 33
	v_readlane_b32 s70, v252, 35
	v_readlane_b32 s74, v252, 37
	s_and_b64 s[0:1], s[4:5], s[0:1]
	v_readlane_b32 s28, v253, 23
	v_readlane_b32 s35, v253, 16
	v_readlane_b32 s29, v252, 26
	v_readlane_b32 s31, v253, 18
	v_readlane_b32 s37, v252, 28
	v_readlane_b32 s9, v253, 20
	v_readlane_b32 s11, v253, 22
	v_readlane_b32 s39, v252, 30
	v_readlane_b32 s61, v252, 32
	v_readlane_b32 s65, v252, 34
	v_readlane_b32 s71, v252, 36
	v_readlane_b32 s75, v252, 38
	v_readlane_b32 s63, v253, 17
	s_mov_b64 exec, s[0:1]
	s_cbranch_execz .LBB0_916
	v_mov_b32_e32 v0, 0x20000
	ds_read_b64 v[0:1], v0
	s_getreg_b32 s44, hwreg(HW_REG_XCC_ID, 0, 4)
	s_lshl_b32 s44, s44, 7
	s_add_u32 s44, s44, 0xdc03600
	v_mov_b32_e32 v2, s44
	v_mov_b32_e32 v4, 1
	s_waitcnt vmcnt(0) lgkmcnt(0)
	global_atomic_add v5, v2, v4, s[42:43] sc0
	buffer_inv sc1
	s_add_u32 s100, s100, 1
	v_readfirstlane_b32 s46, v0
	v_readfirstlane_b32 s47, v1
	v_mov_b32_e32 v2, 0xdc03e00
	s_nop 3
	s_mul_i32 s48, s46, s100
	s_mul_i32 s49, s47, s100
	s_waitcnt vmcnt(1)
	v_readfirstlane_b32 s50, v5
	s_nop 3
	s_add_u32 s50, s50, 1
	s_cmp_lg_u32 s50, s48
	s_cbranch_scc1 .Lxb7_poll
	buffer_wbl2 sc1
	s_waitcnt vmcnt(0)
	global_atomic_add v2, v4, s[42:43]
